# GEMM K-loops: LDS-DMA addresses via saddr form (102 v_lshl_add_u64 removed), bit-identical
# baseline (speedup 1.0000x reference)
; #define PG8_STAGE(bufoff, gbase, voff) do { _Pragma("unroll") for (int _i = 0; _i < 2; ++_i) \
;         __builtin_amdgcn_global_load_lds((const unsigned*)((const char*)(gbase) + (voff)[_i]), (PG8_LAS unsigned*)(lds + (bufoff) + ldsw + _i * 8192), 16, 0, 0); } while (0)
; #define PG8_LDA(dst, b, h) do { _Pragma("unroll") for (int m = 0; m < 4; ++m) _Pragma("unroll") for (int k = 0; k < 2; ++k) dst[m][k] = *(const PG8_LAS bf16x8*)(lds + PG8_SA(b, h) + aoff + m * 2048 + k * 1024); } while (0)
; #define PG8_LDB(dst, b, h) do { _Pragma("unroll") for (int n = 0; n < 2; ++n) _Pragma("unroll") for (int k = 0; k < 2; ++k) dst[n][k] = *(const PG8_LAS bf16x8*)(lds + PG8_SB(b, h) + boff + n * 2048 + k * 1024); } while (0)
; #define PG8_MMA(ai, bj, At, Bt) do { __builtin_amdgcn_s_setprio(1); _Pragma("unroll") for (int m = 0; m < 4; ++m) _Pragma("unroll") for (int n = 0; n < 2; ++n) _Pragma("unroll") for (int k = 0; k < 2; ++k) \
;         acc[ai][bj][m][n] = __builtin_amdgcn_mfma_f32_16x16x32_bf16(Bt[n][k], At[m][k], acc[ai][bj][m][n], 0, 0, 0); __builtin_amdgcn_s_setprio(0); } while (0)
; #define PG8_WAIT_V(n) asm volatile("s_waitcnt vmcnt(" #n ")" ::: "memory")
; template <class Epi, class Sched, bool ALIGN_EPI = false, bool SP2 = false>
; __device__ __forceinline__ void gemm_phase(PG8_LAS unsigned char* lds, const Gemm g, const Sched& S, const Epi& E) {
;     ...
;         for (int t = 0; t < nt; t += 2) {
;             const bool last = (t == nt - 2);
;             const char* a1 = cA + (size_t)(t + 1) * kstep;
;             const char* a2 = last ? nA : cA + (size_t)(t + 2) * kstep; const char* b2 = last ? nB : cB + (size_t)(t + 2) * kstep;
;             const char* a3 = a2 + kstep; const char* b3 = b2 + kstep;
;             if (last && has_next) S.a_ready(nxt);
;             if (last) E.prefetch(lds + 139264, cur, wid, lane);
;             if constexpr (SP2) {
;             PG8_LDB(B0, 0, 0); PG8_LDB(B1, 0, 1); PG8_SCHED; PG8_LDA(At, 0, 0); PG8_STAGE(PG8_SA(1, 1), a1 + hstep, voffA);
;             PG8_WAIT_V(8); PG8_WAIT_L(0); PG8_BAR; PG8_MMA(0, 0, At, B0); PG8_MMA(0, 1, At, B1); PG8_BAR; PG8_SCHED;
;             PG8_LDA(At, 0, 1); PG8_STAGE(PG8_SB(0, 0), b2, voffB); PG8_STAGE(PG8_SB(0, 1), b2 + hstep, voffB); PG8_STAGE(PG8_SA(0, 0), a2, voffA);
;             PG8_WAIT_V(8); PG8_WAIT_L(0); PG8_BAR; PG8_MMA(1, 0, At, B0); PG8_MMA(1, 1, At, B1); PG8_BAR; PG8_SCHED;
.LBB0_510:
	ds_read_b128 v[128:131], v184
	ds_read_b128 v[148:151], v184 offset:1024
	ds_read_b128 v[152:155], v184 offset:2048
	ds_read_b128 v[158:161], v184 offset:3072
	ds_read_b128 v[190:193], v185
	ds_read_b128 v[194:197], v185 offset:1024
	ds_read_b128 v[198:201], v185 offset:2048
	ds_read_b128 v[202:205], v185 offset:3072
	s_add_u32 s34, s10, 0xfffc0080
	s_addc_u32 s35, s11, -1
	s_cmp_eq_u32 vcc_lo, 12
	s_cselect_b32 s69, s57, s35
	s_cselect_b32 s68, s63, s34
	s_cselect_b32 s67, s55, s97
	s_cselect_b32 s66, s95, s96
	s_add_i32 m0, s65, 0xc000
	ds_read_b128 v[206:209], v186
	ds_read_b128 v[210:213], v186 offset:1024
	ds_read_b128 v[214:217], v186 offset:2048
	ds_read_b128 v[218:221], v186 offset:3072
	ds_read_b128 v[222:225], v186 offset:4096
	ds_read_b128 v[226:229], v186 offset:5120
	ds_read_b128 v[230:233], v186 offset:6144
	ds_read_b128 v[234:237], v186 offset:7168
	global_load_lds_dwordx4 v142, s[10:11]
	s_add_i32 m0, s65, 0xe000
	s_nop 0
	global_load_lds_dwordx4 v140, s[10:11]
	s_waitcnt vmcnt(8)
	s_waitcnt lgkmcnt(0)
	s_barrier
	s_setprio 1
	s_waitcnt lgkmcnt(0)
	v_mfma_f32_16x16x32_bf16 v[124:127], v[128:131], v[206:209], v[124:127]
	v_mfma_f32_16x16x32_bf16 v[120:123], v[152:155], v[206:209], v[120:123]
	v_mfma_f32_16x16x32_bf16 v[108:111], v[128:131], v[214:217], v[108:111]
	v_mfma_f32_16x16x32_bf16 v[104:107], v[152:155], v[214:217], v[104:107]
	v_mfma_f32_16x16x32_bf16 v[92:95], v[128:131], v[222:225], v[92:95]
	v_mfma_f32_16x16x32_bf16 v[88:91], v[152:155], v[222:225], v[88:91]
	v_mfma_f32_16x16x32_bf16 v[76:79], v[128:131], v[230:233], v[76:79]
	v_mfma_f32_16x16x32_bf16 v[72:75], v[152:155], v[230:233], v[72:75]
	v_mfma_f32_16x16x32_bf16 v[124:127], v[148:151], v[210:213], v[124:127]
	v_mfma_f32_16x16x32_bf16 v[120:123], v[158:161], v[210:213], v[120:123]
	v_mfma_f32_16x16x32_bf16 v[108:111], v[148:151], v[218:221], v[108:111]
	v_mfma_f32_16x16x32_bf16 v[104:107], v[158:161], v[218:221], v[104:107]
	v_mfma_f32_16x16x32_bf16 v[92:95], v[148:151], v[226:229], v[92:95]
	v_mfma_f32_16x16x32_bf16 v[88:91], v[158:161], v[226:229], v[88:91]
	v_mfma_f32_16x16x32_bf16 v[76:79], v[148:151], v[234:237], v[76:79]
	v_mfma_f32_16x16x32_bf16 v[72:75], v[158:161], v[234:237], v[72:75]
	s_setprio 0
	s_setprio 1
	v_mfma_f32_16x16x32_bf16 v[116:119], v[190:193], v[206:209], v[116:119]
	v_mfma_f32_16x16x32_bf16 v[112:115], v[198:201], v[206:209], v[112:115]
	v_mfma_f32_16x16x32_bf16 v[100:103], v[190:193], v[214:217], v[100:103]
	v_mfma_f32_16x16x32_bf16 v[96:99], v[198:201], v[214:217], v[96:99]
	v_mfma_f32_16x16x32_bf16 v[84:87], v[190:193], v[222:225], v[84:87]
	v_mfma_f32_16x16x32_bf16 v[80:83], v[198:201], v[222:225], v[80:83]
	v_mfma_f32_16x16x32_bf16 v[68:71], v[190:193], v[230:233], v[68:71]
	v_mfma_f32_16x16x32_bf16 v[64:67], v[198:201], v[230:233], v[64:67]
	v_mfma_f32_16x16x32_bf16 v[116:119], v[194:197], v[210:213], v[116:119]
	v_mfma_f32_16x16x32_bf16 v[112:115], v[202:205], v[210:213], v[112:115]
	v_mfma_f32_16x16x32_bf16 v[100:103], v[194:197], v[218:221], v[100:103]
	v_mfma_f32_16x16x32_bf16 v[96:99], v[202:205], v[218:221], v[96:99]
	v_mfma_f32_16x16x32_bf16 v[84:87], v[194:197], v[226:229], v[84:87]
	v_mfma_f32_16x16x32_bf16 v[80:83], v[202:205], v[226:229], v[80:83]
	v_mfma_f32_16x16x32_bf16 v[68:71], v[194:197], v[234:237], v[68:71]
	v_mfma_f32_16x16x32_bf16 v[64:67], v[202:205], v[234:237], v[64:67]
	s_setprio 0
	s_barrier
	s_add_i32 s34, s84, s71
	s_mov_b32 m0, s34
	ds_read_b128 v[206:209], v186 offset:16384
	ds_read_b128 v[210:213], v186 offset:17408
	ds_read_b128 v[214:217], v186 offset:18432
	ds_read_b128 v[218:221], v186 offset:19456
	ds_read_b128 v[222:225], v186 offset:20480
	ds_read_b128 v[226:229], v186 offset:21504
	ds_read_b128 v[230:233], v186 offset:22528
	ds_read_b128 v[234:237], v186 offset:23552
	global_load_lds_dwordx4 v134, s[66:67]
	s_add_i32 m0, s34, 0x2000
	s_add_u32 s34, s66, 0x40000
	s_addc_u32 s35, s67, 0
	s_add_i32 vcc_hi, s85, s71
	global_load_lds_dwordx4 v138, s[66:67]
	s_mov_b32 m0, vcc_hi
	s_nop 0
	global_load_lds_dwordx4 v134, s[34:35]
	s_add_i32 m0, vcc_hi, 0x2000
	s_nop 0
	global_load_lds_dwordx4 v138, s[34:35]
	s_mov_b32 m0, s65
	s_nop 0
	global_load_lds_dwordx4 v132, s[68:69]
	s_mov_b32 m0, s73
	s_nop 0
	global_load_lds_dwordx4 v136, s[68:69]
	s_waitcnt vmcnt(8)
	s_waitcnt lgkmcnt(0)
	s_barrier
	s_setprio 1
	s_waitcnt lgkmcnt(0)
	v_mfma_f32_16x16x32_bf16 v[60:63], v[128:131], v[206:209], v[60:63]
	v_mfma_f32_16x16x32_bf16 v[56:59], v[152:155], v[206:209], v[56:59]
	v_mfma_f32_16x16x32_bf16 v[44:47], v[128:131], v[214:217], v[44:47]
	v_mfma_f32_16x16x32_bf16 v[40:43], v[152:155], v[214:217], v[40:43]
	v_mfma_f32_16x16x32_bf16 v[28:31], v[128:131], v[222:225], v[28:31]
	v_mfma_f32_16x16x32_bf16 v[24:27], v[152:155], v[222:225], v[24:27]
	v_mfma_f32_16x16x32_bf16 v[12:15], v[128:131], v[230:233], v[12:15]
	v_mfma_f32_16x16x32_bf16 v[8:11], v[152:155], v[230:233], v[8:11]
	v_mfma_f32_16x16x32_bf16 v[60:63], v[148:151], v[210:213], v[60:63]
	v_mfma_f32_16x16x32_bf16 v[56:59], v[158:161], v[210:213], v[56:59]
	v_mfma_f32_16x16x32_bf16 v[44:47], v[148:151], v[218:221], v[44:47]
	v_mfma_f32_16x16x32_bf16 v[40:43], v[158:161], v[218:221], v[40:43]
	v_mfma_f32_16x16x32_bf16 v[28:31], v[148:151], v[226:229], v[28:31]
	v_mfma_f32_16x16x32_bf16 v[24:27], v[158:161], v[226:229], v[24:27]
	v_mfma_f32_16x16x32_bf16 v[12:15], v[148:151], v[234:237], v[12:15]
	v_mfma_f32_16x16x32_bf16 v[8:11], v[158:161], v[234:237], v[8:11]
	s_setprio 0
	s_setprio 1
	v_mfma_f32_16x16x32_bf16 v[52:55], v[190:193], v[206:209], v[52:55]
	v_mfma_f32_16x16x32_bf16 v[48:51], v[198:201], v[206:209], v[48:51]
	v_mfma_f32_16x16x32_bf16 v[36:39], v[190:193], v[214:217], v[36:39]
	v_mfma_f32_16x16x32_bf16 v[32:35], v[198:201], v[214:217], v[32:35]
	v_mfma_f32_16x16x32_bf16 v[20:23], v[190:193], v[222:225], v[20:23]
	v_mfma_f32_16x16x32_bf16 v[16:19], v[198:201], v[222:225], v[16:19]
	v_mfma_f32_16x16x32_bf16 v[4:7], v[190:193], v[230:233], v[4:7]
	v_mfma_f32_16x16x32_bf16 v[0:3], v[198:201], v[230:233], v[0:3]
	v_mfma_f32_16x16x32_bf16 v[52:55], v[194:197], v[210:213], v[52:55]
	v_mfma_f32_16x16x32_bf16 v[48:51], v[202:205], v[210:213], v[48:51]
	v_mfma_f32_16x16x32_bf16 v[36:39], v[194:197], v[218:221], v[36:39]
	v_mfma_f32_16x16x32_bf16 v[32:35], v[202:205], v[218:221], v[32:35]
	v_mfma_f32_16x16x32_bf16 v[20:23], v[194:197], v[226:229], v[20:23]
	v_mfma_f32_16x16x32_bf16 v[16:19], v[202:205], v[226:229], v[16:19]
	v_mfma_f32_16x16x32_bf16 v[4:7], v[194:197], v[234:237], v[4:7]
	v_mfma_f32_16x16x32_bf16 v[0:3], v[202:205], v[234:237], v[0:3]
	s_setprio 0
	s_barrier
; #define PG8_STAGE(bufoff, gbase, voff) do { _Pragma("unroll") for (int _i = 0; _i < 2; ++_i) \
;         __builtin_amdgcn_global_load_lds((const unsigned*)((const char*)(gbase) + (voff)[_i]), (PG8_LAS unsigned*)(lds + (bufoff) + ldsw + _i * 8192), 16, 0, 0); } while (0)
; #define PG8_LDA(dst, b, h) do { _Pragma("unroll") for (int m = 0; m < 4; ++m) _Pragma("unroll") for (int k = 0; k < 2; ++k) dst[m][k] = *(const PG8_LAS bf16x8*)(lds + PG8_SA(b, h) + aoff + m * 2048 + k * 1024); } while (0)
; #define PG8_LDB(dst, b, h) do { _Pragma("unroll") for (int n = 0; n < 2; ++n) _Pragma("unroll") for (int k = 0; k < 2; ++k) dst[n][k] = *(const PG8_LAS bf16x8*)(lds + PG8_SB(b, h) + boff + n * 2048 + k * 1024); } while (0)
; #define PG8_MMA(ai, bj, At, Bt) do { __builtin_amdgcn_s_setprio(1); _Pragma("unroll") for (int m = 0; m < 4; ++m) _Pragma("unroll") for (int n = 0; n < 2; ++n) _Pragma("unroll") for (int k = 0; k < 2; ++k) \
;         acc[ai][bj][m][n] = __builtin_amdgcn_mfma_f32_16x16x32_bf16(Bt[n][k], At[m][k], acc[ai][bj][m][n], 0, 0, 0); __builtin_amdgcn_s_setprio(0); } while (0)
; #define PG8_WAIT_V(n) asm volatile("s_waitcnt vmcnt(" #n ")" ::: "memory")
; #define PG8_WAIT_L(n) asm volatile("s_waitcnt lgkmcnt(" #n ")" ::: "memory")
; #define PG8_BAR __builtin_amdgcn_s_barrier()
; #define PG8_SCHED __builtin_amdgcn_sched_barrier(0)
; template <class Epi, class Sched, bool ALIGN_EPI = false, bool SP2 = false>
; __device__ __forceinline__ void gemm_phase(PG8_LAS unsigned char* lds, const Gemm g, const Sched& S, const Epi& E) {
;     ...
;         for (int t = 0; t < nt; t += 2) {
;     ...
;             PG8_LDB(B0, 1, 0); PG8_LDB(B1, 1, 1); PG8_SCHED; PG8_LDA(At, 1, 0); PG8_STAGE(PG8_SA(0, 1), a2 + hstep, voffA);
;             PG8_WAIT_V(8); PG8_WAIT_L(0); PG8_BAR; PG8_MMA(0, 0, At, B0); PG8_MMA(0, 1, At, B1); PG8_BAR; PG8_SCHED;
;             PG8_LDA(At, 1, 1); PG8_STAGE(PG8_SB(1, 0), b3, voffB); PG8_STAGE(PG8_SB(1, 1), b3 + hstep, voffB); PG8_STAGE(PG8_SA(1, 0), a3, voffA);
;             PG8_WAIT_V(8); PG8_WAIT_L(0); PG8_BAR; PG8_MMA(1, 0, At, B0); PG8_MMA(1, 1, At, B1); PG8_BAR; PG8_SCHED;
	s_add_i32 vcc_hi, 0, 0x18000
	s_add_i32 s14, 0, 0x1c000
	v_add_u32_e32 v158, vcc_hi, v163
	v_add_u32_e32 v202, s14, v163
	ds_read_b128 v[128:131], v158
	ds_read_b128 v[148:151], v158 offset:1024
	ds_read_b128 v[152:155], v158 offset:2048
	ds_read_b128 v[158:161], v158 offset:3072
	ds_read_b128 v[190:193], v202
	ds_read_b128 v[194:197], v202 offset:1024
	ds_read_b128 v[198:201], v202 offset:2048
	ds_read_b128 v[202:205], v202 offset:3072
	s_add_u32 s34, s68, 0x40000
	s_addc_u32 s35, s69, 0
	s_mov_b32 m0, s74
	ds_read_b128 v[206:209], v186 offset:32768
	ds_read_b128 v[210:213], v186 offset:33792
	ds_read_b128 v[214:217], v186 offset:34816
	ds_read_b128 v[218:221], v186 offset:35840
	ds_read_b128 v[222:225], v186 offset:36864
	ds_read_b128 v[226:229], v186 offset:37888
	ds_read_b128 v[230:233], v186 offset:38912
	ds_read_b128 v[234:237], v186 offset:39936
	global_load_lds_dwordx4 v132, s[34:35]
	s_mov_b32 m0, s75
	s_nop 0
	global_load_lds_dwordx4 v136, s[34:35]
	s_waitcnt vmcnt(8)
	s_waitcnt lgkmcnt(0)
	s_barrier
	s_setprio 1
	s_waitcnt lgkmcnt(0)
	v_mfma_f32_16x16x32_bf16 v[124:127], v[128:131], v[206:209], v[124:127]
	v_mfma_f32_16x16x32_bf16 v[120:123], v[152:155], v[206:209], v[120:123]
	v_mfma_f32_16x16x32_bf16 v[108:111], v[128:131], v[214:217], v[108:111]
	v_mfma_f32_16x16x32_bf16 v[104:107], v[152:155], v[214:217], v[104:107]
	v_mfma_f32_16x16x32_bf16 v[92:95], v[128:131], v[222:225], v[92:95]
	v_mfma_f32_16x16x32_bf16 v[88:91], v[152:155], v[222:225], v[88:91]
	v_mfma_f32_16x16x32_bf16 v[76:79], v[128:131], v[230:233], v[76:79]
	v_mfma_f32_16x16x32_bf16 v[72:75], v[152:155], v[230:233], v[72:75]
	v_mfma_f32_16x16x32_bf16 v[124:127], v[148:151], v[210:213], v[124:127]
	v_mfma_f32_16x16x32_bf16 v[120:123], v[158:161], v[210:213], v[120:123]
	v_mfma_f32_16x16x32_bf16 v[108:111], v[148:151], v[218:221], v[108:111]
	v_mfma_f32_16x16x32_bf16 v[104:107], v[158:161], v[218:221], v[104:107]
	v_mfma_f32_16x16x32_bf16 v[92:95], v[148:151], v[226:229], v[92:95]
	v_mfma_f32_16x16x32_bf16 v[88:91], v[158:161], v[226:229], v[88:91]
	v_mfma_f32_16x16x32_bf16 v[76:79], v[148:151], v[234:237], v[76:79]
	v_mfma_f32_16x16x32_bf16 v[72:75], v[158:161], v[234:237], v[72:75]
	s_setprio 0
	s_setprio 1
	v_mfma_f32_16x16x32_bf16 v[116:119], v[190:193], v[206:209], v[116:119]
	v_mfma_f32_16x16x32_bf16 v[112:115], v[198:201], v[206:209], v[112:115]
	v_mfma_f32_16x16x32_bf16 v[100:103], v[190:193], v[214:217], v[100:103]
	v_mfma_f32_16x16x32_bf16 v[96:99], v[198:201], v[214:217], v[96:99]
	v_mfma_f32_16x16x32_bf16 v[84:87], v[190:193], v[222:225], v[84:87]
	v_mfma_f32_16x16x32_bf16 v[80:83], v[198:201], v[222:225], v[80:83]
	v_mfma_f32_16x16x32_bf16 v[68:71], v[190:193], v[230:233], v[68:71]
	v_mfma_f32_16x16x32_bf16 v[64:67], v[198:201], v[230:233], v[64:67]
	v_mfma_f32_16x16x32_bf16 v[116:119], v[194:197], v[210:213], v[116:119]
	v_mfma_f32_16x16x32_bf16 v[112:115], v[202:205], v[210:213], v[112:115]
	v_mfma_f32_16x16x32_bf16 v[100:103], v[194:197], v[218:221], v[100:103]
	v_mfma_f32_16x16x32_bf16 v[96:99], v[202:205], v[218:221], v[96:99]
	v_mfma_f32_16x16x32_bf16 v[84:87], v[194:197], v[226:229], v[84:87]
	v_mfma_f32_16x16x32_bf16 v[80:83], v[202:205], v[226:229], v[80:83]
	v_mfma_f32_16x16x32_bf16 v[68:71], v[194:197], v[234:237], v[68:71]
	v_mfma_f32_16x16x32_bf16 v[64:67], v[202:205], v[234:237], v[64:67]
	s_setprio 0
	s_barrier
	s_add_i32 s15, vcc_hi, s71
	s_add_u32 s98, s66, s42
	s_addc_u32 s99, s67, s43
	s_add_u32 s100, s68, s42
	s_addc_u32 s101, s69, s43
	s_mov_b32 m0, s15
	ds_read_b128 v[206:209], v186 offset:49152
	ds_read_b128 v[210:213], v186 offset:50176
	ds_read_b128 v[214:217], v186 offset:51200
	ds_read_b128 v[218:221], v186 offset:52224
	ds_read_b128 v[222:225], v186 offset:53248
	ds_read_b128 v[226:229], v186 offset:54272
	ds_read_b128 v[230:233], v186 offset:55296
	ds_read_b128 v[234:237], v186 offset:56320
	global_load_lds_dwordx4 v134, s[98:99]
	s_add_i32 m0, s15, 0x2000
	s_add_u32 s34, s66, 0x40080
	s_addc_u32 s35, s67, 0
	s_add_i32 s14, s14, s71
	global_load_lds_dwordx4 v138, s[98:99]
	s_mov_b32 m0, s14
	s_nop 0
	global_load_lds_dwordx4 v134, s[34:35]
	s_add_i32 m0, s14, 0x2000
	s_nop 0
	global_load_lds_dwordx4 v138, s[34:35]
	s_mov_b32 m0, s78
	s_nop 0
	global_load_lds_dwordx4 v132, s[100:101]
	s_mov_b32 m0, s79
	s_nop 0
	global_load_lds_dwordx4 v136, s[100:101]
	s_waitcnt vmcnt(8)
	s_waitcnt lgkmcnt(0)
	s_barrier
	s_setprio 1
	s_waitcnt lgkmcnt(0)
	v_mfma_f32_16x16x32_bf16 v[60:63], v[128:131], v[206:209], v[60:63]
	v_mfma_f32_16x16x32_bf16 v[56:59], v[152:155], v[206:209], v[56:59]
	v_mfma_f32_16x16x32_bf16 v[44:47], v[128:131], v[214:217], v[44:47]
	v_mfma_f32_16x16x32_bf16 v[40:43], v[152:155], v[214:217], v[40:43]
	v_mfma_f32_16x16x32_bf16 v[28:31], v[128:131], v[222:225], v[28:31]
	v_mfma_f32_16x16x32_bf16 v[24:27], v[152:155], v[222:225], v[24:27]
	v_mfma_f32_16x16x32_bf16 v[12:15], v[128:131], v[230:233], v[12:15]
	v_mfma_f32_16x16x32_bf16 v[8:11], v[152:155], v[230:233], v[8:11]
	v_mfma_f32_16x16x32_bf16 v[60:63], v[148:151], v[210:213], v[60:63]
	v_mfma_f32_16x16x32_bf16 v[56:59], v[158:161], v[210:213], v[56:59]
	v_mfma_f32_16x16x32_bf16 v[44:47], v[148:151], v[218:221], v[44:47]
	v_mfma_f32_16x16x32_bf16 v[40:43], v[158:161], v[218:221], v[40:43]
	v_mfma_f32_16x16x32_bf16 v[28:31], v[148:151], v[226:229], v[28:31]
	v_mfma_f32_16x16x32_bf16 v[24:27], v[158:161], v[226:229], v[24:27]
	v_mfma_f32_16x16x32_bf16 v[12:15], v[148:151], v[234:237], v[12:15]
	v_mfma_f32_16x16x32_bf16 v[8:11], v[158:161], v[234:237], v[8:11]
	s_setprio 0
	s_setprio 1
	v_mfma_f32_16x16x32_bf16 v[52:55], v[190:193], v[206:209], v[52:55]
	v_mfma_f32_16x16x32_bf16 v[48:51], v[198:201], v[206:209], v[48:51]
	v_mfma_f32_16x16x32_bf16 v[36:39], v[190:193], v[214:217], v[36:39]
	v_mfma_f32_16x16x32_bf16 v[32:35], v[198:201], v[214:217], v[32:35]
	v_mfma_f32_16x16x32_bf16 v[20:23], v[190:193], v[222:225], v[20:23]
	v_mfma_f32_16x16x32_bf16 v[16:19], v[198:201], v[222:225], v[16:19]
	v_mfma_f32_16x16x32_bf16 v[4:7], v[190:193], v[230:233], v[4:7]
	v_mfma_f32_16x16x32_bf16 v[0:3], v[198:201], v[230:233], v[0:3]
	v_mfma_f32_16x16x32_bf16 v[52:55], v[194:197], v[210:213], v[52:55]
	v_mfma_f32_16x16x32_bf16 v[48:51], v[202:205], v[210:213], v[48:51]
	v_mfma_f32_16x16x32_bf16 v[36:39], v[194:197], v[218:221], v[36:39]
	v_mfma_f32_16x16x32_bf16 v[32:35], v[202:205], v[218:221], v[32:35]
	v_mfma_f32_16x16x32_bf16 v[20:23], v[194:197], v[226:229], v[20:23]
	v_mfma_f32_16x16x32_bf16 v[16:19], v[202:205], v[226:229], v[16:19]
	v_mfma_f32_16x16x32_bf16 v[4:7], v[194:197], v[234:237], v[4:7]
	v_mfma_f32_16x16x32_bf16 v[0:3], v[202:205], v[234:237], v[0:3]
	s_setprio 0
	s_barrier
	s_add_i32 vcc_lo, vcc_lo, 2
	s_add_u32 s96, s96, 0x100
	s_addc_u32 s97, s97, 0
	s_add_u32 s10, s10, 0x100
	s_addc_u32 s11, s11, 0
	s_cmp_gt_u32 vcc_lo, 13
	s_cbranch_scc0 .LBB0_510
	s_and_b64 vcc, exec, s[44:45]
	s_cbranch_vccz .LBB0_513
	s_barrier

; #define PG8_STAGE(bufoff, gbase, voff) do { _Pragma("unroll") for (int _i = 0; _i < 2; ++_i) \
;         __builtin_amdgcn_global_load_lds((const unsigned*)((const char*)(gbase) + (voff)[_i]), (PG8_LAS unsigned*)(lds + (bufoff) + ldsw + _i * 8192), 16, 0, 0); } while (0)
; #define PG8_LDA(dst, b, h) do { _Pragma("unroll") for (int m = 0; m < 4; ++m) _Pragma("unroll") for (int k = 0; k < 2; ++k) dst[m][k] = *(const PG8_LAS bf16x8*)(lds + PG8_SA(b, h) + aoff + m * 2048 + k * 1024); } while (0)
; #define PG8_LDB(dst, b, h) do { _Pragma("unroll") for (int n = 0; n < 2; ++n) _Pragma("unroll") for (int k = 0; k < 2; ++k) dst[n][k] = *(const PG8_LAS bf16x8*)(lds + PG8_SB(b, h) + boff + n * 2048 + k * 1024); } while (0)
; #define PG8_MMA(ai, bj, At, Bt) do { __builtin_amdgcn_s_setprio(1); _Pragma("unroll") for (int m = 0; m < 4; ++m) _Pragma("unroll") for (int n = 0; n < 2; ++n) _Pragma("unroll") for (int k = 0; k < 2; ++k) \
;         acc[ai][bj][m][n] = __builtin_amdgcn_mfma_f32_16x16x32_bf16(Bt[n][k], At[m][k], acc[ai][bj][m][n], 0, 0, 0); __builtin_amdgcn_s_setprio(0); } while (0)
; #define PG8_WAIT_V(n) asm volatile("s_waitcnt vmcnt(" #n ")" ::: "memory")
; template <class Epi, class Sched, bool ALIGN_EPI = false, bool SP2 = false>
; __device__ __forceinline__ void gemm_phase(PG8_LAS unsigned char* lds, const Gemm g, const Sched& S, const Epi& E) {
;     ...
;         for (int t = 0; t < nt; t += 2) {
;             const bool last = (t == nt - 2);
;             const char* a1 = cA + (size_t)(t + 1) * kstep;
;             const char* a2 = last ? nA : cA + (size_t)(t + 2) * kstep; const char* b2 = last ? nB : cB + (size_t)(t + 2) * kstep;
;             const char* a3 = a2 + kstep; const char* b3 = b2 + kstep;
;             if (last && has_next) S.a_ready(nxt);
;             if (last) E.prefetch(lds + 139264, cur, wid, lane);
;             if constexpr (SP2) {
;             PG8_LDB(B0, 0, 0); PG8_LDB(B1, 0, 1); PG8_SCHED; PG8_LDA(At, 0, 0); PG8_STAGE(PG8_SA(1, 1), a1 + hstep, voffA);
;             PG8_WAIT_V(8); PG8_WAIT_L(0); PG8_BAR; PG8_MMA(0, 0, At, B0); PG8_MMA(0, 1, At, B1); PG8_BAR; PG8_SCHED;
;             PG8_LDA(At, 0, 1); PG8_STAGE(PG8_SB(0, 0), b2, voffB); PG8_STAGE(PG8_SB(0, 1), b2 + hstep, voffB); PG8_STAGE(PG8_SA(0, 0), a2, voffA);
;             PG8_WAIT_V(8); PG8_WAIT_L(0); PG8_BAR; PG8_MMA(1, 0, At, B0); PG8_MMA(1, 1, At, B1); PG8_BAR; PG8_SCHED;
.LBB0_710:
	ds_read_b128 v[128:131], v169
	ds_read_b128 v[132:135], v169 offset:1024
	ds_read_b128 v[136:139], v169 offset:2048
	ds_read_b128 v[140:143], v169 offset:3072
	ds_read_b128 v[162:165], v170
	ds_read_b128 v[172:175], v170 offset:1024
	ds_read_b128 v[176:179], v170 offset:2048
	ds_read_b128 v[184:187], v170 offset:3072
	s_add_u32 s14, s54, 0xfffc0080
	s_addc_u32 s15, s55, -1
	s_cmp_eq_u32 s84, 12
	s_cselect_b32 s59, s45, s15
	s_cselect_b32 s58, s51, s14
	s_cselect_b32 s57, s43, s83
	s_cselect_b32 s56, s53, s82
	s_add_i32 m0, s64, 0xc000
	ds_read_b128 v[188:191], v171
	ds_read_b128 v[192:195], v171 offset:1024
	ds_read_b128 v[196:199], v171 offset:2048
	ds_read_b128 v[200:203], v171 offset:3072
	ds_read_b128 v[204:207], v171 offset:4096
	ds_read_b128 v[208:211], v171 offset:5120
	ds_read_b128 v[212:215], v171 offset:6144
	ds_read_b128 v[216:219], v171 offset:7168
	global_load_lds_dwordx4 v154, s[54:55]
	s_add_i32 m0, s64, 0xe000
	s_nop 0
	global_load_lds_dwordx4 v152, s[54:55]
	s_waitcnt vmcnt(8)
	s_waitcnt lgkmcnt(0)
	s_barrier
	s_setprio 1
	s_waitcnt lgkmcnt(0)
	v_mfma_f32_16x16x32_bf16 v[124:127], v[128:131], v[188:191], v[124:127]
	v_mfma_f32_16x16x32_bf16 v[120:123], v[136:139], v[188:191], v[120:123]
	v_mfma_f32_16x16x32_bf16 v[116:119], v[128:131], v[196:199], v[116:119]
	v_mfma_f32_16x16x32_bf16 v[108:111], v[136:139], v[196:199], v[108:111]
	v_mfma_f32_16x16x32_bf16 v[100:103], v[128:131], v[204:207], v[100:103]
	v_mfma_f32_16x16x32_bf16 v[92:95], v[136:139], v[204:207], v[92:95]
	v_mfma_f32_16x16x32_bf16 v[84:87], v[128:131], v[212:215], v[84:87]
	v_mfma_f32_16x16x32_bf16 v[76:79], v[136:139], v[212:215], v[76:79]
	v_mfma_f32_16x16x32_bf16 v[124:127], v[132:135], v[192:195], v[124:127]
	v_mfma_f32_16x16x32_bf16 v[120:123], v[140:143], v[192:195], v[120:123]
	v_mfma_f32_16x16x32_bf16 v[116:119], v[132:135], v[200:203], v[116:119]
	v_mfma_f32_16x16x32_bf16 v[108:111], v[140:143], v[200:203], v[108:111]
	v_mfma_f32_16x16x32_bf16 v[100:103], v[132:135], v[208:211], v[100:103]
	v_mfma_f32_16x16x32_bf16 v[92:95], v[140:143], v[208:211], v[92:95]
	v_mfma_f32_16x16x32_bf16 v[84:87], v[132:135], v[216:219], v[84:87]
	v_mfma_f32_16x16x32_bf16 v[76:79], v[140:143], v[216:219], v[76:79]
	s_setprio 0
	s_setprio 1
	v_mfma_f32_16x16x32_bf16 v[112:115], v[162:165], v[188:191], v[112:115]
	v_mfma_f32_16x16x32_bf16 v[104:107], v[176:179], v[188:191], v[104:107]
	v_mfma_f32_16x16x32_bf16 v[96:99], v[162:165], v[196:199], v[96:99]
	v_mfma_f32_16x16x32_bf16 v[88:91], v[176:179], v[196:199], v[88:91]
	v_mfma_f32_16x16x32_bf16 v[80:83], v[162:165], v[204:207], v[80:83]
	v_mfma_f32_16x16x32_bf16 v[72:75], v[176:179], v[204:207], v[72:75]
	v_mfma_f32_16x16x32_bf16 v[68:71], v[162:165], v[212:215], v[68:71]
	v_mfma_f32_16x16x32_bf16 v[64:67], v[176:179], v[212:215], v[64:67]
	v_mfma_f32_16x16x32_bf16 v[112:115], v[172:175], v[192:195], v[112:115]
	v_mfma_f32_16x16x32_bf16 v[104:107], v[184:187], v[192:195], v[104:107]
	v_mfma_f32_16x16x32_bf16 v[96:99], v[172:175], v[200:203], v[96:99]
	v_mfma_f32_16x16x32_bf16 v[88:91], v[184:187], v[200:203], v[88:91]
	v_mfma_f32_16x16x32_bf16 v[80:83], v[172:175], v[208:211], v[80:83]
	v_mfma_f32_16x16x32_bf16 v[72:75], v[184:187], v[208:211], v[72:75]
	v_mfma_f32_16x16x32_bf16 v[68:71], v[172:175], v[216:219], v[68:71]
	v_mfma_f32_16x16x32_bf16 v[64:67], v[184:187], v[216:219], v[64:67]
	s_setprio 0
	s_barrier
	s_add_i32 s14, s80, s63
	s_mov_b32 m0, s14
	ds_read_b128 v[188:191], v171 offset:16384
	ds_read_b128 v[192:195], v171 offset:17408
	ds_read_b128 v[196:199], v171 offset:18432
	ds_read_b128 v[200:203], v171 offset:19456
	ds_read_b128 v[204:207], v171 offset:20480
	ds_read_b128 v[208:211], v171 offset:21504
	ds_read_b128 v[212:215], v171 offset:22528
	ds_read_b128 v[216:219], v171 offset:23552
	global_load_lds_dwordx4 v146, s[56:57]
	s_add_i32 m0, s14, 0x2000
	s_add_u32 s34, s56, 0x40000
	s_addc_u32 s35, s57, 0
	s_add_i32 s14, s81, s63
	global_load_lds_dwordx4 v150, s[56:57]
	s_mov_b32 m0, s14
	s_nop 0
	global_load_lds_dwordx4 v146, s[34:35]
	s_add_i32 m0, s14, 0x2000
	s_nop 0
	global_load_lds_dwordx4 v150, s[34:35]
	s_mov_b32 m0, s64
	s_nop 0
	global_load_lds_dwordx4 v144, s[58:59]
	s_mov_b32 m0, s65
	s_nop 0
	global_load_lds_dwordx4 v148, s[58:59]
	s_waitcnt vmcnt(8)
	s_waitcnt lgkmcnt(0)
	s_barrier
	s_setprio 1
	s_waitcnt lgkmcnt(0)
	v_mfma_f32_16x16x32_bf16 v[60:63], v[128:131], v[188:191], v[60:63]
	v_mfma_f32_16x16x32_bf16 v[56:59], v[136:139], v[188:191], v[56:59]
	v_mfma_f32_16x16x32_bf16 v[48:51], v[128:131], v[196:199], v[48:51]
	v_mfma_f32_16x16x32_bf16 v[44:47], v[136:139], v[196:199], v[44:47]
	v_mfma_f32_16x16x32_bf16 v[36:39], v[128:131], v[204:207], v[36:39]
	v_mfma_f32_16x16x32_bf16 v[28:31], v[136:139], v[204:207], v[28:31]
	v_mfma_f32_16x16x32_bf16 v[20:23], v[128:131], v[212:215], v[20:23]
	v_mfma_f32_16x16x32_bf16 v[12:15], v[136:139], v[212:215], v[12:15]
	v_mfma_f32_16x16x32_bf16 v[60:63], v[132:135], v[192:195], v[60:63]
	v_mfma_f32_16x16x32_bf16 v[56:59], v[140:143], v[192:195], v[56:59]
	v_mfma_f32_16x16x32_bf16 v[48:51], v[132:135], v[200:203], v[48:51]
	v_mfma_f32_16x16x32_bf16 v[44:47], v[140:143], v[200:203], v[44:47]
	v_mfma_f32_16x16x32_bf16 v[36:39], v[132:135], v[208:211], v[36:39]
	v_mfma_f32_16x16x32_bf16 v[28:31], v[140:143], v[208:211], v[28:31]
	v_mfma_f32_16x16x32_bf16 v[20:23], v[132:135], v[216:219], v[20:23]
	v_mfma_f32_16x16x32_bf16 v[12:15], v[140:143], v[216:219], v[12:15]
	s_setprio 0
	s_setprio 1
	v_mfma_f32_16x16x32_bf16 v[52:55], v[162:165], v[188:191], v[52:55]
	v_mfma_f32_16x16x32_bf16 v[40:43], v[176:179], v[188:191], v[40:43]
	v_mfma_f32_16x16x32_bf16 v[32:35], v[162:165], v[196:199], v[32:35]
	v_mfma_f32_16x16x32_bf16 v[24:27], v[176:179], v[196:199], v[24:27]
	v_mfma_f32_16x16x32_bf16 v[16:19], v[162:165], v[204:207], v[16:19]
	v_mfma_f32_16x16x32_bf16 v[8:11], v[176:179], v[204:207], v[8:11]
	v_mfma_f32_16x16x32_bf16 v[4:7], v[162:165], v[212:215], v[4:7]
	v_mfma_f32_16x16x32_bf16 v[0:3], v[176:179], v[212:215], v[0:3]
	v_mfma_f32_16x16x32_bf16 v[52:55], v[172:175], v[192:195], v[52:55]
	v_mfma_f32_16x16x32_bf16 v[40:43], v[184:187], v[192:195], v[40:43]
	v_mfma_f32_16x16x32_bf16 v[32:35], v[172:175], v[200:203], v[32:35]
	v_mfma_f32_16x16x32_bf16 v[24:27], v[184:187], v[200:203], v[24:27]
	v_mfma_f32_16x16x32_bf16 v[16:19], v[172:175], v[208:211], v[16:19]
	v_mfma_f32_16x16x32_bf16 v[8:11], v[184:187], v[208:211], v[8:11]
	v_mfma_f32_16x16x32_bf16 v[4:7], v[172:175], v[216:219], v[4:7]
	v_mfma_f32_16x16x32_bf16 v[0:3], v[184:187], v[216:219], v[0:3]
	s_setprio 0
	s_barrier
; #define PG8_STAGE(bufoff, gbase, voff) do { _Pragma("unroll") for (int _i = 0; _i < 2; ++_i) \
;         __builtin_amdgcn_global_load_lds((const unsigned*)((const char*)(gbase) + (voff)[_i]), (PG8_LAS unsigned*)(lds + (bufoff) + ldsw + _i * 8192), 16, 0, 0); } while (0)
; #define PG8_LDA(dst, b, h) do { _Pragma("unroll") for (int m = 0; m < 4; ++m) _Pragma("unroll") for (int k = 0; k < 2; ++k) dst[m][k] = *(const PG8_LAS bf16x8*)(lds + PG8_SA(b, h) + aoff + m * 2048 + k * 1024); } while (0)
; #define PG8_LDB(dst, b, h) do { _Pragma("unroll") for (int n = 0; n < 2; ++n) _Pragma("unroll") for (int k = 0; k < 2; ++k) dst[n][k] = *(const PG8_LAS bf16x8*)(lds + PG8_SB(b, h) + boff + n * 2048 + k * 1024); } while (0)
; #define PG8_MMA(ai, bj, At, Bt) do { __builtin_amdgcn_s_setprio(1); _Pragma("unroll") for (int m = 0; m < 4; ++m) _Pragma("unroll") for (int n = 0; n < 2; ++n) _Pragma("unroll") for (int k = 0; k < 2; ++k) \
;         acc[ai][bj][m][n] = __builtin_amdgcn_mfma_f32_16x16x32_bf16(Bt[n][k], At[m][k], acc[ai][bj][m][n], 0, 0, 0); __builtin_amdgcn_s_setprio(0); } while (0)
; #define PG8_WAIT_V(n) asm volatile("s_waitcnt vmcnt(" #n ")" ::: "memory")
; #define PG8_WAIT_L(n) asm volatile("s_waitcnt lgkmcnt(" #n ")" ::: "memory")
; #define PG8_BAR __builtin_amdgcn_s_barrier()
; #define PG8_SCHED __builtin_amdgcn_sched_barrier(0)
; template <class Epi, class Sched, bool ALIGN_EPI = false, bool SP2 = false>
; __device__ __forceinline__ void gemm_phase(PG8_LAS unsigned char* lds, const Gemm g, const Sched& S, const Epi& E) {
;     ...
;         for (int t = 0; t < nt; t += 2) {
;     ...
;             PG8_LDB(B0, 1, 0); PG8_LDB(B1, 1, 1); PG8_SCHED; PG8_LDA(At, 1, 0); PG8_STAGE(PG8_SA(0, 1), a2 + hstep, voffA);
;             PG8_WAIT_V(8); PG8_WAIT_L(0); PG8_BAR; PG8_MMA(0, 0, At, B0); PG8_MMA(0, 1, At, B1); PG8_BAR; PG8_SCHED;
;             PG8_LDA(At, 1, 1); PG8_STAGE(PG8_SB(1, 0), b3, voffB); PG8_STAGE(PG8_SB(1, 1), b3 + hstep, voffB); PG8_STAGE(PG8_SA(1, 0), a3, voffA);
;             PG8_WAIT_V(8); PG8_WAIT_L(0); PG8_BAR; PG8_MMA(1, 0, At, B0); PG8_MMA(1, 1, At, B1); PG8_BAR; PG8_SCHED;
	s_add_i32 s14, 0, 0x18000
	s_add_i32 s15, 0, 0x1c000
	v_add_u32_e32 v140, s14, v167
	v_add_u32_e32 v183, s15, v167
	ds_read_b128 v[128:131], v140
	ds_read_b128 v[132:135], v140 offset:1024
	ds_read_b128 v[136:139], v140 offset:2048
	ds_read_b128 v[140:143], v140 offset:3072
	ds_read_b128 v[162:165], v183
	ds_read_b128 v[172:175], v183 offset:1024
	ds_read_b128 v[176:179], v183 offset:2048
	ds_read_b128 v[184:187], v183 offset:3072
	s_add_u32 s34, s58, 0x40000
	s_addc_u32 s35, s59, 0
	s_mov_b32 m0, s66
	ds_read_b128 v[188:191], v171 offset:32768
	ds_read_b128 v[192:195], v171 offset:33792
	ds_read_b128 v[196:199], v171 offset:34816
	ds_read_b128 v[200:203], v171 offset:35840
	ds_read_b128 v[204:207], v171 offset:36864
	ds_read_b128 v[208:211], v171 offset:37888
	ds_read_b128 v[212:215], v171 offset:38912
	ds_read_b128 v[216:219], v171 offset:39936
	global_load_lds_dwordx4 v144, s[34:35]
	s_mov_b32 m0, s67
	s_nop 0
	global_load_lds_dwordx4 v148, s[34:35]
	s_waitcnt vmcnt(8)
	s_waitcnt lgkmcnt(0)
	s_barrier
	s_setprio 1
	s_waitcnt lgkmcnt(0)
	v_mfma_f32_16x16x32_bf16 v[124:127], v[128:131], v[188:191], v[124:127]
	v_mfma_f32_16x16x32_bf16 v[120:123], v[136:139], v[188:191], v[120:123]
	v_mfma_f32_16x16x32_bf16 v[116:119], v[128:131], v[196:199], v[116:119]
	v_mfma_f32_16x16x32_bf16 v[108:111], v[136:139], v[196:199], v[108:111]
	v_mfma_f32_16x16x32_bf16 v[100:103], v[128:131], v[204:207], v[100:103]
	v_mfma_f32_16x16x32_bf16 v[92:95], v[136:139], v[204:207], v[92:95]
	v_mfma_f32_16x16x32_bf16 v[84:87], v[128:131], v[212:215], v[84:87]
	v_mfma_f32_16x16x32_bf16 v[76:79], v[136:139], v[212:215], v[76:79]
	v_mfma_f32_16x16x32_bf16 v[124:127], v[132:135], v[192:195], v[124:127]
	v_mfma_f32_16x16x32_bf16 v[120:123], v[140:143], v[192:195], v[120:123]
	v_mfma_f32_16x16x32_bf16 v[116:119], v[132:135], v[200:203], v[116:119]
	v_mfma_f32_16x16x32_bf16 v[108:111], v[140:143], v[200:203], v[108:111]
	v_mfma_f32_16x16x32_bf16 v[100:103], v[132:135], v[208:211], v[100:103]
	v_mfma_f32_16x16x32_bf16 v[92:95], v[140:143], v[208:211], v[92:95]
	v_mfma_f32_16x16x32_bf16 v[84:87], v[132:135], v[216:219], v[84:87]
	v_mfma_f32_16x16x32_bf16 v[76:79], v[140:143], v[216:219], v[76:79]
	s_setprio 0
	s_setprio 1
	v_mfma_f32_16x16x32_bf16 v[112:115], v[162:165], v[188:191], v[112:115]
	v_mfma_f32_16x16x32_bf16 v[104:107], v[176:179], v[188:191], v[104:107]
	v_mfma_f32_16x16x32_bf16 v[96:99], v[162:165], v[196:199], v[96:99]
	v_mfma_f32_16x16x32_bf16 v[88:91], v[176:179], v[196:199], v[88:91]
	v_mfma_f32_16x16x32_bf16 v[80:83], v[162:165], v[204:207], v[80:83]
	v_mfma_f32_16x16x32_bf16 v[72:75], v[176:179], v[204:207], v[72:75]
	v_mfma_f32_16x16x32_bf16 v[68:71], v[162:165], v[212:215], v[68:71]
	v_mfma_f32_16x16x32_bf16 v[64:67], v[176:179], v[212:215], v[64:67]
	v_mfma_f32_16x16x32_bf16 v[112:115], v[172:175], v[192:195], v[112:115]
	v_mfma_f32_16x16x32_bf16 v[104:107], v[184:187], v[192:195], v[104:107]
	v_mfma_f32_16x16x32_bf16 v[96:99], v[172:175], v[200:203], v[96:99]
	v_mfma_f32_16x16x32_bf16 v[88:91], v[184:187], v[200:203], v[88:91]
	v_mfma_f32_16x16x32_bf16 v[80:83], v[172:175], v[208:211], v[80:83]
	v_mfma_f32_16x16x32_bf16 v[72:75], v[184:187], v[208:211], v[72:75]
	v_mfma_f32_16x16x32_bf16 v[68:71], v[172:175], v[216:219], v[68:71]
	v_mfma_f32_16x16x32_bf16 v[64:67], v[184:187], v[216:219], v[64:67]
	s_setprio 0
	s_barrier
	s_add_i32 s14, s14, s63
	s_add_u32 s98, s56, s36
	s_addc_u32 s99, s57, s37
	s_add_u32 s100, s58, s36
	s_addc_u32 s101, s59, s37
	s_mov_b32 m0, s14
	ds_read_b128 v[188:191], v171 offset:49152
	ds_read_b128 v[192:195], v171 offset:50176
	ds_read_b128 v[196:199], v171 offset:51200
	ds_read_b128 v[200:203], v171 offset:52224
	ds_read_b128 v[204:207], v171 offset:53248
	ds_read_b128 v[208:211], v171 offset:54272
	ds_read_b128 v[212:215], v171 offset:55296
	ds_read_b128 v[216:219], v171 offset:56320
	global_load_lds_dwordx4 v146, s[98:99]
	s_add_i32 m0, s14, 0x2000
	s_add_u32 s34, s56, 0x40080
	s_addc_u32 s35, s57, 0
	s_add_i32 s14, s15, s63
	global_load_lds_dwordx4 v150, s[98:99]
	s_mov_b32 m0, s14
	s_nop 0
	global_load_lds_dwordx4 v146, s[34:35]
	s_add_i32 m0, s14, 0x2000
	s_nop 0
	global_load_lds_dwordx4 v150, s[34:35]
	s_mov_b32 m0, s74
	s_nop 0
	global_load_lds_dwordx4 v144, s[100:101]
	s_mov_b32 m0, s75
	s_nop 0
	global_load_lds_dwordx4 v148, s[100:101]
	s_waitcnt vmcnt(8)
	s_waitcnt lgkmcnt(0)
	s_barrier
	s_setprio 1
	s_waitcnt lgkmcnt(0)
	v_mfma_f32_16x16x32_bf16 v[60:63], v[128:131], v[188:191], v[60:63]
	v_mfma_f32_16x16x32_bf16 v[56:59], v[136:139], v[188:191], v[56:59]
	v_mfma_f32_16x16x32_bf16 v[48:51], v[128:131], v[196:199], v[48:51]
	v_mfma_f32_16x16x32_bf16 v[44:47], v[136:139], v[196:199], v[44:47]
	v_mfma_f32_16x16x32_bf16 v[36:39], v[128:131], v[204:207], v[36:39]
	v_mfma_f32_16x16x32_bf16 v[28:31], v[136:139], v[204:207], v[28:31]
	v_mfma_f32_16x16x32_bf16 v[20:23], v[128:131], v[212:215], v[20:23]
	v_mfma_f32_16x16x32_bf16 v[12:15], v[136:139], v[212:215], v[12:15]
	v_mfma_f32_16x16x32_bf16 v[60:63], v[132:135], v[192:195], v[60:63]
	v_mfma_f32_16x16x32_bf16 v[56:59], v[140:143], v[192:195], v[56:59]
	v_mfma_f32_16x16x32_bf16 v[48:51], v[132:135], v[200:203], v[48:51]
	v_mfma_f32_16x16x32_bf16 v[44:47], v[140:143], v[200:203], v[44:47]
	v_mfma_f32_16x16x32_bf16 v[36:39], v[132:135], v[208:211], v[36:39]
	v_mfma_f32_16x16x32_bf16 v[28:31], v[140:143], v[208:211], v[28:31]
	v_mfma_f32_16x16x32_bf16 v[20:23], v[132:135], v[216:219], v[20:23]
	v_mfma_f32_16x16x32_bf16 v[12:15], v[140:143], v[216:219], v[12:15]
	s_setprio 0
	s_setprio 1
	v_mfma_f32_16x16x32_bf16 v[52:55], v[162:165], v[188:191], v[52:55]
	v_mfma_f32_16x16x32_bf16 v[40:43], v[176:179], v[188:191], v[40:43]
	v_mfma_f32_16x16x32_bf16 v[32:35], v[162:165], v[196:199], v[32:35]
	v_mfma_f32_16x16x32_bf16 v[24:27], v[176:179], v[196:199], v[24:27]
	v_mfma_f32_16x16x32_bf16 v[16:19], v[162:165], v[204:207], v[16:19]
	v_mfma_f32_16x16x32_bf16 v[8:11], v[176:179], v[204:207], v[8:11]
	v_mfma_f32_16x16x32_bf16 v[4:7], v[162:165], v[212:215], v[4:7]
	v_mfma_f32_16x16x32_bf16 v[0:3], v[176:179], v[212:215], v[0:3]
	v_mfma_f32_16x16x32_bf16 v[52:55], v[172:175], v[192:195], v[52:55]
	v_mfma_f32_16x16x32_bf16 v[40:43], v[184:187], v[192:195], v[40:43]
	v_mfma_f32_16x16x32_bf16 v[32:35], v[172:175], v[200:203], v[32:35]
	v_mfma_f32_16x16x32_bf16 v[24:27], v[184:187], v[200:203], v[24:27]
	v_mfma_f32_16x16x32_bf16 v[16:19], v[172:175], v[208:211], v[16:19]
	v_mfma_f32_16x16x32_bf16 v[8:11], v[184:187], v[208:211], v[8:11]
	v_mfma_f32_16x16x32_bf16 v[4:7], v[172:175], v[216:219], v[4:7]
	v_mfma_f32_16x16x32_bf16 v[0:3], v[184:187], v[216:219], v[0:3]
	s_setprio 0
	s_barrier
	s_add_i32 s84, s84, 2
	s_add_u32 s82, s82, 0x100
	s_addc_u32 s83, s83, 0
	s_add_u32 s54, s54, 0x100
	s_addc_u32 s55, s55, 0
	s_cmp_gt_u32 s84, 13
	s_cbranch_scc0 .LBB0_710
	s_and_b64 vcc, exec, s[40:41]
	s_cbranch_vccz .LBB0_713
	s_barrier

; #define PG8_STAGE(bufoff, gbase, voff) do { _Pragma("unroll") for (int _i = 0; _i < 2; ++_i) \
;         __builtin_amdgcn_global_load_lds((const unsigned*)((const char*)(gbase) + (voff)[_i]), (PG8_LAS unsigned*)(lds + (bufoff) + ldsw + _i * 8192), 16, 0, 0); } while (0)
; #define PG8_LDA(dst, b, h) do { _Pragma("unroll") for (int m = 0; m < 4; ++m) _Pragma("unroll") for (int k = 0; k < 2; ++k) dst[m][k] = *(const PG8_LAS bf16x8*)(lds + PG8_SA(b, h) + aoff + m * 2048 + k * 1024); } while (0)
; #define PG8_LDB(dst, b, h) do { _Pragma("unroll") for (int n = 0; n < 2; ++n) _Pragma("unroll") for (int k = 0; k < 2; ++k) dst[n][k] = *(const PG8_LAS bf16x8*)(lds + PG8_SB(b, h) + boff + n * 2048 + k * 1024); } while (0)
; #define PG8_MMA(ai, bj, At, Bt) do { __builtin_amdgcn_s_setprio(1); _Pragma("unroll") for (int m = 0; m < 4; ++m) _Pragma("unroll") for (int n = 0; n < 2; ++n) _Pragma("unroll") for (int k = 0; k < 2; ++k) \
;         acc[ai][bj][m][n] = __builtin_amdgcn_mfma_f32_16x16x32_bf16(Bt[n][k], At[m][k], acc[ai][bj][m][n], 0, 0, 0); __builtin_amdgcn_s_setprio(0); } while (0)
; #define PG8_WAIT_V(n) asm volatile("s_waitcnt vmcnt(" #n ")" ::: "memory")
; template <class Epi, class Sched, bool ALIGN_EPI = false, bool SP2 = false>
; __device__ __forceinline__ void gemm_phase(PG8_LAS unsigned char* lds, const Gemm g, const Sched& S, const Epi& E) {
;     ...
;         for (int t = 0; t < nt; t += 2) {
;             const bool last = (t == nt - 2);
;             const char* a1 = cA + (size_t)(t + 1) * kstep;
;             const char* a2 = last ? nA : cA + (size_t)(t + 2) * kstep; const char* b2 = last ? nB : cB + (size_t)(t + 2) * kstep;
;             const char* a3 = a2 + kstep; const char* b3 = b2 + kstep;
;             if (last && has_next) S.a_ready(nxt);
;             if (last) E.prefetch(lds + 139264, cur, wid, lane);
;             if constexpr (SP2) {
;             PG8_LDB(B0, 0, 0); PG8_LDB(B1, 0, 1); PG8_SCHED; PG8_LDA(At, 0, 0); PG8_STAGE(PG8_SA(1, 1), a1 + hstep, voffA);
;             PG8_WAIT_V(8); PG8_WAIT_L(0); PG8_BAR; PG8_MMA(0, 0, At, B0); PG8_MMA(0, 1, At, B1); PG8_BAR; PG8_SCHED;
;             PG8_LDA(At, 0, 1); PG8_STAGE(PG8_SB(0, 0), b2, voffB); PG8_STAGE(PG8_SB(0, 1), b2 + hstep, voffB); PG8_STAGE(PG8_SA(0, 0), a2, voffA);
;             PG8_WAIT_V(8); PG8_WAIT_L(0); PG8_BAR; PG8_MMA(1, 0, At, B0); PG8_MMA(1, 1, At, B1); PG8_BAR; PG8_SCHED;
.LBB0_796:
	v_add_u32_e32 v130, s76, v165
	ds_read_b128 v[118:121], v130
	ds_read_b128 v[122:125], v130 offset:1024
	ds_read_b128 v[126:129], v130 offset:2048
	ds_read_b128 v[172:175], v130 offset:3072
	v_add_u32_e32 v130, s77, v165
	ds_read_b128 v[176:179], v130
	ds_read_b128 v[184:187], v130 offset:1024
	ds_read_b128 v[188:191], v130 offset:2048
	ds_read_b128 v[192:195], v130 offset:3072
	s_add_u32 s12, s52, 0xfffc0080
	s_addc_u32 s13, s53, -1
	s_and_b64 s[34:35], s[54:55], exec
	s_cselect_b32 s57, s43, s13
	s_cselect_b32 s56, s78, s12
	s_cselect_b32 s55, s41, s51
	s_cselect_b32 s54, s79, s49
	s_add_i32 m0, s62, 0xc000
	ds_read_b128 v[196:199], v170
	ds_read_b128 v[200:203], v170 offset:1024
	ds_read_b128 v[204:207], v170 offset:2048
	ds_read_b128 v[208:211], v170 offset:3072
	ds_read_b128 v[212:215], v170 offset:4096
	ds_read_b128 v[216:219], v170 offset:5120
	ds_read_b128 v[220:223], v170 offset:6144
	ds_read_b128 v[224:227], v170 offset:7168
	global_load_lds_dwordx4 v154, s[52:53]
	s_add_i32 m0, s62, 0xe000
	s_nop 0
	global_load_lds_dwordx4 v152, s[52:53]
	s_waitcnt vmcnt(8)
	s_waitcnt lgkmcnt(0)
	s_barrier
	s_setprio 1
	s_waitcnt lgkmcnt(0)
	v_mfma_f32_16x16x32_bf16 v[140:143], v[118:121], v[196:199], v[140:143]
	v_mfma_f32_16x16x32_bf16 v[136:139], v[126:129], v[196:199], v[136:139]
	v_mfma_f32_16x16x32_bf16 v[108:111], v[118:121], v[204:207], v[108:111]
	v_mfma_f32_16x16x32_bf16 v[104:107], v[126:129], v[204:207], v[104:107]
	v_mfma_f32_16x16x32_bf16 v[92:95], v[118:121], v[212:215], v[92:95]
	v_mfma_f32_16x16x32_bf16 v[88:91], v[126:129], v[212:215], v[88:91]
	v_mfma_f32_16x16x32_bf16 v[76:79], v[118:121], v[220:223], v[76:79]
	v_mfma_f32_16x16x32_bf16 v[72:75], v[126:129], v[220:223], v[72:75]
	v_mfma_f32_16x16x32_bf16 v[140:143], v[122:125], v[200:203], v[140:143]
	v_mfma_f32_16x16x32_bf16 v[136:139], v[172:175], v[200:203], v[136:139]
	v_mfma_f32_16x16x32_bf16 v[108:111], v[122:125], v[208:211], v[108:111]
	v_mfma_f32_16x16x32_bf16 v[104:107], v[172:175], v[208:211], v[104:107]
	v_mfma_f32_16x16x32_bf16 v[92:95], v[122:125], v[216:219], v[92:95]
	v_mfma_f32_16x16x32_bf16 v[88:91], v[172:175], v[216:219], v[88:91]
	v_mfma_f32_16x16x32_bf16 v[76:79], v[122:125], v[224:227], v[76:79]
	v_mfma_f32_16x16x32_bf16 v[72:75], v[172:175], v[224:227], v[72:75]
	s_setprio 0
	s_setprio 1
	v_mfma_f32_16x16x32_bf16 v[130:133], v[176:179], v[196:199], v[132:135]
	v_mfma_f32_16x16x32_bf16 v[112:115], v[188:191], v[196:199], v[112:115]
	v_mfma_f32_16x16x32_bf16 v[100:103], v[176:179], v[204:207], v[100:103]
	v_mfma_f32_16x16x32_bf16 v[96:99], v[188:191], v[204:207], v[96:99]
	v_mfma_f32_16x16x32_bf16 v[84:87], v[176:179], v[212:215], v[84:87]
	v_mfma_f32_16x16x32_bf16 v[80:83], v[188:191], v[212:215], v[80:83]
	v_mfma_f32_16x16x32_bf16 v[68:71], v[176:179], v[220:223], v[68:71]
	v_mfma_f32_16x16x32_bf16 v[64:67], v[188:191], v[220:223], v[64:67]
	v_mfma_f32_16x16x32_bf16 v[130:133], v[184:187], v[200:203], v[130:133]
	v_mfma_f32_16x16x32_bf16 v[112:115], v[192:195], v[200:203], v[112:115]
	v_mfma_f32_16x16x32_bf16 v[100:103], v[184:187], v[208:211], v[100:103]
	v_mfma_f32_16x16x32_bf16 v[96:99], v[192:195], v[208:211], v[96:99]
	v_mfma_f32_16x16x32_bf16 v[84:87], v[184:187], v[216:219], v[84:87]
	v_mfma_f32_16x16x32_bf16 v[80:83], v[192:195], v[216:219], v[80:83]
	v_mfma_f32_16x16x32_bf16 v[68:71], v[184:187], v[224:227], v[68:71]
	v_mfma_f32_16x16x32_bf16 v[64:67], v[192:195], v[224:227], v[64:67]
	s_setprio 0
	s_barrier
	s_add_i32 s12, s76, s59
	s_mov_b32 m0, s12
	ds_read_b128 v[196:199], v170 offset:16384
	ds_read_b128 v[200:203], v170 offset:17408
	ds_read_b128 v[204:207], v170 offset:18432
	ds_read_b128 v[208:211], v170 offset:19456
	ds_read_b128 v[212:215], v170 offset:20480
	ds_read_b128 v[216:219], v170 offset:21504
	ds_read_b128 v[220:223], v170 offset:22528
	ds_read_b128 v[224:227], v170 offset:23552
	global_load_lds_dwordx4 v148, s[54:55]
	s_add_i32 m0, s12, 0x2000
	s_add_u32 s34, s54, 0x40000
	s_addc_u32 s35, s55, 0
	s_add_i32 s12, s77, s59
	global_load_lds_dwordx4 v144, s[54:55]
	s_mov_b32 m0, s12
	s_nop 0
	global_load_lds_dwordx4 v148, s[34:35]
	s_add_i32 m0, s12, 0x2000
	s_nop 0
	global_load_lds_dwordx4 v144, s[34:35]
	s_mov_b32 m0, s62
	s_nop 0
	global_load_lds_dwordx4 v150, s[56:57]
	s_mov_b32 m0, s63
	s_nop 0
	global_load_lds_dwordx4 v146, s[56:57]
	s_waitcnt vmcnt(8)
	s_waitcnt lgkmcnt(0)
	s_barrier
	s_setprio 1
	s_waitcnt lgkmcnt(0)
	v_mfma_f32_16x16x32_bf16 v[60:63], v[118:121], v[196:199], v[60:63]
	v_mfma_f32_16x16x32_bf16 v[56:59], v[126:129], v[196:199], v[56:59]
	v_mfma_f32_16x16x32_bf16 v[44:47], v[118:121], v[204:207], v[44:47]
	v_mfma_f32_16x16x32_bf16 v[40:43], v[126:129], v[204:207], v[40:43]
	v_mfma_f32_16x16x32_bf16 v[28:31], v[118:121], v[212:215], v[28:31]
	v_mfma_f32_16x16x32_bf16 v[24:27], v[126:129], v[212:215], v[24:27]
	v_mfma_f32_16x16x32_bf16 v[12:15], v[118:121], v[220:223], v[12:15]
	v_mfma_f32_16x16x32_bf16 v[8:11], v[126:129], v[220:223], v[8:11]
	v_mfma_f32_16x16x32_bf16 v[60:63], v[122:125], v[200:203], v[60:63]
	v_mfma_f32_16x16x32_bf16 v[56:59], v[172:175], v[200:203], v[56:59]
	v_mfma_f32_16x16x32_bf16 v[44:47], v[122:125], v[208:211], v[44:47]
	v_mfma_f32_16x16x32_bf16 v[40:43], v[172:175], v[208:211], v[40:43]
	v_mfma_f32_16x16x32_bf16 v[28:31], v[122:125], v[216:219], v[28:31]
	v_mfma_f32_16x16x32_bf16 v[24:27], v[172:175], v[216:219], v[24:27]
	v_mfma_f32_16x16x32_bf16 v[12:15], v[122:125], v[224:227], v[12:15]
	v_mfma_f32_16x16x32_bf16 v[8:11], v[172:175], v[224:227], v[8:11]
	s_setprio 0
	s_setprio 1
	v_mfma_f32_16x16x32_bf16 v[52:55], v[176:179], v[196:199], v[52:55]
	v_mfma_f32_16x16x32_bf16 v[48:51], v[188:191], v[196:199], v[48:51]
	v_mfma_f32_16x16x32_bf16 v[36:39], v[176:179], v[204:207], v[36:39]
	v_mfma_f32_16x16x32_bf16 v[32:35], v[188:191], v[204:207], v[32:35]
	v_mfma_f32_16x16x32_bf16 v[20:23], v[176:179], v[212:215], v[20:23]
	v_mfma_f32_16x16x32_bf16 v[16:19], v[188:191], v[212:215], v[16:19]
	v_mfma_f32_16x16x32_bf16 v[4:7], v[176:179], v[220:223], v[4:7]
	v_mfma_f32_16x16x32_bf16 v[0:3], v[188:191], v[220:223], v[0:3]
	v_mfma_f32_16x16x32_bf16 v[52:55], v[184:187], v[200:203], v[52:55]
	v_mfma_f32_16x16x32_bf16 v[48:51], v[192:195], v[200:203], v[48:51]
	v_mfma_f32_16x16x32_bf16 v[36:39], v[184:187], v[208:211], v[36:39]
	v_mfma_f32_16x16x32_bf16 v[32:35], v[192:195], v[208:211], v[32:35]
	v_mfma_f32_16x16x32_bf16 v[20:23], v[184:187], v[216:219], v[20:23]
	v_mfma_f32_16x16x32_bf16 v[16:19], v[192:195], v[216:219], v[16:19]
	v_mfma_f32_16x16x32_bf16 v[4:7], v[184:187], v[224:227], v[4:7]
	v_mfma_f32_16x16x32_bf16 v[0:3], v[192:195], v[224:227], v[0:3]
	s_setprio 0
	s_barrier
; #define PG8_STAGE(bufoff, gbase, voff) do { _Pragma("unroll") for (int _i = 0; _i < 2; ++_i) \
;         __builtin_amdgcn_global_load_lds((const unsigned*)((const char*)(gbase) + (voff)[_i]), (PG8_LAS unsigned*)(lds + (bufoff) + ldsw + _i * 8192), 16, 0, 0); } while (0)
; #define PG8_LDA(dst, b, h) do { _Pragma("unroll") for (int m = 0; m < 4; ++m) _Pragma("unroll") for (int k = 0; k < 2; ++k) dst[m][k] = *(const PG8_LAS bf16x8*)(lds + PG8_SA(b, h) + aoff + m * 2048 + k * 1024); } while (0)
; #define PG8_LDB(dst, b, h) do { _Pragma("unroll") for (int n = 0; n < 2; ++n) _Pragma("unroll") for (int k = 0; k < 2; ++k) dst[n][k] = *(const PG8_LAS bf16x8*)(lds + PG8_SB(b, h) + boff + n * 2048 + k * 1024); } while (0)
; #define PG8_MMA(ai, bj, At, Bt) do { __builtin_amdgcn_s_setprio(1); _Pragma("unroll") for (int m = 0; m < 4; ++m) _Pragma("unroll") for (int n = 0; n < 2; ++n) _Pragma("unroll") for (int k = 0; k < 2; ++k) \
;         acc[ai][bj][m][n] = __builtin_amdgcn_mfma_f32_16x16x32_bf16(Bt[n][k], At[m][k], acc[ai][bj][m][n], 0, 0, 0); __builtin_amdgcn_s_setprio(0); } while (0)
; #define PG8_WAIT_V(n) asm volatile("s_waitcnt vmcnt(" #n ")" ::: "memory")
; #define PG8_WAIT_L(n) asm volatile("s_waitcnt lgkmcnt(" #n ")" ::: "memory")
; #define PG8_BAR __builtin_amdgcn_s_barrier()
; #define PG8_SCHED __builtin_amdgcn_sched_barrier(0)
; template <class Epi, class Sched, bool ALIGN_EPI = false, bool SP2 = false>
; __device__ __forceinline__ void gemm_phase(PG8_LAS unsigned char* lds, const Gemm g, const Sched& S, const Epi& E) {
;     ...
;         for (int t = 0; t < nt; t += 2) {
;     ...
;             PG8_LDB(B0, 1, 0); PG8_LDB(B1, 1, 1); PG8_SCHED; PG8_LDA(At, 1, 0); PG8_STAGE(PG8_SA(0, 1), a2 + hstep, voffA);
;             PG8_WAIT_V(8); PG8_WAIT_L(0); PG8_BAR; PG8_MMA(0, 0, At, B0); PG8_MMA(0, 1, At, B1); PG8_BAR; PG8_SCHED;
;             PG8_LDA(At, 1, 1); PG8_STAGE(PG8_SB(1, 0), b3, voffB); PG8_STAGE(PG8_SB(1, 1), b3 + hstep, voffB); PG8_STAGE(PG8_SA(1, 0), a3, voffA);
;             PG8_WAIT_V(8); PG8_WAIT_L(0); PG8_BAR; PG8_MMA(1, 0, At, B0); PG8_MMA(1, 1, At, B1); PG8_BAR; PG8_SCHED;
	s_add_i32 s12, 0, 0x18000
	v_add_u32_e32 v134, s12, v165
	s_add_i32 s13, 0, 0x1c000
	ds_read_b128 v[118:121], v134
	ds_read_b128 v[122:125], v134 offset:1024
	ds_read_b128 v[126:129], v134 offset:2048
	ds_read_b128 v[172:175], v134 offset:3072
	v_add_u32_e32 v134, s13, v165
	ds_read_b128 v[176:179], v134
	ds_read_b128 v[184:187], v134 offset:1024
	ds_read_b128 v[188:191], v134 offset:2048
	ds_read_b128 v[192:195], v134 offset:3072
	s_add_u32 s34, s56, 0x40000
	s_addc_u32 s35, s57, 0
	s_mov_b32 m0, s64
	ds_read_b128 v[196:199], v170 offset:32768
	ds_read_b128 v[200:203], v170 offset:33792
	ds_read_b128 v[204:207], v170 offset:34816
	ds_read_b128 v[208:211], v170 offset:35840
	ds_read_b128 v[212:215], v170 offset:36864
	ds_read_b128 v[216:219], v170 offset:37888
	ds_read_b128 v[220:223], v170 offset:38912
	ds_read_b128 v[224:227], v170 offset:39936
	global_load_lds_dwordx4 v150, s[34:35]
	s_mov_b32 m0, s65
	s_nop 0
	global_load_lds_dwordx4 v146, s[34:35]
	s_waitcnt vmcnt(8)
	s_waitcnt lgkmcnt(0)
	s_barrier
	s_setprio 1
	s_waitcnt lgkmcnt(0)
	v_mfma_f32_16x16x32_bf16 v[140:143], v[118:121], v[196:199], v[140:143]
	v_mfma_f32_16x16x32_bf16 v[134:137], v[126:129], v[196:199], v[136:139]
	v_mfma_f32_16x16x32_bf16 v[108:111], v[118:121], v[204:207], v[108:111]
	v_mfma_f32_16x16x32_bf16 v[104:107], v[126:129], v[204:207], v[104:107]
	v_mfma_f32_16x16x32_bf16 v[92:95], v[118:121], v[212:215], v[92:95]
	v_mfma_f32_16x16x32_bf16 v[88:91], v[126:129], v[212:215], v[88:91]
	v_mfma_f32_16x16x32_bf16 v[76:79], v[118:121], v[220:223], v[76:79]
	v_mfma_f32_16x16x32_bf16 v[72:75], v[126:129], v[220:223], v[72:75]
	v_mfma_f32_16x16x32_bf16 v[140:143], v[122:125], v[200:203], v[140:143]
	v_mfma_f32_16x16x32_bf16 v[136:139], v[172:175], v[200:203], v[134:137]
	v_mfma_f32_16x16x32_bf16 v[108:111], v[122:125], v[208:211], v[108:111]
	v_mfma_f32_16x16x32_bf16 v[104:107], v[172:175], v[208:211], v[104:107]
	v_mfma_f32_16x16x32_bf16 v[92:95], v[122:125], v[216:219], v[92:95]
	v_mfma_f32_16x16x32_bf16 v[88:91], v[172:175], v[216:219], v[88:91]
	v_mfma_f32_16x16x32_bf16 v[76:79], v[122:125], v[224:227], v[76:79]
	v_mfma_f32_16x16x32_bf16 v[72:75], v[172:175], v[224:227], v[72:75]
	s_setprio 0
	s_setprio 1
	v_mfma_f32_16x16x32_bf16 v[130:133], v[176:179], v[196:199], v[130:133]
	v_mfma_f32_16x16x32_bf16 v[112:115], v[188:191], v[196:199], v[112:115]
	v_mfma_f32_16x16x32_bf16 v[100:103], v[176:179], v[204:207], v[100:103]
	v_mfma_f32_16x16x32_bf16 v[96:99], v[188:191], v[204:207], v[96:99]
	v_mfma_f32_16x16x32_bf16 v[84:87], v[176:179], v[212:215], v[84:87]
	v_mfma_f32_16x16x32_bf16 v[80:83], v[188:191], v[212:215], v[80:83]
	v_mfma_f32_16x16x32_bf16 v[68:71], v[176:179], v[220:223], v[68:71]
	v_mfma_f32_16x16x32_bf16 v[64:67], v[188:191], v[220:223], v[64:67]
	v_mfma_f32_16x16x32_bf16 v[132:135], v[184:187], v[200:203], v[130:133]
	v_mfma_f32_16x16x32_bf16 v[112:115], v[192:195], v[200:203], v[112:115]
	v_mfma_f32_16x16x32_bf16 v[100:103], v[184:187], v[208:211], v[100:103]
	v_mfma_f32_16x16x32_bf16 v[96:99], v[192:195], v[208:211], v[96:99]
	v_mfma_f32_16x16x32_bf16 v[84:87], v[184:187], v[216:219], v[84:87]
	v_mfma_f32_16x16x32_bf16 v[80:83], v[192:195], v[216:219], v[80:83]
	v_mfma_f32_16x16x32_bf16 v[68:71], v[184:187], v[224:227], v[68:71]
	v_mfma_f32_16x16x32_bf16 v[64:67], v[192:195], v[224:227], v[64:67]
	s_setprio 0
	s_barrier
	s_add_i32 s12, s12, s59
	s_add_u32 s98, s54, s18
	s_addc_u32 s99, s55, s19
	s_add_u32 s100, s56, s18
	s_addc_u32 s101, s57, s19
	s_mov_b32 m0, s12
	ds_read_b128 v[196:199], v170 offset:49152
	ds_read_b128 v[200:203], v170 offset:50176
	ds_read_b128 v[204:207], v170 offset:51200
	ds_read_b128 v[208:211], v170 offset:52224
	ds_read_b128 v[212:215], v170 offset:53248
	ds_read_b128 v[216:219], v170 offset:54272
	ds_read_b128 v[220:223], v170 offset:55296
	ds_read_b128 v[224:227], v170 offset:56320
	global_load_lds_dwordx4 v148, s[98:99]
	s_add_i32 m0, s12, 0x2000
	s_add_u32 s34, s54, 0x40080
	s_addc_u32 s35, s55, 0
	s_add_i32 s12, s13, s59
	global_load_lds_dwordx4 v144, s[98:99]
	s_mov_b32 m0, s12
	s_nop 0
	global_load_lds_dwordx4 v148, s[34:35]
	s_add_i32 m0, s12, 0x2000
	s_nop 0
	global_load_lds_dwordx4 v144, s[34:35]
	s_mov_b32 m0, s68
	s_nop 0
	global_load_lds_dwordx4 v150, s[100:101]
	s_mov_b32 m0, s69
	s_nop 0
	global_load_lds_dwordx4 v146, s[100:101]
	s_waitcnt vmcnt(8)
	s_waitcnt lgkmcnt(0)
	s_barrier
	s_setprio 1
	s_waitcnt lgkmcnt(0)
	v_mfma_f32_16x16x32_bf16 v[60:63], v[118:121], v[196:199], v[60:63]
	v_mfma_f32_16x16x32_bf16 v[56:59], v[126:129], v[196:199], v[56:59]
	v_mfma_f32_16x16x32_bf16 v[44:47], v[118:121], v[204:207], v[44:47]
	v_mfma_f32_16x16x32_bf16 v[40:43], v[126:129], v[204:207], v[40:43]
	v_mfma_f32_16x16x32_bf16 v[28:31], v[118:121], v[212:215], v[28:31]
	v_mfma_f32_16x16x32_bf16 v[24:27], v[126:129], v[212:215], v[24:27]
	v_mfma_f32_16x16x32_bf16 v[12:15], v[118:121], v[220:223], v[12:15]
	v_mfma_f32_16x16x32_bf16 v[8:11], v[126:129], v[220:223], v[8:11]
	v_mfma_f32_16x16x32_bf16 v[60:63], v[122:125], v[200:203], v[60:63]
	v_mfma_f32_16x16x32_bf16 v[56:59], v[172:175], v[200:203], v[56:59]
	v_mfma_f32_16x16x32_bf16 v[44:47], v[122:125], v[208:211], v[44:47]
	v_mfma_f32_16x16x32_bf16 v[40:43], v[172:175], v[208:211], v[40:43]
	v_mfma_f32_16x16x32_bf16 v[28:31], v[122:125], v[216:219], v[28:31]
	v_mfma_f32_16x16x32_bf16 v[24:27], v[172:175], v[216:219], v[24:27]
	v_mfma_f32_16x16x32_bf16 v[12:15], v[122:125], v[224:227], v[12:15]
	v_mfma_f32_16x16x32_bf16 v[8:11], v[172:175], v[224:227], v[8:11]
	s_setprio 0
	s_setprio 1
	v_mfma_f32_16x16x32_bf16 v[52:55], v[176:179], v[196:199], v[52:55]
	v_mfma_f32_16x16x32_bf16 v[48:51], v[188:191], v[196:199], v[48:51]
	v_mfma_f32_16x16x32_bf16 v[36:39], v[176:179], v[204:207], v[36:39]
	v_mfma_f32_16x16x32_bf16 v[32:35], v[188:191], v[204:207], v[32:35]
	v_mfma_f32_16x16x32_bf16 v[20:23], v[176:179], v[212:215], v[20:23]
	v_mfma_f32_16x16x32_bf16 v[16:19], v[188:191], v[212:215], v[16:19]
	v_mfma_f32_16x16x32_bf16 v[4:7], v[176:179], v[220:223], v[4:7]
	v_mfma_f32_16x16x32_bf16 v[0:3], v[188:191], v[220:223], v[0:3]
	v_mfma_f32_16x16x32_bf16 v[52:55], v[184:187], v[200:203], v[52:55]
	v_mfma_f32_16x16x32_bf16 v[48:51], v[192:195], v[200:203], v[48:51]
	v_mfma_f32_16x16x32_bf16 v[36:39], v[184:187], v[208:211], v[36:39]
	v_mfma_f32_16x16x32_bf16 v[32:35], v[192:195], v[208:211], v[32:35]
	v_mfma_f32_16x16x32_bf16 v[20:23], v[184:187], v[216:219], v[20:23]
	v_mfma_f32_16x16x32_bf16 v[16:19], v[192:195], v[216:219], v[16:19]
	v_mfma_f32_16x16x32_bf16 v[4:7], v[184:187], v[224:227], v[4:7]
	v_mfma_f32_16x16x32_bf16 v[0:3], v[192:195], v[224:227], v[0:3]
	s_setprio 0
	s_barrier
	s_add_i32 s80, s80, 2
	s_add_u32 s49, s49, 0x100
	s_addc_u32 s51, s51, 0
	s_add_u32 s52, s52, 0x100
	s_addc_u32 s53, s53, 0
	s_cmp_gt_u32 s80, 13
	s_cbranch_scc1 .LBB0_799

; #define PG8_STAGE(bufoff, gbase, voff) do { _Pragma("unroll") for (int _i = 0; _i < 2; ++_i) \
;         __builtin_amdgcn_global_load_lds((const unsigned*)((const char*)(gbase) + (voff)[_i]), (PG8_LAS unsigned*)(lds + (bufoff) + ldsw + _i * 8192), 16, 0, 0); } while (0)
; #define PG8_LDA(dst, b, h) do { _Pragma("unroll") for (int m = 0; m < 4; ++m) _Pragma("unroll") for (int k = 0; k < 2; ++k) dst[m][k] = *(const PG8_LAS bf16x8*)(lds + PG8_SA(b, h) + aoff + m * 2048 + k * 1024); } while (0)
; #define PG8_LDB(dst, b, h) do { _Pragma("unroll") for (int n = 0; n < 2; ++n) _Pragma("unroll") for (int k = 0; k < 2; ++k) dst[n][k] = *(const PG8_LAS bf16x8*)(lds + PG8_SB(b, h) + boff + n * 2048 + k * 1024); } while (0)
; #define PG8_MMA(ai, bj, At, Bt) do { __builtin_amdgcn_s_setprio(1); _Pragma("unroll") for (int m = 0; m < 4; ++m) _Pragma("unroll") for (int n = 0; n < 2; ++n) _Pragma("unroll") for (int k = 0; k < 2; ++k) \
;         acc[ai][bj][m][n] = __builtin_amdgcn_mfma_f32_16x16x32_bf16(Bt[n][k], At[m][k], acc[ai][bj][m][n], 0, 0, 0); __builtin_amdgcn_s_setprio(0); } while (0)
; #define PG8_WAIT_V(n) asm volatile("s_waitcnt vmcnt(" #n ")" ::: "memory")
; template <class Epi, class Sched, bool ALIGN_EPI = false, bool SP2 = false>
; __device__ __forceinline__ void gemm_phase(PG8_LAS unsigned char* lds, const Gemm g, const Sched& S, const Epi& E) {
;     ...
;         for (int t = 0; t < nt; t += 2) {
;             const bool last = (t == nt - 2);
;             const char* a1 = cA + (size_t)(t + 1) * kstep;
;             const char* a2 = last ? nA : cA + (size_t)(t + 2) * kstep; const char* b2 = last ? nB : cB + (size_t)(t + 2) * kstep;
;             const char* a3 = a2 + kstep; const char* b3 = b2 + kstep;
;             if (last && has_next) S.a_ready(nxt);
;             if (last) E.prefetch(lds + 139264, cur, wid, lane);
;             if constexpr (SP2) {
;             PG8_LDB(B0, 0, 0); PG8_LDB(B1, 0, 1); PG8_SCHED; PG8_LDA(At, 0, 0); PG8_STAGE(PG8_SA(1, 1), a1 + hstep, voffA);
;             PG8_WAIT_V(8); PG8_WAIT_L(0); PG8_BAR; PG8_MMA(0, 0, At, B0); PG8_MMA(0, 1, At, B1); PG8_BAR; PG8_SCHED;
;             PG8_LDA(At, 0, 1); PG8_STAGE(PG8_SB(0, 0), b2, voffB); PG8_STAGE(PG8_SB(0, 1), b2 + hstep, voffB); PG8_STAGE(PG8_SA(0, 0), a2, voffA);
;             PG8_WAIT_V(8); PG8_WAIT_L(0); PG8_BAR; PG8_MMA(1, 0, At, B0); PG8_MMA(1, 1, At, B1); PG8_BAR; PG8_SCHED;
.LBB0_872:
	ds_read_b128 v[128:131], v169
	ds_read_b128 v[132:135], v169 offset:1024
	ds_read_b128 v[136:139], v169 offset:2048
	ds_read_b128 v[140:143], v169 offset:3072
	ds_read_b128 v[162:165], v170
	ds_read_b128 v[172:175], v170 offset:1024
	ds_read_b128 v[176:179], v170 offset:2048
	ds_read_b128 v[184:187], v170 offset:3072
	s_add_u32 s42, s40, 0x100
	s_addc_u32 s43, s41, 0
	s_cmp_eq_u32 s74, 40
	s_cselect_b32 s47, s11, s43
	s_cselect_b32 s46, s10, s42
	s_cselect_b32 s45, s37, s73
	s_cselect_b32 s44, s36, s71
	v_lshl_add_u64 v[180:181], s[40:41], 0, v[154:155]
	s_add_i32 m0, s50, 0xc000
	ds_read_b128 v[188:191], v171
	ds_read_b128 v[192:195], v171 offset:1024
	ds_read_b128 v[196:199], v171 offset:2048
	ds_read_b128 v[200:203], v171 offset:3072
	ds_read_b128 v[204:207], v171 offset:4096
	ds_read_b128 v[208:211], v171 offset:5120
	ds_read_b128 v[212:215], v171 offset:6144
	ds_read_b128 v[216:219], v171 offset:7168
	global_load_lds_dwordx4 v[180:181], off
	v_lshl_add_u64 v[180:181], s[40:41], 0, v[152:153]
	s_add_i32 m0, s50, 0xe000
	s_nop 0
	global_load_lds_dwordx4 v[180:181], off
	s_waitcnt vmcnt(8)
	s_waitcnt lgkmcnt(0)
	s_barrier
	s_setprio 1
	s_waitcnt lgkmcnt(0)
	v_mfma_f32_16x16x32_bf16 v[124:127], v[128:131], v[188:191], v[124:127]
	v_mfma_f32_16x16x32_bf16 v[120:123], v[136:139], v[188:191], v[120:123]
	v_mfma_f32_16x16x32_bf16 v[116:119], v[128:131], v[196:199], v[116:119]
	v_mfma_f32_16x16x32_bf16 v[108:111], v[136:139], v[196:199], v[108:111]
	v_mfma_f32_16x16x32_bf16 v[100:103], v[128:131], v[204:207], v[100:103]
	v_mfma_f32_16x16x32_bf16 v[92:95], v[136:139], v[204:207], v[92:95]
	v_mfma_f32_16x16x32_bf16 v[84:87], v[128:131], v[212:215], v[84:87]
	v_mfma_f32_16x16x32_bf16 v[76:79], v[136:139], v[212:215], v[76:79]
	v_mfma_f32_16x16x32_bf16 v[124:127], v[132:135], v[192:195], v[124:127]
	v_mfma_f32_16x16x32_bf16 v[120:123], v[140:143], v[192:195], v[120:123]
	v_mfma_f32_16x16x32_bf16 v[116:119], v[132:135], v[200:203], v[116:119]
	v_mfma_f32_16x16x32_bf16 v[108:111], v[140:143], v[200:203], v[108:111]
	v_mfma_f32_16x16x32_bf16 v[100:103], v[132:135], v[208:211], v[100:103]
	v_mfma_f32_16x16x32_bf16 v[92:95], v[140:143], v[208:211], v[92:95]
	v_mfma_f32_16x16x32_bf16 v[84:87], v[132:135], v[216:219], v[84:87]
	v_mfma_f32_16x16x32_bf16 v[76:79], v[140:143], v[216:219], v[76:79]
	s_setprio 0
	s_setprio 1
	v_mfma_f32_16x16x32_bf16 v[112:115], v[162:165], v[188:191], v[112:115]
	v_mfma_f32_16x16x32_bf16 v[104:107], v[176:179], v[188:191], v[104:107]
	v_mfma_f32_16x16x32_bf16 v[96:99], v[162:165], v[196:199], v[96:99]
	v_mfma_f32_16x16x32_bf16 v[88:91], v[176:179], v[196:199], v[88:91]
	v_mfma_f32_16x16x32_bf16 v[80:83], v[162:165], v[204:207], v[80:83]
	v_mfma_f32_16x16x32_bf16 v[72:75], v[176:179], v[204:207], v[72:75]
	v_mfma_f32_16x16x32_bf16 v[68:71], v[162:165], v[212:215], v[68:71]
	v_mfma_f32_16x16x32_bf16 v[64:67], v[176:179], v[212:215], v[64:67]
	v_mfma_f32_16x16x32_bf16 v[112:115], v[172:175], v[192:195], v[112:115]
	v_mfma_f32_16x16x32_bf16 v[104:107], v[184:187], v[192:195], v[104:107]
	v_mfma_f32_16x16x32_bf16 v[96:99], v[172:175], v[200:203], v[96:99]
	v_mfma_f32_16x16x32_bf16 v[88:91], v[184:187], v[200:203], v[88:91]
	v_mfma_f32_16x16x32_bf16 v[80:83], v[172:175], v[208:211], v[80:83]
	v_mfma_f32_16x16x32_bf16 v[72:75], v[184:187], v[208:211], v[72:75]
	v_mfma_f32_16x16x32_bf16 v[68:71], v[172:175], v[216:219], v[68:71]
	v_mfma_f32_16x16x32_bf16 v[64:67], v[184:187], v[216:219], v[64:67]
	s_setprio 0
	s_barrier
	s_add_i32 s12, s65, s49
	s_mov_b32 m0, s12
	ds_read_b128 v[188:191], v171 offset:16384
	ds_read_b128 v[192:195], v171 offset:17408
	ds_read_b128 v[196:199], v171 offset:18432
	ds_read_b128 v[200:203], v171 offset:19456
	ds_read_b128 v[204:207], v171 offset:20480
	ds_read_b128 v[208:211], v171 offset:21504
	ds_read_b128 v[212:215], v171 offset:22528
	ds_read_b128 v[216:219], v171 offset:23552
	global_load_lds_dwordx4 v146, s[44:45]
	s_add_i32 m0, s12, 0x2000
	s_add_u32 s40, s44, 0xb0000
	s_addc_u32 s41, s45, 0
	s_add_i32 s12, s66, s49
	global_load_lds_dwordx4 v150, s[44:45]
	s_mov_b32 m0, s12
	s_nop 0
	global_load_lds_dwordx4 v146, s[40:41]
	s_add_i32 m0, s12, 0x2000
	s_nop 0
	global_load_lds_dwordx4 v150, s[40:41]
	s_mov_b32 m0, s50
	s_nop 0
	global_load_lds_dwordx4 v144, s[46:47]
	s_mov_b32 m0, s51
	s_nop 0
	global_load_lds_dwordx4 v148, s[46:47]
	s_waitcnt vmcnt(8)
	s_waitcnt lgkmcnt(0)
	s_barrier
	s_setprio 1
	s_waitcnt lgkmcnt(0)
	v_mfma_f32_16x16x32_bf16 v[60:63], v[128:131], v[188:191], v[60:63]
	v_mfma_f32_16x16x32_bf16 v[56:59], v[136:139], v[188:191], v[56:59]
	v_mfma_f32_16x16x32_bf16 v[48:51], v[128:131], v[196:199], v[48:51]
	v_mfma_f32_16x16x32_bf16 v[44:47], v[136:139], v[196:199], v[44:47]
	v_mfma_f32_16x16x32_bf16 v[36:39], v[128:131], v[204:207], v[36:39]
	v_mfma_f32_16x16x32_bf16 v[28:31], v[136:139], v[204:207], v[28:31]
	v_mfma_f32_16x16x32_bf16 v[20:23], v[128:131], v[212:215], v[20:23]
	v_mfma_f32_16x16x32_bf16 v[12:15], v[136:139], v[212:215], v[12:15]
	v_mfma_f32_16x16x32_bf16 v[60:63], v[132:135], v[192:195], v[60:63]
	v_mfma_f32_16x16x32_bf16 v[56:59], v[140:143], v[192:195], v[56:59]
	v_mfma_f32_16x16x32_bf16 v[48:51], v[132:135], v[200:203], v[48:51]
	v_mfma_f32_16x16x32_bf16 v[44:47], v[140:143], v[200:203], v[44:47]
	v_mfma_f32_16x16x32_bf16 v[36:39], v[132:135], v[208:211], v[36:39]
	v_mfma_f32_16x16x32_bf16 v[28:31], v[140:143], v[208:211], v[28:31]
	v_mfma_f32_16x16x32_bf16 v[20:23], v[132:135], v[216:219], v[20:23]
	v_mfma_f32_16x16x32_bf16 v[12:15], v[140:143], v[216:219], v[12:15]
	s_setprio 0
	s_setprio 1
	v_mfma_f32_16x16x32_bf16 v[52:55], v[162:165], v[188:191], v[52:55]
	v_mfma_f32_16x16x32_bf16 v[40:43], v[176:179], v[188:191], v[40:43]
	v_mfma_f32_16x16x32_bf16 v[32:35], v[162:165], v[196:199], v[32:35]
	v_mfma_f32_16x16x32_bf16 v[24:27], v[176:179], v[196:199], v[24:27]
	v_mfma_f32_16x16x32_bf16 v[16:19], v[162:165], v[204:207], v[16:19]
	v_mfma_f32_16x16x32_bf16 v[8:11], v[176:179], v[204:207], v[8:11]
	v_mfma_f32_16x16x32_bf16 v[4:7], v[162:165], v[212:215], v[4:7]
	v_mfma_f32_16x16x32_bf16 v[0:3], v[176:179], v[212:215], v[0:3]
	v_mfma_f32_16x16x32_bf16 v[52:55], v[172:175], v[192:195], v[52:55]
	v_mfma_f32_16x16x32_bf16 v[40:43], v[184:187], v[192:195], v[40:43]
	v_mfma_f32_16x16x32_bf16 v[32:35], v[172:175], v[200:203], v[32:35]
	v_mfma_f32_16x16x32_bf16 v[24:27], v[184:187], v[200:203], v[24:27]
	v_mfma_f32_16x16x32_bf16 v[16:19], v[172:175], v[208:211], v[16:19]
	v_mfma_f32_16x16x32_bf16 v[8:11], v[184:187], v[208:211], v[8:11]
	v_mfma_f32_16x16x32_bf16 v[4:7], v[172:175], v[216:219], v[4:7]
	v_mfma_f32_16x16x32_bf16 v[0:3], v[184:187], v[216:219], v[0:3]
	s_setprio 0
	s_barrier
; #define PG8_STAGE(bufoff, gbase, voff) do { _Pragma("unroll") for (int _i = 0; _i < 2; ++_i) \
;         __builtin_amdgcn_global_load_lds((const unsigned*)((const char*)(gbase) + (voff)[_i]), (PG8_LAS unsigned*)(lds + (bufoff) + ldsw + _i * 8192), 16, 0, 0); } while (0)
; #define PG8_LDA(dst, b, h) do { _Pragma("unroll") for (int m = 0; m < 4; ++m) _Pragma("unroll") for (int k = 0; k < 2; ++k) dst[m][k] = *(const PG8_LAS bf16x8*)(lds + PG8_SA(b, h) + aoff + m * 2048 + k * 1024); } while (0)
; #define PG8_LDB(dst, b, h) do { _Pragma("unroll") for (int n = 0; n < 2; ++n) _Pragma("unroll") for (int k = 0; k < 2; ++k) dst[n][k] = *(const PG8_LAS bf16x8*)(lds + PG8_SB(b, h) + boff + n * 2048 + k * 1024); } while (0)
; #define PG8_MMA(ai, bj, At, Bt) do { __builtin_amdgcn_s_setprio(1); _Pragma("unroll") for (int m = 0; m < 4; ++m) _Pragma("unroll") for (int n = 0; n < 2; ++n) _Pragma("unroll") for (int k = 0; k < 2; ++k) \
;         acc[ai][bj][m][n] = __builtin_amdgcn_mfma_f32_16x16x32_bf16(Bt[n][k], At[m][k], acc[ai][bj][m][n], 0, 0, 0); __builtin_amdgcn_s_setprio(0); } while (0)
; #define PG8_WAIT_V(n) asm volatile("s_waitcnt vmcnt(" #n ")" ::: "memory")
; #define PG8_WAIT_L(n) asm volatile("s_waitcnt lgkmcnt(" #n ")" ::: "memory")
; #define PG8_BAR __builtin_amdgcn_s_barrier()
; #define PG8_SCHED __builtin_amdgcn_sched_barrier(0)
; template <class Epi, class Sched, bool ALIGN_EPI = false, bool SP2 = false>
; __device__ __forceinline__ void gemm_phase(PG8_LAS unsigned char* lds, const Gemm g, const Sched& S, const Epi& E) {
;     ...
;         for (int t = 0; t < nt; t += 2) {
;     ...
;             PG8_LDB(B0, 1, 0); PG8_LDB(B1, 1, 1); PG8_SCHED; PG8_LDA(At, 1, 0); PG8_STAGE(PG8_SA(0, 1), a2 + hstep, voffA);
;             PG8_WAIT_V(8); PG8_WAIT_L(0); PG8_BAR; PG8_MMA(0, 0, At, B0); PG8_MMA(0, 1, At, B1); PG8_BAR; PG8_SCHED;
;             PG8_LDA(At, 1, 1); PG8_STAGE(PG8_SB(1, 0), b3, voffB); PG8_STAGE(PG8_SB(1, 1), b3 + hstep, voffB); PG8_STAGE(PG8_SA(1, 0), a3, voffA);
;             PG8_WAIT_V(8); PG8_WAIT_L(0); PG8_BAR; PG8_MMA(1, 0, At, B0); PG8_MMA(1, 1, At, B1); PG8_BAR; PG8_SCHED;
	s_add_i32 s12, 0, 0x18000
	s_add_i32 s13, 0, 0x1c000
	v_add_u32_e32 v140, s12, v167
	v_add_u32_e32 v183, s13, v167
	ds_read_b128 v[128:131], v140
	ds_read_b128 v[132:135], v140 offset:1024
	ds_read_b128 v[136:139], v140 offset:2048
	ds_read_b128 v[140:143], v140 offset:3072
	ds_read_b128 v[162:165], v183
	ds_read_b128 v[172:175], v183 offset:1024
	ds_read_b128 v[176:179], v183 offset:2048
	ds_read_b128 v[184:187], v183 offset:3072
	s_add_u32 s40, s46, 0xb0000
	s_addc_u32 s41, s47, 0
	s_mov_b32 m0, s52
	ds_read_b128 v[188:191], v171 offset:32768
	ds_read_b128 v[192:195], v171 offset:33792
	ds_read_b128 v[196:199], v171 offset:34816
	ds_read_b128 v[200:203], v171 offset:35840
	ds_read_b128 v[204:207], v171 offset:36864
	ds_read_b128 v[208:211], v171 offset:37888
	ds_read_b128 v[212:215], v171 offset:38912
	ds_read_b128 v[216:219], v171 offset:39936
	global_load_lds_dwordx4 v144, s[40:41]
	s_mov_b32 m0, s53
	s_nop 0
	global_load_lds_dwordx4 v148, s[40:41]
	s_waitcnt vmcnt(8)
	s_waitcnt lgkmcnt(0)
	s_barrier
	s_setprio 1
	s_waitcnt lgkmcnt(0)
	v_mfma_f32_16x16x32_bf16 v[124:127], v[128:131], v[188:191], v[124:127]
	v_mfma_f32_16x16x32_bf16 v[120:123], v[136:139], v[188:191], v[120:123]
	v_mfma_f32_16x16x32_bf16 v[116:119], v[128:131], v[196:199], v[116:119]
	v_mfma_f32_16x16x32_bf16 v[108:111], v[136:139], v[196:199], v[108:111]
	v_mfma_f32_16x16x32_bf16 v[100:103], v[128:131], v[204:207], v[100:103]
	v_mfma_f32_16x16x32_bf16 v[92:95], v[136:139], v[204:207], v[92:95]
	v_mfma_f32_16x16x32_bf16 v[84:87], v[128:131], v[212:215], v[84:87]
	v_mfma_f32_16x16x32_bf16 v[76:79], v[136:139], v[212:215], v[76:79]
	v_mfma_f32_16x16x32_bf16 v[124:127], v[132:135], v[192:195], v[124:127]
	v_mfma_f32_16x16x32_bf16 v[120:123], v[140:143], v[192:195], v[120:123]
	v_mfma_f32_16x16x32_bf16 v[116:119], v[132:135], v[200:203], v[116:119]
	v_mfma_f32_16x16x32_bf16 v[108:111], v[140:143], v[200:203], v[108:111]
	v_mfma_f32_16x16x32_bf16 v[100:103], v[132:135], v[208:211], v[100:103]
	v_mfma_f32_16x16x32_bf16 v[92:95], v[140:143], v[208:211], v[92:95]
	v_mfma_f32_16x16x32_bf16 v[84:87], v[132:135], v[216:219], v[84:87]
	v_mfma_f32_16x16x32_bf16 v[76:79], v[140:143], v[216:219], v[76:79]
	s_setprio 0
	s_setprio 1
	v_mfma_f32_16x16x32_bf16 v[112:115], v[162:165], v[188:191], v[112:115]
	v_mfma_f32_16x16x32_bf16 v[104:107], v[176:179], v[188:191], v[104:107]
	v_mfma_f32_16x16x32_bf16 v[96:99], v[162:165], v[196:199], v[96:99]
	v_mfma_f32_16x16x32_bf16 v[88:91], v[176:179], v[196:199], v[88:91]
	v_mfma_f32_16x16x32_bf16 v[80:83], v[162:165], v[204:207], v[80:83]
	v_mfma_f32_16x16x32_bf16 v[72:75], v[176:179], v[204:207], v[72:75]
	v_mfma_f32_16x16x32_bf16 v[68:71], v[162:165], v[212:215], v[68:71]
	v_mfma_f32_16x16x32_bf16 v[64:67], v[176:179], v[212:215], v[64:67]
	v_mfma_f32_16x16x32_bf16 v[112:115], v[172:175], v[192:195], v[112:115]
	v_mfma_f32_16x16x32_bf16 v[104:107], v[184:187], v[192:195], v[104:107]
	v_mfma_f32_16x16x32_bf16 v[96:99], v[172:175], v[200:203], v[96:99]
	v_mfma_f32_16x16x32_bf16 v[88:91], v[184:187], v[200:203], v[88:91]
	v_mfma_f32_16x16x32_bf16 v[80:83], v[172:175], v[208:211], v[80:83]
	v_mfma_f32_16x16x32_bf16 v[72:75], v[184:187], v[208:211], v[72:75]
	v_mfma_f32_16x16x32_bf16 v[68:71], v[172:175], v[216:219], v[68:71]
	v_mfma_f32_16x16x32_bf16 v[64:67], v[184:187], v[216:219], v[64:67]
	s_setprio 0
	s_barrier
	s_add_i32 s12, s12, s49
	s_add_u32 s98, s44, s30
	s_addc_u32 s99, s45, s31
	s_add_u32 s100, s46, s30
	s_addc_u32 s101, s47, s31
	s_mov_b32 m0, s12
	ds_read_b128 v[188:191], v171 offset:49152
	ds_read_b128 v[192:195], v171 offset:50176
	ds_read_b128 v[196:199], v171 offset:51200
	ds_read_b128 v[200:203], v171 offset:52224
	ds_read_b128 v[204:207], v171 offset:53248
	ds_read_b128 v[208:211], v171 offset:54272
	ds_read_b128 v[212:215], v171 offset:55296
	ds_read_b128 v[216:219], v171 offset:56320
	global_load_lds_dwordx4 v146, s[98:99]
	s_add_i32 m0, s12, 0x2000
	s_add_u32 s40, s44, 0xb0080
	s_addc_u32 s41, s45, 0
	s_add_i32 s12, s13, s49
	global_load_lds_dwordx4 v150, s[98:99]
	s_mov_b32 m0, s12
	s_nop 0
	global_load_lds_dwordx4 v146, s[40:41]
	s_add_i32 m0, s12, 0x2000
	s_nop 0
	global_load_lds_dwordx4 v150, s[40:41]
	s_mov_b32 m0, s59
	s_nop 0
	global_load_lds_dwordx4 v144, s[100:101]
	s_mov_b32 m0, s60
	s_nop 0
	global_load_lds_dwordx4 v148, s[100:101]
	s_waitcnt vmcnt(8)
	s_waitcnt lgkmcnt(0)
	s_barrier
	s_setprio 1
	s_waitcnt lgkmcnt(0)
	v_mfma_f32_16x16x32_bf16 v[60:63], v[128:131], v[188:191], v[60:63]
	v_mfma_f32_16x16x32_bf16 v[56:59], v[136:139], v[188:191], v[56:59]
	v_mfma_f32_16x16x32_bf16 v[48:51], v[128:131], v[196:199], v[48:51]
	v_mfma_f32_16x16x32_bf16 v[44:47], v[136:139], v[196:199], v[44:47]
	v_mfma_f32_16x16x32_bf16 v[36:39], v[128:131], v[204:207], v[36:39]
	v_mfma_f32_16x16x32_bf16 v[28:31], v[136:139], v[204:207], v[28:31]
	v_mfma_f32_16x16x32_bf16 v[20:23], v[128:131], v[212:215], v[20:23]
	v_mfma_f32_16x16x32_bf16 v[12:15], v[136:139], v[212:215], v[12:15]
	v_mfma_f32_16x16x32_bf16 v[60:63], v[132:135], v[192:195], v[60:63]
	v_mfma_f32_16x16x32_bf16 v[56:59], v[140:143], v[192:195], v[56:59]
	v_mfma_f32_16x16x32_bf16 v[48:51], v[132:135], v[200:203], v[48:51]
	v_mfma_f32_16x16x32_bf16 v[44:47], v[140:143], v[200:203], v[44:47]
	v_mfma_f32_16x16x32_bf16 v[36:39], v[132:135], v[208:211], v[36:39]
	v_mfma_f32_16x16x32_bf16 v[28:31], v[140:143], v[208:211], v[28:31]
	v_mfma_f32_16x16x32_bf16 v[20:23], v[132:135], v[216:219], v[20:23]
	v_mfma_f32_16x16x32_bf16 v[12:15], v[140:143], v[216:219], v[12:15]
	s_setprio 0
	s_setprio 1
	v_mfma_f32_16x16x32_bf16 v[52:55], v[162:165], v[188:191], v[52:55]
	v_mfma_f32_16x16x32_bf16 v[40:43], v[176:179], v[188:191], v[40:43]
	v_mfma_f32_16x16x32_bf16 v[32:35], v[162:165], v[196:199], v[32:35]
	v_mfma_f32_16x16x32_bf16 v[24:27], v[176:179], v[196:199], v[24:27]
	v_mfma_f32_16x16x32_bf16 v[16:19], v[162:165], v[204:207], v[16:19]
	v_mfma_f32_16x16x32_bf16 v[8:11], v[176:179], v[204:207], v[8:11]
	v_mfma_f32_16x16x32_bf16 v[4:7], v[162:165], v[212:215], v[4:7]
	v_mfma_f32_16x16x32_bf16 v[0:3], v[176:179], v[212:215], v[0:3]
	v_mfma_f32_16x16x32_bf16 v[52:55], v[172:175], v[192:195], v[52:55]
	v_mfma_f32_16x16x32_bf16 v[40:43], v[184:187], v[192:195], v[40:43]
	v_mfma_f32_16x16x32_bf16 v[32:35], v[172:175], v[200:203], v[32:35]
	v_mfma_f32_16x16x32_bf16 v[24:27], v[184:187], v[200:203], v[24:27]
	v_mfma_f32_16x16x32_bf16 v[16:19], v[172:175], v[208:211], v[16:19]
	v_mfma_f32_16x16x32_bf16 v[8:11], v[184:187], v[208:211], v[8:11]
	v_mfma_f32_16x16x32_bf16 v[4:7], v[172:175], v[216:219], v[4:7]
	v_mfma_f32_16x16x32_bf16 v[0:3], v[184:187], v[216:219], v[0:3]
	s_setprio 0
	s_barrier
	s_add_i32 s74, s74, 2
	s_add_u32 s71, s71, 0x100
	s_addc_u32 s73, s73, 0
	s_cmp_gt_u32 s74, 41
	s_mov_b64 s[40:41], s[42:43]
	s_cbranch_scc0 .LBB0_872
	s_and_b64 vcc, exec, s[34:35]
	s_cbranch_vccz .LBB0_875
	s_barrier

; #define PG8_STAGE(bufoff, gbase, voff) do { _Pragma("unroll") for (int _i = 0; _i < 2; ++_i) \
;         __builtin_amdgcn_global_load_lds((const unsigned*)((const char*)(gbase) + (voff)[_i]), (PG8_LAS unsigned*)(lds + (bufoff) + ldsw + _i * 8192), 16, 0, 0); } while (0)
; #define PG8_LDA(dst, b, h) do { _Pragma("unroll") for (int m = 0; m < 4; ++m) _Pragma("unroll") for (int k = 0; k < 2; ++k) dst[m][k] = *(const PG8_LAS bf16x8*)(lds + PG8_SA(b, h) + aoff + m * 2048 + k * 1024); } while (0)
; #define PG8_LDB(dst, b, h) do { _Pragma("unroll") for (int n = 0; n < 2; ++n) _Pragma("unroll") for (int k = 0; k < 2; ++k) dst[n][k] = *(const PG8_LAS bf16x8*)(lds + PG8_SB(b, h) + boff + n * 2048 + k * 1024); } while (0)
; #define PG8_MMA(ai, bj, At, Bt) do { __builtin_amdgcn_s_setprio(1); _Pragma("unroll") for (int m = 0; m < 4; ++m) _Pragma("unroll") for (int n = 0; n < 2; ++n) _Pragma("unroll") for (int k = 0; k < 2; ++k) \
;         acc[ai][bj][m][n] = __builtin_amdgcn_mfma_f32_16x16x32_bf16(Bt[n][k], At[m][k], acc[ai][bj][m][n], 0, 0, 0); __builtin_amdgcn_s_setprio(0); } while (0)
; #define PG8_WAIT_V(n) asm volatile("s_waitcnt vmcnt(" #n ")" ::: "memory")
; template <class Epi, class Sched, bool ALIGN_EPI = false, bool SP2 = false>
; __device__ __forceinline__ void gemm_phase(PG8_LAS unsigned char* lds, const Gemm g, const Sched& S, const Epi& E) {
;     ...
;         for (int t = 0; t < nt; t += 2) {
;             const bool last = (t == nt - 2);
;             const char* a1 = cA + (size_t)(t + 1) * kstep;
;             const char* a2 = last ? nA : cA + (size_t)(t + 2) * kstep; const char* b2 = last ? nB : cB + (size_t)(t + 2) * kstep;
;             const char* a3 = a2 + kstep; const char* b3 = b2 + kstep;
;             if (last && has_next) S.a_ready(nxt);
;             if (last) E.prefetch(lds + 139264, cur, wid, lane);
;             if constexpr (SP2) {
;             PG8_LDB(B0, 0, 0); PG8_LDB(B1, 0, 1); PG8_SCHED; PG8_LDA(At, 0, 0); PG8_STAGE(PG8_SA(1, 1), a1 + hstep, voffA);
;             PG8_WAIT_V(8); PG8_WAIT_L(0); PG8_BAR; PG8_MMA(0, 0, At, B0); PG8_MMA(0, 1, At, B1); PG8_BAR; PG8_SCHED;
;             PG8_LDA(At, 0, 1); PG8_STAGE(PG8_SB(0, 0), b2, voffB); PG8_STAGE(PG8_SB(0, 1), b2 + hstep, voffB); PG8_STAGE(PG8_SA(0, 0), a2, voffA);
;             PG8_WAIT_V(8); PG8_WAIT_L(0); PG8_BAR; PG8_MMA(1, 0, At, B0); PG8_MMA(1, 1, At, B1); PG8_BAR; PG8_SCHED;
.LBB0_960:
	v_add_u32_e32 v130, s89, v169
	ds_read_b128 v[150:153], v130
	ds_read_b128 v[158:161], v130 offset:1024
	ds_read_b128 v[162:165], v130 offset:2048
	ds_read_b128 v[196:199], v130 offset:3072
	v_add_u32_e32 v130, s90, v169
	ds_read_b128 v[200:203], v130
	ds_read_b128 v[204:207], v130 offset:1024
	ds_read_b128 v[208:211], v130 offset:2048
	ds_read_b128 v[212:215], v130 offset:3072
	s_add_u32 s12, s10, 0xfffc0080
	s_addc_u32 s13, s11, -1
	s_and_b64 s[66:67], s[66:67], exec
	s_cselect_b32 s69, s57, s13
	s_cselect_b32 s68, s63, s12
	s_cselect_b32 s67, s55, s71
	s_cselect_b32 s66, s70, s65
	s_add_i32 m0, s75, 0xc000
	ds_read_b128 v[216:219], v191
	ds_read_b128 v[220:223], v191 offset:1024
	ds_read_b128 v[224:227], v191 offset:2048
	ds_read_b128 v[228:231], v191 offset:3072
	ds_read_b128 v[232:235], v191 offset:4096
	ds_read_b128 v[236:239], v191 offset:5120
	ds_read_b128 v[240:243], v191 offset:6144
	ds_read_b128 v[244:247], v191 offset:7168
	global_load_lds_dwordx4 v142, s[10:11]
	s_add_i32 m0, s75, 0xe000
	s_nop 0
	global_load_lds_dwordx4 v140, s[10:11]
	s_waitcnt vmcnt(8)
	s_waitcnt lgkmcnt(0)
	s_barrier
	s_setprio 1
	s_waitcnt lgkmcnt(0)
	v_mfma_f32_16x16x32_bf16 v[124:127], v[150:153], v[216:219], v[124:127]
	v_mfma_f32_16x16x32_bf16 v[120:123], v[162:165], v[216:219], v[120:123]
	v_mfma_f32_16x16x32_bf16 v[112:115], v[150:153], v[224:227], v[112:115]
	v_mfma_f32_16x16x32_bf16 v[104:107], v[162:165], v[224:227], v[104:107]
	v_mfma_f32_16x16x32_bf16 v[100:103], v[150:153], v[232:235], v[100:103]
	v_mfma_f32_16x16x32_bf16 v[96:99], v[162:165], v[232:235], v[96:99]
	v_mfma_f32_16x16x32_bf16 v[80:83], v[150:153], v[240:243], v[80:83]
	v_mfma_f32_16x16x32_bf16 v[72:75], v[162:165], v[240:243], v[72:75]
	v_mfma_f32_16x16x32_bf16 v[124:127], v[158:161], v[220:223], v[124:127]
	v_mfma_f32_16x16x32_bf16 v[120:123], v[196:199], v[220:223], v[120:123]
	v_mfma_f32_16x16x32_bf16 v[112:115], v[158:161], v[228:231], v[112:115]
	v_mfma_f32_16x16x32_bf16 v[104:107], v[196:199], v[228:231], v[104:107]
	v_mfma_f32_16x16x32_bf16 v[100:103], v[158:161], v[236:239], v[100:103]
	v_mfma_f32_16x16x32_bf16 v[96:99], v[196:199], v[236:239], v[96:99]
	v_mfma_f32_16x16x32_bf16 v[80:83], v[158:161], v[244:247], v[80:83]
	v_mfma_f32_16x16x32_bf16 v[72:75], v[196:199], v[244:247], v[72:75]
	s_setprio 0
	s_setprio 1
	v_mfma_f32_16x16x32_bf16 v[116:119], v[200:203], v[216:219], v[116:119]
	v_mfma_f32_16x16x32_bf16 v[108:111], v[208:211], v[216:219], v[108:111]
	v_mfma_f32_16x16x32_bf16 v[92:95], v[200:203], v[224:227], v[92:95]
	v_mfma_f32_16x16x32_bf16 v[88:91], v[208:211], v[224:227], v[88:91]
	v_mfma_f32_16x16x32_bf16 v[84:87], v[200:203], v[232:235], v[84:87]
	v_mfma_f32_16x16x32_bf16 v[76:79], v[208:211], v[232:235], v[76:79]
	v_mfma_f32_16x16x32_bf16 v[68:71], v[200:203], v[240:243], v[68:71]
	v_mfma_f32_16x16x32_bf16 v[64:67], v[208:211], v[240:243], v[64:67]
	v_mfma_f32_16x16x32_bf16 v[116:119], v[204:207], v[220:223], v[116:119]
	v_mfma_f32_16x16x32_bf16 v[108:111], v[212:215], v[220:223], v[108:111]
	v_mfma_f32_16x16x32_bf16 v[92:95], v[204:207], v[228:231], v[92:95]
	v_mfma_f32_16x16x32_bf16 v[88:91], v[212:215], v[228:231], v[88:91]
	v_mfma_f32_16x16x32_bf16 v[84:87], v[204:207], v[236:239], v[84:87]
	v_mfma_f32_16x16x32_bf16 v[76:79], v[212:215], v[236:239], v[76:79]
	v_mfma_f32_16x16x32_bf16 v[68:71], v[204:207], v[244:247], v[68:71]
	v_mfma_f32_16x16x32_bf16 v[64:67], v[212:215], v[244:247], v[64:67]
	s_setprio 0
	s_barrier
	s_add_i32 s12, s89, s74
	s_mov_b32 m0, s12
	ds_read_b128 v[216:219], v191 offset:16384
	ds_read_b128 v[220:223], v191 offset:17408
	ds_read_b128 v[224:227], v191 offset:18432
	ds_read_b128 v[228:231], v191 offset:19456
	ds_read_b128 v[232:235], v191 offset:20480
	ds_read_b128 v[236:239], v191 offset:21504
	ds_read_b128 v[240:243], v191 offset:22528
	ds_read_b128 v[244:247], v191 offset:23552
	global_load_lds_dwordx4 v134, s[66:67]
	s_add_i32 m0, s12, 0x2000
	s_add_u32 vcc_lo, s66, 0x40000
	v_lshl_add_u64 v[154:155], s[66:67], 0, v[138:139]
	s_addc_u32 vcc_hi, s67, 0
	s_add_i32 s12, s90, s74
	global_load_lds_dwordx4 v138, s[66:67]
	v_lshl_add_u64 v[166:167], vcc, 0, v[134:135]
	s_mov_b32 m0, s12
	v_lshl_add_u64 v[248:249], s[68:69], 0, v[136:137]
	global_load_lds_dwordx4 v[166:167], off
	v_lshl_add_u64 v[166:167], vcc, 0, v[138:139]
	s_add_i32 m0, s12, 0x2000
	s_nop 0
	global_load_lds_dwordx4 v[166:167], off
	v_lshl_add_u64 v[166:167], s[68:69], 0, v[132:133]
	s_mov_b32 m0, s75
	s_nop 0
	global_load_lds_dwordx4 v132, s[68:69]
	s_mov_b32 m0, s76
	s_nop 0
	global_load_lds_dwordx4 v136, s[68:69]
	s_waitcnt vmcnt(8)
	s_waitcnt lgkmcnt(0)
	s_barrier
; #define PG8_STAGE(bufoff, gbase, voff) do { _Pragma("unroll") for (int _i = 0; _i < 2; ++_i) \
;         __builtin_amdgcn_global_load_lds((const unsigned*)((const char*)(gbase) + (voff)[_i]), (PG8_LAS unsigned*)(lds + (bufoff) + ldsw + _i * 8192), 16, 0, 0); } while (0)
; #define PG8_LDA(dst, b, h) do { _Pragma("unroll") for (int m = 0; m < 4; ++m) _Pragma("unroll") for (int k = 0; k < 2; ++k) dst[m][k] = *(const PG8_LAS bf16x8*)(lds + PG8_SA(b, h) + aoff + m * 2048 + k * 1024); } while (0)
; #define PG8_LDB(dst, b, h) do { _Pragma("unroll") for (int n = 0; n < 2; ++n) _Pragma("unroll") for (int k = 0; k < 2; ++k) dst[n][k] = *(const PG8_LAS bf16x8*)(lds + PG8_SB(b, h) + boff + n * 2048 + k * 1024); } while (0)
; #define PG8_MMA(ai, bj, At, Bt) do { __builtin_amdgcn_s_setprio(1); _Pragma("unroll") for (int m = 0; m < 4; ++m) _Pragma("unroll") for (int n = 0; n < 2; ++n) _Pragma("unroll") for (int k = 0; k < 2; ++k) \
;         acc[ai][bj][m][n] = __builtin_amdgcn_mfma_f32_16x16x32_bf16(Bt[n][k], At[m][k], acc[ai][bj][m][n], 0, 0, 0); __builtin_amdgcn_s_setprio(0); } while (0)
; #define PG8_WAIT_V(n) asm volatile("s_waitcnt vmcnt(" #n ")" ::: "memory")
; #define PG8_WAIT_L(n) asm volatile("s_waitcnt lgkmcnt(" #n ")" ::: "memory")
; #define PG8_BAR __builtin_amdgcn_s_barrier()
; #define PG8_SCHED __builtin_amdgcn_sched_barrier(0)
; template <class Epi, class Sched, bool ALIGN_EPI = false, bool SP2 = false>
; __device__ __forceinline__ void gemm_phase(PG8_LAS unsigned char* lds, const Gemm g, const Sched& S, const Epi& E) {
;     ...
;             PG8_WAIT_V(8); PG8_WAIT_L(0); PG8_BAR; PG8_MMA(1, 0, At, B0); PG8_MMA(1, 1, At, B1); PG8_BAR; PG8_SCHED;
;             PG8_LDB(B0, 1, 0); PG8_LDB(B1, 1, 1); PG8_SCHED; PG8_LDA(At, 1, 0); PG8_STAGE(PG8_SA(0, 1), a2 + hstep, voffA);
;             PG8_WAIT_V(8); PG8_WAIT_L(0); PG8_BAR; PG8_MMA(0, 0, At, B0); PG8_MMA(0, 1, At, B1); PG8_BAR; PG8_SCHED;
	s_setprio 1
	s_waitcnt lgkmcnt(0)
	v_mfma_f32_16x16x32_bf16 v[60:63], v[150:153], v[216:219], v[60:63]
	v_mfma_f32_16x16x32_bf16 v[56:59], v[162:165], v[216:219], v[56:59]
	v_mfma_f32_16x16x32_bf16 v[48:51], v[150:153], v[224:227], v[48:51]
	v_mfma_f32_16x16x32_bf16 v[40:43], v[162:165], v[224:227], v[40:43]
	v_mfma_f32_16x16x32_bf16 v[36:39], v[150:153], v[232:235], v[36:39]
	v_mfma_f32_16x16x32_bf16 v[32:35], v[162:165], v[232:235], v[32:35]
	v_mfma_f32_16x16x32_bf16 v[20:23], v[150:153], v[240:243], v[20:23]
	v_mfma_f32_16x16x32_bf16 v[16:19], v[162:165], v[240:243], v[16:19]
	v_mfma_f32_16x16x32_bf16 v[60:63], v[158:161], v[220:223], v[60:63]
	v_mfma_f32_16x16x32_bf16 v[56:59], v[196:199], v[220:223], v[56:59]
	v_mfma_f32_16x16x32_bf16 v[48:51], v[158:161], v[228:231], v[48:51]
	v_mfma_f32_16x16x32_bf16 v[40:43], v[196:199], v[228:231], v[40:43]
	v_mfma_f32_16x16x32_bf16 v[36:39], v[158:161], v[236:239], v[36:39]
	v_mfma_f32_16x16x32_bf16 v[32:35], v[196:199], v[236:239], v[32:35]
	v_mfma_f32_16x16x32_bf16 v[20:23], v[158:161], v[244:247], v[20:23]
	v_mfma_f32_16x16x32_bf16 v[16:19], v[196:199], v[244:247], v[16:19]
	s_setprio 0
	s_setprio 1
	v_mfma_f32_16x16x32_bf16 v[52:55], v[200:203], v[216:219], v[52:55]
	v_mfma_f32_16x16x32_bf16 v[44:47], v[208:211], v[216:219], v[44:47]
	v_mfma_f32_16x16x32_bf16 v[28:31], v[200:203], v[224:227], v[28:31]
	v_mfma_f32_16x16x32_bf16 v[24:27], v[208:211], v[224:227], v[24:27]
	v_mfma_f32_16x16x32_bf16 v[12:15], v[200:203], v[232:235], v[12:15]
	v_mfma_f32_16x16x32_bf16 v[8:11], v[208:211], v[232:235], v[8:11]
	v_mfma_f32_16x16x32_bf16 v[4:7], v[200:203], v[240:243], v[4:7]
	v_mfma_f32_16x16x32_bf16 v[0:3], v[208:211], v[240:243], v[0:3]
	v_mfma_f32_16x16x32_bf16 v[52:55], v[204:207], v[220:223], v[52:55]
	v_mfma_f32_16x16x32_bf16 v[44:47], v[212:215], v[220:223], v[44:47]
	v_mfma_f32_16x16x32_bf16 v[28:31], v[204:207], v[228:231], v[28:31]
	v_mfma_f32_16x16x32_bf16 v[24:27], v[212:215], v[228:231], v[24:27]
	v_mfma_f32_16x16x32_bf16 v[12:15], v[204:207], v[236:239], v[12:15]
	v_mfma_f32_16x16x32_bf16 v[8:11], v[212:215], v[236:239], v[8:11]
	v_mfma_f32_16x16x32_bf16 v[4:7], v[204:207], v[244:247], v[4:7]
	v_mfma_f32_16x16x32_bf16 v[0:3], v[212:215], v[244:247], v[0:3]
	s_setprio 0
	s_barrier
	s_add_i32 s12, 0, 0x18000
	v_add_u32_e32 v195, s12, v169
	s_add_i32 s13, 0, 0x1c000
	ds_read_b128 v[150:153], v195
	ds_read_b128 v[158:161], v195 offset:1024
	ds_read_b128 v[162:165], v195 offset:2048
	ds_read_b128 v[196:199], v195 offset:3072
	v_add_u32_e32 v195, s13, v169
	ds_read_b128 v[200:203], v195
	ds_read_b128 v[204:207], v195 offset:1024
	ds_read_b128 v[208:211], v195 offset:2048
	ds_read_b128 v[212:215], v195 offset:3072
	s_add_u32 s68, s68, 0x40000
	s_addc_u32 s69, s69, 0
	s_mov_b32 m0, s77
	ds_read_b128 v[216:219], v191 offset:32768
	ds_read_b128 v[220:223], v191 offset:33792
	ds_read_b128 v[224:227], v191 offset:34816
	ds_read_b128 v[228:231], v191 offset:35840
	ds_read_b128 v[232:235], v191 offset:36864
	ds_read_b128 v[236:239], v191 offset:37888
	ds_read_b128 v[240:243], v191 offset:38912
	ds_read_b128 v[244:247], v191 offset:39936
	global_load_lds_dwordx4 v132, s[68:69]
	s_mov_b32 m0, s78
	s_nop 0
	global_load_lds_dwordx4 v136, s[68:69]
	s_waitcnt vmcnt(8)
	s_waitcnt lgkmcnt(0)
	s_barrier
	s_setprio 1
	s_waitcnt lgkmcnt(0)
	v_mfma_f32_16x16x32_bf16 v[124:127], v[150:153], v[216:219], v[124:127]
	v_mfma_f32_16x16x32_bf16 v[120:123], v[162:165], v[216:219], v[120:123]
	v_mfma_f32_16x16x32_bf16 v[112:115], v[150:153], v[224:227], v[112:115]
	v_mfma_f32_16x16x32_bf16 v[104:107], v[162:165], v[224:227], v[104:107]
	v_mfma_f32_16x16x32_bf16 v[100:103], v[150:153], v[232:235], v[100:103]
	v_mfma_f32_16x16x32_bf16 v[96:99], v[162:165], v[232:235], v[96:99]
	v_mfma_f32_16x16x32_bf16 v[80:83], v[150:153], v[240:243], v[80:83]
	v_mfma_f32_16x16x32_bf16 v[72:75], v[162:165], v[240:243], v[72:75]
	v_mfma_f32_16x16x32_bf16 v[124:127], v[158:161], v[220:223], v[124:127]
	v_mfma_f32_16x16x32_bf16 v[120:123], v[196:199], v[220:223], v[120:123]
	v_mfma_f32_16x16x32_bf16 v[112:115], v[158:161], v[228:231], v[112:115]
	v_mfma_f32_16x16x32_bf16 v[104:107], v[196:199], v[228:231], v[104:107]
	v_mfma_f32_16x16x32_bf16 v[100:103], v[158:161], v[236:239], v[100:103]
	v_mfma_f32_16x16x32_bf16 v[96:99], v[196:199], v[236:239], v[96:99]
	v_mfma_f32_16x16x32_bf16 v[80:83], v[158:161], v[244:247], v[80:83]
	v_mfma_f32_16x16x32_bf16 v[72:75], v[196:199], v[244:247], v[72:75]
	s_setprio 0
	s_setprio 1
	v_mfma_f32_16x16x32_bf16 v[116:119], v[200:203], v[216:219], v[116:119]
	v_mfma_f32_16x16x32_bf16 v[108:111], v[208:211], v[216:219], v[108:111]
	v_mfma_f32_16x16x32_bf16 v[92:95], v[200:203], v[224:227], v[92:95]
	v_mfma_f32_16x16x32_bf16 v[88:91], v[208:211], v[224:227], v[88:91]
	v_mfma_f32_16x16x32_bf16 v[84:87], v[200:203], v[232:235], v[84:87]
	v_mfma_f32_16x16x32_bf16 v[76:79], v[208:211], v[232:235], v[76:79]
	v_mfma_f32_16x16x32_bf16 v[68:71], v[200:203], v[240:243], v[68:71]
	v_mfma_f32_16x16x32_bf16 v[64:67], v[208:211], v[240:243], v[64:67]
	v_mfma_f32_16x16x32_bf16 v[116:119], v[204:207], v[220:223], v[116:119]
	v_mfma_f32_16x16x32_bf16 v[108:111], v[212:215], v[220:223], v[108:111]
	v_mfma_f32_16x16x32_bf16 v[92:95], v[204:207], v[228:231], v[92:95]
	v_mfma_f32_16x16x32_bf16 v[88:91], v[212:215], v[228:231], v[88:91]
	v_mfma_f32_16x16x32_bf16 v[84:87], v[204:207], v[236:239], v[84:87]
	v_mfma_f32_16x16x32_bf16 v[76:79], v[212:215], v[236:239], v[76:79]
	v_mfma_f32_16x16x32_bf16 v[68:71], v[204:207], v[244:247], v[68:71]
	v_mfma_f32_16x16x32_bf16 v[64:67], v[212:215], v[244:247], v[64:67]
	s_setprio 0
	s_barrier
; #define PG8_STAGE(bufoff, gbase, voff) do { _Pragma("unroll") for (int _i = 0; _i < 2; ++_i) \
;         __builtin_amdgcn_global_load_lds((const unsigned*)((const char*)(gbase) + (voff)[_i]), (PG8_LAS unsigned*)(lds + (bufoff) + ldsw + _i * 8192), 16, 0, 0); } while (0)
; #define PG8_LDA(dst, b, h) do { _Pragma("unroll") for (int m = 0; m < 4; ++m) _Pragma("unroll") for (int k = 0; k < 2; ++k) dst[m][k] = *(const PG8_LAS bf16x8*)(lds + PG8_SA(b, h) + aoff + m * 2048 + k * 1024); } while (0)
; #define PG8_MMA(ai, bj, At, Bt) do { __builtin_amdgcn_s_setprio(1); _Pragma("unroll") for (int m = 0; m < 4; ++m) _Pragma("unroll") for (int n = 0; n < 2; ++n) _Pragma("unroll") for (int k = 0; k < 2; ++k) \
;         acc[ai][bj][m][n] = __builtin_amdgcn_mfma_f32_16x16x32_bf16(Bt[n][k], At[m][k], acc[ai][bj][m][n], 0, 0, 0); __builtin_amdgcn_s_setprio(0); } while (0)
; #define PG8_WAIT_V(n) asm volatile("s_waitcnt vmcnt(" #n ")" ::: "memory")
; #define PG8_WAIT_L(n) asm volatile("s_waitcnt lgkmcnt(" #n ")" ::: "memory")
; #define PG8_BAR __builtin_amdgcn_s_barrier()
; #define PG8_SCHED __builtin_amdgcn_sched_barrier(0)
; template <class Epi, class Sched, bool ALIGN_EPI = false, bool SP2 = false>
; __device__ __forceinline__ void gemm_phase(PG8_LAS unsigned char* lds, const Gemm g, const Sched& S, const Epi& E) {
;     ...
;         for (int t = 0; t < nt; t += 2) {
;     ...
;             PG8_LDA(At, 1, 1); PG8_STAGE(PG8_SB(1, 0), b3, voffB); PG8_STAGE(PG8_SB(1, 1), b3 + hstep, voffB); PG8_STAGE(PG8_SA(1, 0), a3, voffA);
;             PG8_WAIT_V(8); PG8_WAIT_L(0); PG8_BAR; PG8_MMA(1, 0, At, B0); PG8_MMA(1, 1, At, B1); PG8_BAR; PG8_SCHED;
	s_add_i32 s12, s12, s74
	s_add_u32 s98, s66, s42
	s_addc_u32 s99, s67, s43
	s_mov_b32 m0, s12
	ds_read_b128 v[216:219], v191 offset:49152
	ds_read_b128 v[220:223], v191 offset:50176
	ds_read_b128 v[224:227], v191 offset:51200
	ds_read_b128 v[228:231], v191 offset:52224
	ds_read_b128 v[232:235], v191 offset:53248
	ds_read_b128 v[236:239], v191 offset:54272
	ds_read_b128 v[240:243], v191 offset:55296
	ds_read_b128 v[244:247], v191 offset:56320
	global_load_lds_dwordx4 v134, s[98:99]
	s_add_i32 m0, s12, 0x2000
	s_add_u32 s66, s66, 0x40080
	v_lshl_add_u64 v[130:131], v[154:155], 0, s[42:43]
	s_addc_u32 s67, s67, 0
	s_add_i32 s12, s13, s74
	global_load_lds_dwordx4 v[130:131], off
	s_mov_b32 m0, s12
	s_nop 0
	global_load_lds_dwordx4 v134, s[66:67]
	s_add_i32 m0, s12, 0x2000
	s_nop 0
	global_load_lds_dwordx4 v138, s[66:67]
	v_lshl_add_u64 v[130:131], v[166:167], 0, s[42:43]
	s_mov_b32 m0, s79
	s_nop 0
	global_load_lds_dwordx4 v[130:131], off
	v_lshl_add_u64 v[130:131], v[248:249], 0, s[42:43]
	s_mov_b32 m0, s80
	s_nop 0
	global_load_lds_dwordx4 v[130:131], off
	s_waitcnt vmcnt(8)
	s_waitcnt lgkmcnt(0)
	s_barrier
	s_setprio 1
	s_waitcnt lgkmcnt(0)
	v_mfma_f32_16x16x32_bf16 v[60:63], v[150:153], v[216:219], v[60:63]
	v_mfma_f32_16x16x32_bf16 v[56:59], v[162:165], v[216:219], v[56:59]
	v_mfma_f32_16x16x32_bf16 v[48:51], v[150:153], v[224:227], v[48:51]
	v_mfma_f32_16x16x32_bf16 v[40:43], v[162:165], v[224:227], v[40:43]
	v_mfma_f32_16x16x32_bf16 v[36:39], v[150:153], v[232:235], v[36:39]
	v_mfma_f32_16x16x32_bf16 v[32:35], v[162:165], v[232:235], v[32:35]
	v_mfma_f32_16x16x32_bf16 v[20:23], v[150:153], v[240:243], v[20:23]
	v_mfma_f32_16x16x32_bf16 v[16:19], v[162:165], v[240:243], v[16:19]
	v_mfma_f32_16x16x32_bf16 v[60:63], v[158:161], v[220:223], v[60:63]
	v_mfma_f32_16x16x32_bf16 v[56:59], v[196:199], v[220:223], v[56:59]
	v_mfma_f32_16x16x32_bf16 v[48:51], v[158:161], v[228:231], v[48:51]
	v_mfma_f32_16x16x32_bf16 v[40:43], v[196:199], v[228:231], v[40:43]
	v_mfma_f32_16x16x32_bf16 v[36:39], v[158:161], v[236:239], v[36:39]
	v_mfma_f32_16x16x32_bf16 v[32:35], v[196:199], v[236:239], v[32:35]
	v_mfma_f32_16x16x32_bf16 v[20:23], v[158:161], v[244:247], v[20:23]
	v_mfma_f32_16x16x32_bf16 v[16:19], v[196:199], v[244:247], v[16:19]
	s_setprio 0
	s_setprio 1
	v_mfma_f32_16x16x32_bf16 v[52:55], v[200:203], v[216:219], v[52:55]
	v_mfma_f32_16x16x32_bf16 v[44:47], v[208:211], v[216:219], v[44:47]
	v_mfma_f32_16x16x32_bf16 v[28:31], v[200:203], v[224:227], v[28:31]
	v_mfma_f32_16x16x32_bf16 v[24:27], v[208:211], v[224:227], v[24:27]
	v_mfma_f32_16x16x32_bf16 v[12:15], v[200:203], v[232:235], v[12:15]
	v_mfma_f32_16x16x32_bf16 v[8:11], v[208:211], v[232:235], v[8:11]
	v_mfma_f32_16x16x32_bf16 v[4:7], v[200:203], v[240:243], v[4:7]
	v_mfma_f32_16x16x32_bf16 v[0:3], v[208:211], v[240:243], v[0:3]
	v_mfma_f32_16x16x32_bf16 v[52:55], v[204:207], v[220:223], v[52:55]
	v_mfma_f32_16x16x32_bf16 v[44:47], v[212:215], v[220:223], v[44:47]
	v_mfma_f32_16x16x32_bf16 v[28:31], v[204:207], v[228:231], v[28:31]
	v_mfma_f32_16x16x32_bf16 v[24:27], v[212:215], v[228:231], v[24:27]
	v_mfma_f32_16x16x32_bf16 v[12:15], v[204:207], v[236:239], v[12:15]
	v_mfma_f32_16x16x32_bf16 v[8:11], v[212:215], v[236:239], v[8:11]
	v_mfma_f32_16x16x32_bf16 v[4:7], v[204:207], v[244:247], v[4:7]
	v_mfma_f32_16x16x32_bf16 v[0:3], v[212:215], v[244:247], v[0:3]
	s_setprio 0
	s_barrier
	s_add_i32 s96, s96, 2
	s_add_u32 s65, s65, 0x100
	s_addc_u32 s71, s71, 0
	s_add_u32 s10, s10, 0x100
	s_addc_u32 s11, s11, 0
	s_cmp_gt_u32 s96, 13
	s_cbranch_scc1 .LBB0_963

; #define PG8_STAGE(bufoff, gbase, voff) do { _Pragma("unroll") for (int _i = 0; _i < 2; ++_i) \
;         __builtin_amdgcn_global_load_lds((const unsigned*)((const char*)(gbase) + (voff)[_i]), (PG8_LAS unsigned*)(lds + (bufoff) + ldsw + _i * 8192), 16, 0, 0); } while (0)
; #define PG8_LDA(dst, b, h) do { _Pragma("unroll") for (int m = 0; m < 4; ++m) _Pragma("unroll") for (int k = 0; k < 2; ++k) dst[m][k] = *(const PG8_LAS bf16x8*)(lds + PG8_SA(b, h) + aoff + m * 2048 + k * 1024); } while (0)
; #define PG8_LDB(dst, b, h) do { _Pragma("unroll") for (int n = 0; n < 2; ++n) _Pragma("unroll") for (int k = 0; k < 2; ++k) dst[n][k] = *(const PG8_LAS bf16x8*)(lds + PG8_SB(b, h) + boff + n * 2048 + k * 1024); } while (0)
; #define PG8_MMA(ai, bj, At, Bt) do { __builtin_amdgcn_s_setprio(1); _Pragma("unroll") for (int m = 0; m < 4; ++m) _Pragma("unroll") for (int n = 0; n < 2; ++n) _Pragma("unroll") for (int k = 0; k < 2; ++k) \
;         acc[ai][bj][m][n] = __builtin_amdgcn_mfma_f32_16x16x32_bf16(Bt[n][k], At[m][k], acc[ai][bj][m][n], 0, 0, 0); __builtin_amdgcn_s_setprio(0); } while (0)
; #define PG8_WAIT_V(n) asm volatile("s_waitcnt vmcnt(" #n ")" ::: "memory")
; template <class Epi, class Sched, bool ALIGN_EPI = false, bool SP2 = false>
; __device__ __forceinline__ void gemm_phase(PG8_LAS unsigned char* lds, const Gemm g, const Sched& S, const Epi& E) {
;     ...
;         for (int t = 0; t < nt; t += 2) {
;             const bool last = (t == nt - 2);
;             const char* a1 = cA + (size_t)(t + 1) * kstep;
;             const char* a2 = last ? nA : cA + (size_t)(t + 2) * kstep; const char* b2 = last ? nB : cB + (size_t)(t + 2) * kstep;
;             const char* a3 = a2 + kstep; const char* b3 = b2 + kstep;
;             if (last && has_next) S.a_ready(nxt);
;             if (last) E.prefetch(lds + 139264, cur, wid, lane);
;             if constexpr (SP2) {
;             PG8_LDB(B0, 0, 0); PG8_LDB(B1, 0, 1); PG8_SCHED; PG8_LDA(At, 0, 0); PG8_STAGE(PG8_SA(1, 1), a1 + hstep, voffA);
;             PG8_WAIT_V(8); PG8_WAIT_L(0); PG8_BAR; PG8_MMA(0, 0, At, B0); PG8_MMA(0, 1, At, B1); PG8_BAR; PG8_SCHED;
;             PG8_LDA(At, 0, 1); PG8_STAGE(PG8_SB(0, 0), b2, voffB); PG8_STAGE(PG8_SB(0, 1), b2 + hstep, voffB); PG8_STAGE(PG8_SA(0, 0), a2, voffA);
;             PG8_WAIT_V(8); PG8_WAIT_L(0); PG8_BAR; PG8_MMA(1, 0, At, B0); PG8_MMA(1, 1, At, B1); PG8_BAR; PG8_SCHED;
.LBB0_1272:
	ds_read_b128 v[128:131], v167
	ds_read_b128 v[132:135], v167 offset:1024
	ds_read_b128 v[136:139], v167 offset:2048
	ds_read_b128 v[140:143], v167 offset:3072
	ds_read_b128 v[160:163], v168
	ds_read_b128 v[170:173], v168 offset:1024
	ds_read_b128 v[174:177], v168 offset:2048
	ds_read_b128 v[178:181], v168 offset:3072
	s_add_u32 s12, s50, 0xfffc0080
	s_addc_u32 s13, s51, -1
	s_cmp_eq_u32 s79, 12
	s_cselect_b32 s55, s41, s13
	s_cselect_b32 s54, s47, s12
	s_cselect_b32 s53, s39, s78
	s_cselect_b32 s52, s49, s77
	s_add_i32 m0, s60, 0xc000
	ds_read_b128 v[188:191], v169
	ds_read_b128 v[192:195], v169 offset:1024
	ds_read_b128 v[196:199], v169 offset:2048
	ds_read_b128 v[200:203], v169 offset:3072
	ds_read_b128 v[204:207], v169 offset:4096
	ds_read_b128 v[208:211], v169 offset:5120
	ds_read_b128 v[212:215], v169 offset:6144
	ds_read_b128 v[216:219], v169 offset:7168
	global_load_lds_dwordx4 v154, s[50:51]
	s_add_i32 m0, s60, 0xe000
	s_nop 0
	global_load_lds_dwordx4 v152, s[50:51]
	s_waitcnt vmcnt(8)
	s_waitcnt lgkmcnt(0)
	s_barrier
	s_setprio 1
	s_waitcnt lgkmcnt(0)
	v_mfma_f32_16x16x32_bf16 v[124:127], v[128:131], v[188:191], v[124:127]
	v_mfma_f32_16x16x32_bf16 v[120:123], v[136:139], v[188:191], v[120:123]
	v_mfma_f32_16x16x32_bf16 v[116:119], v[128:131], v[196:199], v[116:119]
	v_mfma_f32_16x16x32_bf16 v[108:111], v[136:139], v[196:199], v[108:111]
	v_mfma_f32_16x16x32_bf16 v[100:103], v[128:131], v[204:207], v[100:103]
	v_mfma_f32_16x16x32_bf16 v[92:95], v[136:139], v[204:207], v[92:95]
	v_mfma_f32_16x16x32_bf16 v[84:87], v[128:131], v[212:215], v[84:87]
	v_mfma_f32_16x16x32_bf16 v[76:79], v[136:139], v[212:215], v[76:79]
	v_mfma_f32_16x16x32_bf16 v[124:127], v[132:135], v[192:195], v[124:127]
	v_mfma_f32_16x16x32_bf16 v[120:123], v[140:143], v[192:195], v[120:123]
	v_mfma_f32_16x16x32_bf16 v[116:119], v[132:135], v[200:203], v[116:119]
	v_mfma_f32_16x16x32_bf16 v[108:111], v[140:143], v[200:203], v[108:111]
	v_mfma_f32_16x16x32_bf16 v[100:103], v[132:135], v[208:211], v[100:103]
	v_mfma_f32_16x16x32_bf16 v[92:95], v[140:143], v[208:211], v[92:95]
	v_mfma_f32_16x16x32_bf16 v[84:87], v[132:135], v[216:219], v[84:87]
	v_mfma_f32_16x16x32_bf16 v[76:79], v[140:143], v[216:219], v[76:79]
	s_setprio 0
	s_setprio 1
	v_mfma_f32_16x16x32_bf16 v[112:115], v[160:163], v[188:191], v[112:115]
	v_mfma_f32_16x16x32_bf16 v[104:107], v[174:177], v[188:191], v[104:107]
	v_mfma_f32_16x16x32_bf16 v[96:99], v[160:163], v[196:199], v[96:99]
	v_mfma_f32_16x16x32_bf16 v[88:91], v[174:177], v[196:199], v[88:91]
	v_mfma_f32_16x16x32_bf16 v[80:83], v[160:163], v[204:207], v[80:83]
	v_mfma_f32_16x16x32_bf16 v[72:75], v[174:177], v[204:207], v[72:75]
	v_mfma_f32_16x16x32_bf16 v[68:71], v[160:163], v[212:215], v[68:71]
	v_mfma_f32_16x16x32_bf16 v[64:67], v[174:177], v[212:215], v[64:67]
	v_mfma_f32_16x16x32_bf16 v[112:115], v[170:173], v[192:195], v[112:115]
	v_mfma_f32_16x16x32_bf16 v[104:107], v[178:181], v[192:195], v[104:107]
	v_mfma_f32_16x16x32_bf16 v[96:99], v[170:173], v[200:203], v[96:99]
	v_mfma_f32_16x16x32_bf16 v[88:91], v[178:181], v[200:203], v[88:91]
	v_mfma_f32_16x16x32_bf16 v[80:83], v[170:173], v[208:211], v[80:83]
	v_mfma_f32_16x16x32_bf16 v[72:75], v[178:181], v[208:211], v[72:75]
	v_mfma_f32_16x16x32_bf16 v[68:71], v[170:173], v[216:219], v[68:71]
	v_mfma_f32_16x16x32_bf16 v[64:67], v[178:181], v[216:219], v[64:67]
	s_setprio 0
	s_barrier
	s_add_i32 s12, s75, s59
	s_mov_b32 m0, s12
	ds_read_b128 v[188:191], v169 offset:16384
	ds_read_b128 v[192:195], v169 offset:17408
	ds_read_b128 v[196:199], v169 offset:18432
	ds_read_b128 v[200:203], v169 offset:19456
	ds_read_b128 v[204:207], v169 offset:20480
	ds_read_b128 v[208:211], v169 offset:21504
	ds_read_b128 v[212:215], v169 offset:22528
	ds_read_b128 v[216:219], v169 offset:23552
	global_load_lds_dwordx4 v146, s[52:53]
	s_add_i32 m0, s12, 0x2000
	s_add_u32 s80, s52, 0x40000
	v_lshl_add_u64 v[220:221], s[52:53], 0, v[150:151]
	s_addc_u32 s81, s53, 0
	s_add_i32 s12, s76, s59
	global_load_lds_dwordx4 v150, s[52:53]
	s_mov_b32 m0, s12
	v_lshl_add_u64 v[224:225], s[54:55], 0, v[148:149]
	global_load_lds_dwordx4 v146, s[80:81]
	s_add_i32 m0, s12, 0x2000
	s_nop 0
	global_load_lds_dwordx4 v150, s[80:81]
	v_lshl_add_u64 v[222:223], s[54:55], 0, v[144:145]
	s_mov_b32 m0, s60
	s_nop 0
	global_load_lds_dwordx4 v144, s[54:55]
	s_mov_b32 m0, s61
	s_nop 0
	global_load_lds_dwordx4 v148, s[54:55]
	s_waitcnt vmcnt(8)
	s_waitcnt lgkmcnt(0)
	s_barrier
	s_setprio 1
	s_waitcnt lgkmcnt(0)
	v_mfma_f32_16x16x32_bf16 v[60:63], v[128:131], v[188:191], v[60:63]
	v_mfma_f32_16x16x32_bf16 v[56:59], v[136:139], v[188:191], v[56:59]
	v_mfma_f32_16x16x32_bf16 v[48:51], v[128:131], v[196:199], v[48:51]
	v_mfma_f32_16x16x32_bf16 v[44:47], v[136:139], v[196:199], v[44:47]
	v_mfma_f32_16x16x32_bf16 v[36:39], v[128:131], v[204:207], v[36:39]
	v_mfma_f32_16x16x32_bf16 v[28:31], v[136:139], v[204:207], v[28:31]
	v_mfma_f32_16x16x32_bf16 v[20:23], v[128:131], v[212:215], v[20:23]
	v_mfma_f32_16x16x32_bf16 v[12:15], v[136:139], v[212:215], v[12:15]
	v_mfma_f32_16x16x32_bf16 v[60:63], v[132:135], v[192:195], v[60:63]
	v_mfma_f32_16x16x32_bf16 v[56:59], v[140:143], v[192:195], v[56:59]
	v_mfma_f32_16x16x32_bf16 v[48:51], v[132:135], v[200:203], v[48:51]
	v_mfma_f32_16x16x32_bf16 v[44:47], v[140:143], v[200:203], v[44:47]
	v_mfma_f32_16x16x32_bf16 v[36:39], v[132:135], v[208:211], v[36:39]
	v_mfma_f32_16x16x32_bf16 v[28:31], v[140:143], v[208:211], v[28:31]
	v_mfma_f32_16x16x32_bf16 v[20:23], v[132:135], v[216:219], v[20:23]
	v_mfma_f32_16x16x32_bf16 v[12:15], v[140:143], v[216:219], v[12:15]
	s_setprio 0
	s_setprio 1
	v_mfma_f32_16x16x32_bf16 v[52:55], v[160:163], v[188:191], v[52:55]
	v_mfma_f32_16x16x32_bf16 v[40:43], v[174:177], v[188:191], v[40:43]
	v_mfma_f32_16x16x32_bf16 v[32:35], v[160:163], v[196:199], v[32:35]
	v_mfma_f32_16x16x32_bf16 v[24:27], v[174:177], v[196:199], v[24:27]
	v_mfma_f32_16x16x32_bf16 v[16:19], v[160:163], v[204:207], v[16:19]
	v_mfma_f32_16x16x32_bf16 v[8:11], v[174:177], v[204:207], v[8:11]
	v_mfma_f32_16x16x32_bf16 v[4:7], v[160:163], v[212:215], v[4:7]
	v_mfma_f32_16x16x32_bf16 v[0:3], v[174:177], v[212:215], v[0:3]
	v_mfma_f32_16x16x32_bf16 v[52:55], v[170:173], v[192:195], v[52:55]
	v_mfma_f32_16x16x32_bf16 v[40:43], v[178:181], v[192:195], v[40:43]
	v_mfma_f32_16x16x32_bf16 v[32:35], v[170:173], v[200:203], v[32:35]
	v_mfma_f32_16x16x32_bf16 v[24:27], v[178:181], v[200:203], v[24:27]
	v_mfma_f32_16x16x32_bf16 v[16:19], v[170:173], v[208:211], v[16:19]
	v_mfma_f32_16x16x32_bf16 v[8:11], v[178:181], v[208:211], v[8:11]
	v_mfma_f32_16x16x32_bf16 v[4:7], v[170:173], v[216:219], v[4:7]
	v_mfma_f32_16x16x32_bf16 v[0:3], v[178:181], v[216:219], v[0:3]
	s_setprio 0
	s_barrier
; #define PG8_STAGE(bufoff, gbase, voff) do { _Pragma("unroll") for (int _i = 0; _i < 2; ++_i) \
;         __builtin_amdgcn_global_load_lds((const unsigned*)((const char*)(gbase) + (voff)[_i]), (PG8_LAS unsigned*)(lds + (bufoff) + ldsw + _i * 8192), 16, 0, 0); } while (0)
; #define PG8_LDA(dst, b, h) do { _Pragma("unroll") for (int m = 0; m < 4; ++m) _Pragma("unroll") for (int k = 0; k < 2; ++k) dst[m][k] = *(const PG8_LAS bf16x8*)(lds + PG8_SA(b, h) + aoff + m * 2048 + k * 1024); } while (0)
; #define PG8_LDB(dst, b, h) do { _Pragma("unroll") for (int n = 0; n < 2; ++n) _Pragma("unroll") for (int k = 0; k < 2; ++k) dst[n][k] = *(const PG8_LAS bf16x8*)(lds + PG8_SB(b, h) + boff + n * 2048 + k * 1024); } while (0)
; #define PG8_MMA(ai, bj, At, Bt) do { __builtin_amdgcn_s_setprio(1); _Pragma("unroll") for (int m = 0; m < 4; ++m) _Pragma("unroll") for (int n = 0; n < 2; ++n) _Pragma("unroll") for (int k = 0; k < 2; ++k) \
;         acc[ai][bj][m][n] = __builtin_amdgcn_mfma_f32_16x16x32_bf16(Bt[n][k], At[m][k], acc[ai][bj][m][n], 0, 0, 0); __builtin_amdgcn_s_setprio(0); } while (0)
; #define PG8_WAIT_V(n) asm volatile("s_waitcnt vmcnt(" #n ")" ::: "memory")
; #define PG8_WAIT_L(n) asm volatile("s_waitcnt lgkmcnt(" #n ")" ::: "memory")
; #define PG8_BAR __builtin_amdgcn_s_barrier()
; #define PG8_SCHED __builtin_amdgcn_sched_barrier(0)
; template <class Epi, class Sched, bool ALIGN_EPI = false, bool SP2 = false>
; __device__ __forceinline__ void gemm_phase(PG8_LAS unsigned char* lds, const Gemm g, const Sched& S, const Epi& E) {
;     ...
;         for (int t = 0; t < nt; t += 2) {
;     ...
;             PG8_LDB(B0, 1, 0); PG8_LDB(B1, 1, 1); PG8_SCHED; PG8_LDA(At, 1, 0); PG8_STAGE(PG8_SA(0, 1), a2 + hstep, voffA);
;             PG8_WAIT_V(8); PG8_WAIT_L(0); PG8_BAR; PG8_MMA(0, 0, At, B0); PG8_MMA(0, 1, At, B1); PG8_BAR; PG8_SCHED;
;             PG8_LDA(At, 1, 1); PG8_STAGE(PG8_SB(1, 0), b3, voffB); PG8_STAGE(PG8_SB(1, 1), b3 + hstep, voffB); PG8_STAGE(PG8_SA(1, 0), a3, voffA);
;             PG8_WAIT_V(8); PG8_WAIT_L(0); PG8_BAR; PG8_MMA(1, 0, At, B0); PG8_MMA(1, 1, At, B1); PG8_BAR; PG8_SCHED;
	s_add_i32 s12, 0, 0x18000
	s_add_i32 s13, 0, 0x1c000
	v_add_u32_e32 v140, s12, v165
	v_add_u32_e32 v178, s13, v165
	ds_read_b128 v[128:131], v140
	ds_read_b128 v[132:135], v140 offset:1024
	ds_read_b128 v[136:139], v140 offset:2048
	ds_read_b128 v[140:143], v140 offset:3072
	ds_read_b128 v[160:163], v178
	ds_read_b128 v[170:173], v178 offset:1024
	ds_read_b128 v[174:177], v178 offset:2048
	ds_read_b128 v[178:181], v178 offset:3072
	s_add_u32 s54, s54, 0x40000
	s_addc_u32 s55, s55, 0
	s_mov_b32 m0, s62
	ds_read_b128 v[188:191], v169 offset:32768
	ds_read_b128 v[192:195], v169 offset:33792
	ds_read_b128 v[196:199], v169 offset:34816
	ds_read_b128 v[200:203], v169 offset:35840
	ds_read_b128 v[204:207], v169 offset:36864
	ds_read_b128 v[208:211], v169 offset:37888
	ds_read_b128 v[212:215], v169 offset:38912
	ds_read_b128 v[216:219], v169 offset:39936
	global_load_lds_dwordx4 v144, s[54:55]
	s_mov_b32 m0, s63
	s_nop 0
	global_load_lds_dwordx4 v148, s[54:55]
	s_waitcnt vmcnt(8)
	s_waitcnt lgkmcnt(0)
	s_barrier
	s_setprio 1
	s_waitcnt lgkmcnt(0)
	v_mfma_f32_16x16x32_bf16 v[124:127], v[128:131], v[188:191], v[124:127]
	v_mfma_f32_16x16x32_bf16 v[120:123], v[136:139], v[188:191], v[120:123]
	v_mfma_f32_16x16x32_bf16 v[116:119], v[128:131], v[196:199], v[116:119]
	v_mfma_f32_16x16x32_bf16 v[108:111], v[136:139], v[196:199], v[108:111]
	v_mfma_f32_16x16x32_bf16 v[100:103], v[128:131], v[204:207], v[100:103]
	v_mfma_f32_16x16x32_bf16 v[92:95], v[136:139], v[204:207], v[92:95]
	v_mfma_f32_16x16x32_bf16 v[84:87], v[128:131], v[212:215], v[84:87]
	v_mfma_f32_16x16x32_bf16 v[76:79], v[136:139], v[212:215], v[76:79]
	v_mfma_f32_16x16x32_bf16 v[124:127], v[132:135], v[192:195], v[124:127]
	v_mfma_f32_16x16x32_bf16 v[120:123], v[140:143], v[192:195], v[120:123]
	v_mfma_f32_16x16x32_bf16 v[116:119], v[132:135], v[200:203], v[116:119]
	v_mfma_f32_16x16x32_bf16 v[108:111], v[140:143], v[200:203], v[108:111]
	v_mfma_f32_16x16x32_bf16 v[100:103], v[132:135], v[208:211], v[100:103]
	v_mfma_f32_16x16x32_bf16 v[92:95], v[140:143], v[208:211], v[92:95]
	v_mfma_f32_16x16x32_bf16 v[84:87], v[132:135], v[216:219], v[84:87]
	v_mfma_f32_16x16x32_bf16 v[76:79], v[140:143], v[216:219], v[76:79]
	s_setprio 0
	s_setprio 1
	v_mfma_f32_16x16x32_bf16 v[112:115], v[160:163], v[188:191], v[112:115]
	v_mfma_f32_16x16x32_bf16 v[104:107], v[174:177], v[188:191], v[104:107]
	v_mfma_f32_16x16x32_bf16 v[96:99], v[160:163], v[196:199], v[96:99]
	v_mfma_f32_16x16x32_bf16 v[88:91], v[174:177], v[196:199], v[88:91]
	v_mfma_f32_16x16x32_bf16 v[80:83], v[160:163], v[204:207], v[80:83]
	v_mfma_f32_16x16x32_bf16 v[72:75], v[174:177], v[204:207], v[72:75]
	v_mfma_f32_16x16x32_bf16 v[68:71], v[160:163], v[212:215], v[68:71]
	v_mfma_f32_16x16x32_bf16 v[64:67], v[174:177], v[212:215], v[64:67]
	v_mfma_f32_16x16x32_bf16 v[112:115], v[170:173], v[192:195], v[112:115]
	v_mfma_f32_16x16x32_bf16 v[104:107], v[178:181], v[192:195], v[104:107]
	v_mfma_f32_16x16x32_bf16 v[96:99], v[170:173], v[200:203], v[96:99]
	v_mfma_f32_16x16x32_bf16 v[88:91], v[178:181], v[200:203], v[88:91]
	v_mfma_f32_16x16x32_bf16 v[80:83], v[170:173], v[208:211], v[80:83]
	v_mfma_f32_16x16x32_bf16 v[72:75], v[178:181], v[208:211], v[72:75]
	v_mfma_f32_16x16x32_bf16 v[68:71], v[170:173], v[216:219], v[68:71]
	v_mfma_f32_16x16x32_bf16 v[64:67], v[178:181], v[216:219], v[64:67]
	s_setprio 0
	s_barrier
	s_add_i32 s12, s12, s59
	s_add_u32 s98, s52, s22
	s_addc_u32 s99, s53, s23
	s_mov_b32 m0, s12
	ds_read_b128 v[188:191], v169 offset:49152
	ds_read_b128 v[192:195], v169 offset:50176
	ds_read_b128 v[196:199], v169 offset:51200
	ds_read_b128 v[200:203], v169 offset:52224
	ds_read_b128 v[204:207], v169 offset:53248
	ds_read_b128 v[208:211], v169 offset:54272
	ds_read_b128 v[212:215], v169 offset:55296
	ds_read_b128 v[216:219], v169 offset:56320
	global_load_lds_dwordx4 v146, s[98:99]
	s_add_i32 m0, s12, 0x2000
	s_add_u32 s52, s52, 0x40080
	v_lshl_add_u64 v[184:185], v[220:221], 0, s[22:23]
	s_addc_u32 s53, s53, 0
	s_add_i32 s12, s13, s59
	global_load_lds_dwordx4 v[184:185], off
	s_mov_b32 m0, s12
	s_nop 0
	global_load_lds_dwordx4 v146, s[52:53]
	s_add_i32 m0, s12, 0x2000
	s_nop 0
	global_load_lds_dwordx4 v150, s[52:53]
	v_lshl_add_u64 v[184:185], v[222:223], 0, s[22:23]
	s_mov_b32 m0, s69
	s_nop 0
	global_load_lds_dwordx4 v[184:185], off
	v_lshl_add_u64 v[184:185], v[224:225], 0, s[22:23]
	s_mov_b32 m0, s70
	s_nop 0
	global_load_lds_dwordx4 v[184:185], off
	s_waitcnt vmcnt(8)
	s_waitcnt lgkmcnt(0)
	s_barrier
	s_setprio 1
	s_waitcnt lgkmcnt(0)
	v_mfma_f32_16x16x32_bf16 v[60:63], v[128:131], v[188:191], v[60:63]
	v_mfma_f32_16x16x32_bf16 v[56:59], v[136:139], v[188:191], v[56:59]
	v_mfma_f32_16x16x32_bf16 v[48:51], v[128:131], v[196:199], v[48:51]
	v_mfma_f32_16x16x32_bf16 v[44:47], v[136:139], v[196:199], v[44:47]
	v_mfma_f32_16x16x32_bf16 v[36:39], v[128:131], v[204:207], v[36:39]
	v_mfma_f32_16x16x32_bf16 v[28:31], v[136:139], v[204:207], v[28:31]
	v_mfma_f32_16x16x32_bf16 v[20:23], v[128:131], v[212:215], v[20:23]
	v_mfma_f32_16x16x32_bf16 v[12:15], v[136:139], v[212:215], v[12:15]
	v_mfma_f32_16x16x32_bf16 v[60:63], v[132:135], v[192:195], v[60:63]
	v_mfma_f32_16x16x32_bf16 v[56:59], v[140:143], v[192:195], v[56:59]
	v_mfma_f32_16x16x32_bf16 v[48:51], v[132:135], v[200:203], v[48:51]
	v_mfma_f32_16x16x32_bf16 v[44:47], v[140:143], v[200:203], v[44:47]
	v_mfma_f32_16x16x32_bf16 v[36:39], v[132:135], v[208:211], v[36:39]
	v_mfma_f32_16x16x32_bf16 v[28:31], v[140:143], v[208:211], v[28:31]
	v_mfma_f32_16x16x32_bf16 v[20:23], v[132:135], v[216:219], v[20:23]
	v_mfma_f32_16x16x32_bf16 v[12:15], v[140:143], v[216:219], v[12:15]
	s_setprio 0
	s_setprio 1
	v_mfma_f32_16x16x32_bf16 v[52:55], v[160:163], v[188:191], v[52:55]
	v_mfma_f32_16x16x32_bf16 v[40:43], v[174:177], v[188:191], v[40:43]
	v_mfma_f32_16x16x32_bf16 v[32:35], v[160:163], v[196:199], v[32:35]
	v_mfma_f32_16x16x32_bf16 v[24:27], v[174:177], v[196:199], v[24:27]
	v_mfma_f32_16x16x32_bf16 v[16:19], v[160:163], v[204:207], v[16:19]
	v_mfma_f32_16x16x32_bf16 v[8:11], v[174:177], v[204:207], v[8:11]
	v_mfma_f32_16x16x32_bf16 v[4:7], v[160:163], v[212:215], v[4:7]
	v_mfma_f32_16x16x32_bf16 v[0:3], v[174:177], v[212:215], v[0:3]
	v_mfma_f32_16x16x32_bf16 v[52:55], v[170:173], v[192:195], v[52:55]
	v_mfma_f32_16x16x32_bf16 v[40:43], v[178:181], v[192:195], v[40:43]
	v_mfma_f32_16x16x32_bf16 v[32:35], v[170:173], v[200:203], v[32:35]
	v_mfma_f32_16x16x32_bf16 v[24:27], v[178:181], v[200:203], v[24:27]
	v_mfma_f32_16x16x32_bf16 v[16:19], v[170:173], v[208:211], v[16:19]
	v_mfma_f32_16x16x32_bf16 v[8:11], v[178:181], v[208:211], v[8:11]
	v_mfma_f32_16x16x32_bf16 v[4:7], v[170:173], v[216:219], v[4:7]
	v_mfma_f32_16x16x32_bf16 v[0:3], v[178:181], v[216:219], v[0:3]
	s_setprio 0
	s_barrier
	s_add_i32 s79, s79, 2
	s_add_u32 s77, s77, 0x100
	s_addc_u32 s78, s78, 0
	s_add_u32 s50, s50, 0x100
	s_addc_u32 s51, s51, 0
	s_cmp_gt_u32 s79, 13
	s_cbranch_scc0 .LBB0_1272
	s_and_b64 vcc, exec, s[36:37]
	s_cbranch_vccz .LBB0_1275
	s_barrier

; #define PG8_STAGE(bufoff, gbase, voff) do { _Pragma("unroll") for (int _i = 0; _i < 2; ++_i) \
;         __builtin_amdgcn_global_load_lds((const unsigned*)((const char*)(gbase) + (voff)[_i]), (PG8_LAS unsigned*)(lds + (bufoff) + ldsw + _i * 8192), 16, 0, 0); } while (0)
; #define PG8_LDA(dst, b, h) do { _Pragma("unroll") for (int m = 0; m < 4; ++m) _Pragma("unroll") for (int k = 0; k < 2; ++k) dst[m][k] = *(const PG8_LAS bf16x8*)(lds + PG8_SA(b, h) + aoff + m * 2048 + k * 1024); } while (0)
; #define PG8_LDB(dst, b, h) do { _Pragma("unroll") for (int n = 0; n < 2; ++n) _Pragma("unroll") for (int k = 0; k < 2; ++k) dst[n][k] = *(const PG8_LAS bf16x8*)(lds + PG8_SB(b, h) + boff + n * 2048 + k * 1024); } while (0)
; #define PG8_MMA(ai, bj, At, Bt) do { __builtin_amdgcn_s_setprio(1); _Pragma("unroll") for (int m = 0; m < 4; ++m) _Pragma("unroll") for (int n = 0; n < 2; ++n) _Pragma("unroll") for (int k = 0; k < 2; ++k) \
;         acc[ai][bj][m][n] = __builtin_amdgcn_mfma_f32_16x16x32_bf16(Bt[n][k], At[m][k], acc[ai][bj][m][n], 0, 0, 0); __builtin_amdgcn_s_setprio(0); } while (0)
; #define PG8_WAIT_V(n) asm volatile("s_waitcnt vmcnt(" #n ")" ::: "memory")
; template <class Epi, class Sched, bool ALIGN_EPI = false, bool SP2 = false>
; __device__ __forceinline__ void gemm_phase(PG8_LAS unsigned char* lds, const Gemm g, const Sched& S, const Epi& E) {
;     ...
;         for (int t = 0; t < nt; t += 2) {
;             const bool last = (t == nt - 2);
;             const char* a1 = cA + (size_t)(t + 1) * kstep;
;             const char* a2 = last ? nA : cA + (size_t)(t + 2) * kstep; const char* b2 = last ? nB : cB + (size_t)(t + 2) * kstep;
;             const char* a3 = a2 + kstep; const char* b3 = b2 + kstep;
;             if (last && has_next) S.a_ready(nxt);
;             if (last) E.prefetch(lds + 139264, cur, wid, lane);
;             if constexpr (SP2) {
;             PG8_LDB(B0, 0, 0); PG8_LDB(B1, 0, 1); PG8_SCHED; PG8_LDA(At, 0, 0); PG8_STAGE(PG8_SA(1, 1), a1 + hstep, voffA);
;             PG8_WAIT_V(8); PG8_WAIT_L(0); PG8_BAR; PG8_MMA(0, 0, At, B0); PG8_MMA(0, 1, At, B1); PG8_BAR; PG8_SCHED;
;             PG8_LDA(At, 0, 1); PG8_STAGE(PG8_SB(0, 0), b2, voffB); PG8_STAGE(PG8_SB(0, 1), b2 + hstep, voffB); PG8_STAGE(PG8_SA(0, 0), a2, voffA);
;             PG8_WAIT_V(8); PG8_WAIT_L(0); PG8_BAR; PG8_MMA(1, 0, At, B0); PG8_MMA(1, 1, At, B1); PG8_BAR; PG8_SCHED;
.LBB0_1358:
	v_add_u32_e32 v130, s71, v163
	ds_read_b128 v[118:121], v130
	ds_read_b128 v[122:125], v130 offset:1024
	ds_read_b128 v[126:129], v130 offset:2048
	ds_read_b128 v[170:173], v130 offset:3072
	v_add_u32_e32 v130, s72, v163
	ds_read_b128 v[174:177], v130
	ds_read_b128 v[178:181], v130 offset:1024
	ds_read_b128 v[184:187], v130 offset:2048
	ds_read_b128 v[188:191], v130 offset:3072
	s_add_u32 s14, s48, 0xfffc0080
	s_addc_u32 s15, s49, -1
	s_and_b64 s[50:51], s[50:51], exec
	s_cselect_b32 s53, s39, s15
	s_cselect_b32 s52, s73, s14
	s_cselect_b32 s51, s37, s47
	s_cselect_b32 s50, s74, s45
	s_add_i32 m0, s58, 0xc000
	ds_read_b128 v[192:195], v168
	ds_read_b128 v[196:199], v168 offset:1024
	ds_read_b128 v[200:203], v168 offset:2048
	ds_read_b128 v[204:207], v168 offset:3072
	ds_read_b128 v[208:211], v168 offset:4096
	ds_read_b128 v[212:215], v168 offset:5120
	ds_read_b128 v[216:219], v168 offset:6144
	ds_read_b128 v[220:223], v168 offset:7168
	global_load_lds_dwordx4 v154, s[48:49]
	s_add_i32 m0, s58, 0xe000
	s_nop 0
	global_load_lds_dwordx4 v152, s[48:49]
	s_waitcnt vmcnt(8)
	s_waitcnt lgkmcnt(0)
	s_barrier
	s_setprio 1
	s_waitcnt lgkmcnt(0)
	v_mfma_f32_16x16x32_bf16 v[140:143], v[118:121], v[192:195], v[140:143]
	v_mfma_f32_16x16x32_bf16 v[136:139], v[126:129], v[192:195], v[136:139]
	v_mfma_f32_16x16x32_bf16 v[108:111], v[118:121], v[200:203], v[108:111]
	v_mfma_f32_16x16x32_bf16 v[104:107], v[126:129], v[200:203], v[104:107]
	v_mfma_f32_16x16x32_bf16 v[92:95], v[118:121], v[208:211], v[92:95]
	v_mfma_f32_16x16x32_bf16 v[88:91], v[126:129], v[208:211], v[88:91]
	v_mfma_f32_16x16x32_bf16 v[76:79], v[118:121], v[216:219], v[76:79]
	v_mfma_f32_16x16x32_bf16 v[72:75], v[126:129], v[216:219], v[72:75]
	v_mfma_f32_16x16x32_bf16 v[140:143], v[122:125], v[196:199], v[140:143]
	v_mfma_f32_16x16x32_bf16 v[136:139], v[170:173], v[196:199], v[136:139]
	v_mfma_f32_16x16x32_bf16 v[108:111], v[122:125], v[204:207], v[108:111]
	v_mfma_f32_16x16x32_bf16 v[104:107], v[170:173], v[204:207], v[104:107]
	v_mfma_f32_16x16x32_bf16 v[92:95], v[122:125], v[212:215], v[92:95]
	v_mfma_f32_16x16x32_bf16 v[88:91], v[170:173], v[212:215], v[88:91]
	v_mfma_f32_16x16x32_bf16 v[76:79], v[122:125], v[220:223], v[76:79]
	v_mfma_f32_16x16x32_bf16 v[72:75], v[170:173], v[220:223], v[72:75]
	s_setprio 0
	s_setprio 1
	v_mfma_f32_16x16x32_bf16 v[130:133], v[174:177], v[192:195], v[132:135]
	v_mfma_f32_16x16x32_bf16 v[112:115], v[184:187], v[192:195], v[112:115]
	v_mfma_f32_16x16x32_bf16 v[100:103], v[174:177], v[200:203], v[100:103]
	v_mfma_f32_16x16x32_bf16 v[96:99], v[184:187], v[200:203], v[96:99]
	v_mfma_f32_16x16x32_bf16 v[84:87], v[174:177], v[208:211], v[84:87]
	v_mfma_f32_16x16x32_bf16 v[80:83], v[184:187], v[208:211], v[80:83]
	v_mfma_f32_16x16x32_bf16 v[68:71], v[174:177], v[216:219], v[68:71]
	v_mfma_f32_16x16x32_bf16 v[64:67], v[184:187], v[216:219], v[64:67]
	v_mfma_f32_16x16x32_bf16 v[130:133], v[178:181], v[196:199], v[130:133]
	v_mfma_f32_16x16x32_bf16 v[112:115], v[188:191], v[196:199], v[112:115]
	v_mfma_f32_16x16x32_bf16 v[100:103], v[178:181], v[204:207], v[100:103]
	v_mfma_f32_16x16x32_bf16 v[96:99], v[188:191], v[204:207], v[96:99]
	v_mfma_f32_16x16x32_bf16 v[84:87], v[178:181], v[212:215], v[84:87]
	v_mfma_f32_16x16x32_bf16 v[80:83], v[188:191], v[212:215], v[80:83]
	v_mfma_f32_16x16x32_bf16 v[68:71], v[178:181], v[220:223], v[68:71]
	v_mfma_f32_16x16x32_bf16 v[64:67], v[188:191], v[220:223], v[64:67]
	s_setprio 0
	s_barrier
	s_add_i32 s14, s71, s55
	s_mov_b32 m0, s14
	ds_read_b128 v[192:195], v168 offset:16384
	ds_read_b128 v[196:199], v168 offset:17408
	ds_read_b128 v[200:203], v168 offset:18432
	ds_read_b128 v[204:207], v168 offset:19456
	ds_read_b128 v[208:211], v168 offset:20480
	ds_read_b128 v[212:215], v168 offset:21504
	ds_read_b128 v[216:219], v168 offset:22528
	ds_read_b128 v[220:223], v168 offset:23552
	global_load_lds_dwordx4 v148, s[50:51]
	s_add_i32 m0, s14, 0x2000
	s_add_u32 s76, s50, 0x40000
	v_lshl_add_u64 v[226:227], s[50:51], 0, v[144:145]
	s_addc_u32 s77, s51, 0
	s_add_i32 s14, s72, s55
	global_load_lds_dwordx4 v144, s[50:51]
	s_mov_b32 m0, s14
	v_lshl_add_u64 v[228:229], s[52:53], 0, v[150:151]
	global_load_lds_dwordx4 v148, s[76:77]
	s_add_i32 m0, s14, 0x2000
	v_lshl_add_u64 v[230:231], s[52:53], 0, v[146:147]
	global_load_lds_dwordx4 v144, s[76:77]
	s_mov_b32 m0, s58
	s_nop 0
	global_load_lds_dwordx4 v150, s[52:53]
	s_mov_b32 m0, s59
	s_nop 0
	global_load_lds_dwordx4 v146, s[52:53]
	s_waitcnt vmcnt(8)
	s_waitcnt lgkmcnt(0)
	s_barrier
; #define PG8_STAGE(bufoff, gbase, voff) do { _Pragma("unroll") for (int _i = 0; _i < 2; ++_i) \
;         __builtin_amdgcn_global_load_lds((const unsigned*)((const char*)(gbase) + (voff)[_i]), (PG8_LAS unsigned*)(lds + (bufoff) + ldsw + _i * 8192), 16, 0, 0); } while (0)
; #define PG8_LDA(dst, b, h) do { _Pragma("unroll") for (int m = 0; m < 4; ++m) _Pragma("unroll") for (int k = 0; k < 2; ++k) dst[m][k] = *(const PG8_LAS bf16x8*)(lds + PG8_SA(b, h) + aoff + m * 2048 + k * 1024); } while (0)
; #define PG8_LDB(dst, b, h) do { _Pragma("unroll") for (int n = 0; n < 2; ++n) _Pragma("unroll") for (int k = 0; k < 2; ++k) dst[n][k] = *(const PG8_LAS bf16x8*)(lds + PG8_SB(b, h) + boff + n * 2048 + k * 1024); } while (0)
; #define PG8_MMA(ai, bj, At, Bt) do { __builtin_amdgcn_s_setprio(1); _Pragma("unroll") for (int m = 0; m < 4; ++m) _Pragma("unroll") for (int n = 0; n < 2; ++n) _Pragma("unroll") for (int k = 0; k < 2; ++k) \
;         acc[ai][bj][m][n] = __builtin_amdgcn_mfma_f32_16x16x32_bf16(Bt[n][k], At[m][k], acc[ai][bj][m][n], 0, 0, 0); __builtin_amdgcn_s_setprio(0); } while (0)
; #define PG8_WAIT_V(n) asm volatile("s_waitcnt vmcnt(" #n ")" ::: "memory")
; template <class Epi, class Sched, bool ALIGN_EPI = false, bool SP2 = false>
; __device__ __forceinline__ void gemm_phase(PG8_LAS unsigned char* lds, const Gemm g, const Sched& S, const Epi& E) {
;     ...
;             PG8_LDB(B0, 0, 0); PG8_LDB(B1, 0, 1); PG8_SCHED; PG8_LDA(At, 0, 0); PG8_STAGE(PG8_SA(1, 1), a1 + hstep, voffA);
;             PG8_WAIT_V(8); PG8_WAIT_L(0); PG8_BAR; PG8_MMA(0, 0, At, B0); PG8_MMA(0, 1, At, B1); PG8_BAR; PG8_SCHED;
;             PG8_LDA(At, 0, 1); PG8_STAGE(PG8_SB(0, 0), b2, voffB); PG8_STAGE(PG8_SB(0, 1), b2 + hstep, voffB); PG8_STAGE(PG8_SA(0, 0), a2, voffA);
;             PG8_WAIT_V(8); PG8_WAIT_L(0); PG8_BAR; PG8_MMA(1, 0, At, B0); PG8_MMA(1, 1, At, B1); PG8_BAR; PG8_SCHED;
;             PG8_LDB(B0, 1, 0); PG8_LDB(B1, 1, 1); PG8_SCHED; PG8_LDA(At, 1, 0); PG8_STAGE(PG8_SA(0, 1), a2 + hstep, voffA);
;             PG8_WAIT_V(8); PG8_WAIT_L(0); PG8_BAR; PG8_MMA(0, 0, At, B0); PG8_MMA(0, 1, At, B1); PG8_BAR; PG8_SCHED;
;             PG8_LDA(At, 1, 1); PG8_STAGE(PG8_SB(1, 0), b3, voffB); PG8_STAGE(PG8_SB(1, 1), b3 + hstep, voffB); PG8_STAGE(PG8_SA(1, 0), a3, voffA);
;             PG8_WAIT_V(8); PG8_WAIT_L(0); PG8_BAR; PG8_MMA(1, 0, At, B0); PG8_MMA(1, 1, At, B1); PG8_BAR; PG8_SCHED;
	s_setprio 1
	s_waitcnt lgkmcnt(0)
	v_mfma_f32_16x16x32_bf16 v[60:63], v[118:121], v[192:195], v[60:63]
	v_mfma_f32_16x16x32_bf16 v[56:59], v[126:129], v[192:195], v[56:59]
	v_mfma_f32_16x16x32_bf16 v[44:47], v[118:121], v[200:203], v[44:47]
	v_mfma_f32_16x16x32_bf16 v[40:43], v[126:129], v[200:203], v[40:43]
	v_mfma_f32_16x16x32_bf16 v[28:31], v[118:121], v[208:211], v[28:31]
	v_mfma_f32_16x16x32_bf16 v[24:27], v[126:129], v[208:211], v[24:27]
	v_mfma_f32_16x16x32_bf16 v[12:15], v[118:121], v[216:219], v[12:15]
	v_mfma_f32_16x16x32_bf16 v[8:11], v[126:129], v[216:219], v[8:11]
	v_mfma_f32_16x16x32_bf16 v[60:63], v[122:125], v[196:199], v[60:63]
	v_mfma_f32_16x16x32_bf16 v[56:59], v[170:173], v[196:199], v[56:59]
	v_mfma_f32_16x16x32_bf16 v[44:47], v[122:125], v[204:207], v[44:47]
	v_mfma_f32_16x16x32_bf16 v[40:43], v[170:173], v[204:207], v[40:43]
	v_mfma_f32_16x16x32_bf16 v[28:31], v[122:125], v[212:215], v[28:31]
	v_mfma_f32_16x16x32_bf16 v[24:27], v[170:173], v[212:215], v[24:27]
	v_mfma_f32_16x16x32_bf16 v[12:15], v[122:125], v[220:223], v[12:15]
	v_mfma_f32_16x16x32_bf16 v[8:11], v[170:173], v[220:223], v[8:11]
	s_setprio 0
	s_setprio 1
	v_mfma_f32_16x16x32_bf16 v[52:55], v[174:177], v[192:195], v[52:55]
	v_mfma_f32_16x16x32_bf16 v[48:51], v[184:187], v[192:195], v[48:51]
	v_mfma_f32_16x16x32_bf16 v[36:39], v[174:177], v[200:203], v[36:39]
	v_mfma_f32_16x16x32_bf16 v[32:35], v[184:187], v[200:203], v[32:35]
	v_mfma_f32_16x16x32_bf16 v[20:23], v[174:177], v[208:211], v[20:23]
	v_mfma_f32_16x16x32_bf16 v[16:19], v[184:187], v[208:211], v[16:19]
	v_mfma_f32_16x16x32_bf16 v[4:7], v[174:177], v[216:219], v[4:7]
	v_mfma_f32_16x16x32_bf16 v[0:3], v[184:187], v[216:219], v[0:3]
	v_mfma_f32_16x16x32_bf16 v[52:55], v[178:181], v[196:199], v[52:55]
	v_mfma_f32_16x16x32_bf16 v[48:51], v[188:191], v[196:199], v[48:51]
	v_mfma_f32_16x16x32_bf16 v[36:39], v[178:181], v[204:207], v[36:39]
	v_mfma_f32_16x16x32_bf16 v[32:35], v[188:191], v[204:207], v[32:35]
	v_mfma_f32_16x16x32_bf16 v[20:23], v[178:181], v[212:215], v[20:23]
	v_mfma_f32_16x16x32_bf16 v[16:19], v[188:191], v[212:215], v[16:19]
	v_mfma_f32_16x16x32_bf16 v[4:7], v[178:181], v[220:223], v[4:7]
	v_mfma_f32_16x16x32_bf16 v[0:3], v[188:191], v[220:223], v[0:3]
	s_setprio 0
	s_barrier
	s_add_i32 s14, 0, 0x18000
	v_add_u32_e32 v134, s14, v163
	s_add_i32 s15, 0, 0x1c000
	ds_read_b128 v[118:121], v134
	ds_read_b128 v[122:125], v134 offset:1024
	ds_read_b128 v[126:129], v134 offset:2048
	ds_read_b128 v[170:173], v134 offset:3072
	v_add_u32_e32 v134, s15, v163
	ds_read_b128 v[174:177], v134
	ds_read_b128 v[178:181], v134 offset:1024
	ds_read_b128 v[184:187], v134 offset:2048
	ds_read_b128 v[188:191], v134 offset:3072
	s_add_u32 s52, s52, 0x40000
	s_addc_u32 s53, s53, 0
	s_mov_b32 m0, s60
	ds_read_b128 v[192:195], v168 offset:32768
	ds_read_b128 v[196:199], v168 offset:33792
	ds_read_b128 v[200:203], v168 offset:34816
	ds_read_b128 v[204:207], v168 offset:35840
	ds_read_b128 v[208:211], v168 offset:36864
	ds_read_b128 v[212:215], v168 offset:37888
	ds_read_b128 v[216:219], v168 offset:38912
	ds_read_b128 v[220:223], v168 offset:39936
	global_load_lds_dwordx4 v150, s[52:53]
	s_mov_b32 m0, s61
	s_nop 0
	global_load_lds_dwordx4 v146, s[52:53]
	s_waitcnt vmcnt(8)
	s_waitcnt lgkmcnt(0)
	s_barrier
	s_setprio 1
	s_waitcnt lgkmcnt(0)
	v_mfma_f32_16x16x32_bf16 v[140:143], v[118:121], v[192:195], v[140:143]
	v_mfma_f32_16x16x32_bf16 v[134:137], v[126:129], v[192:195], v[136:139]
	v_mfma_f32_16x16x32_bf16 v[108:111], v[118:121], v[200:203], v[108:111]
	v_mfma_f32_16x16x32_bf16 v[104:107], v[126:129], v[200:203], v[104:107]
	v_mfma_f32_16x16x32_bf16 v[92:95], v[118:121], v[208:211], v[92:95]
	v_mfma_f32_16x16x32_bf16 v[88:91], v[126:129], v[208:211], v[88:91]
	v_mfma_f32_16x16x32_bf16 v[76:79], v[118:121], v[216:219], v[76:79]
	v_mfma_f32_16x16x32_bf16 v[72:75], v[126:129], v[216:219], v[72:75]
	v_mfma_f32_16x16x32_bf16 v[140:143], v[122:125], v[196:199], v[140:143]
	v_mfma_f32_16x16x32_bf16 v[136:139], v[170:173], v[196:199], v[134:137]
	v_mfma_f32_16x16x32_bf16 v[108:111], v[122:125], v[204:207], v[108:111]
	v_mfma_f32_16x16x32_bf16 v[104:107], v[170:173], v[204:207], v[104:107]
	v_mfma_f32_16x16x32_bf16 v[92:95], v[122:125], v[212:215], v[92:95]
	v_mfma_f32_16x16x32_bf16 v[88:91], v[170:173], v[212:215], v[88:91]
	v_mfma_f32_16x16x32_bf16 v[76:79], v[122:125], v[220:223], v[76:79]
	v_mfma_f32_16x16x32_bf16 v[72:75], v[170:173], v[220:223], v[72:75]
	s_setprio 0
	s_setprio 1
	v_mfma_f32_16x16x32_bf16 v[130:133], v[174:177], v[192:195], v[130:133]
	v_mfma_f32_16x16x32_bf16 v[112:115], v[184:187], v[192:195], v[112:115]
	v_mfma_f32_16x16x32_bf16 v[100:103], v[174:177], v[200:203], v[100:103]
	v_mfma_f32_16x16x32_bf16 v[96:99], v[184:187], v[200:203], v[96:99]
	v_mfma_f32_16x16x32_bf16 v[84:87], v[174:177], v[208:211], v[84:87]
	v_mfma_f32_16x16x32_bf16 v[80:83], v[184:187], v[208:211], v[80:83]
	v_mfma_f32_16x16x32_bf16 v[68:71], v[174:177], v[216:219], v[68:71]
	v_mfma_f32_16x16x32_bf16 v[64:67], v[184:187], v[216:219], v[64:67]
	v_mfma_f32_16x16x32_bf16 v[132:135], v[178:181], v[196:199], v[130:133]
	v_mfma_f32_16x16x32_bf16 v[112:115], v[188:191], v[196:199], v[112:115]
	v_mfma_f32_16x16x32_bf16 v[100:103], v[178:181], v[204:207], v[100:103]
	v_mfma_f32_16x16x32_bf16 v[96:99], v[188:191], v[204:207], v[96:99]
	v_mfma_f32_16x16x32_bf16 v[84:87], v[178:181], v[212:215], v[84:87]
	v_mfma_f32_16x16x32_bf16 v[80:83], v[188:191], v[212:215], v[80:83]
	v_mfma_f32_16x16x32_bf16 v[68:71], v[178:181], v[220:223], v[68:71]
	v_mfma_f32_16x16x32_bf16 v[64:67], v[188:191], v[220:223], v[64:67]
	s_setprio 0
	s_barrier
; #define PG8_STAGE(bufoff, gbase, voff) do { _Pragma("unroll") for (int _i = 0; _i < 2; ++_i) \
;         __builtin_amdgcn_global_load_lds((const unsigned*)((const char*)(gbase) + (voff)[_i]), (PG8_LAS unsigned*)(lds + (bufoff) + ldsw + _i * 8192), 16, 0, 0); } while (0)
; #define PG8_LDA(dst, b, h) do { _Pragma("unroll") for (int m = 0; m < 4; ++m) _Pragma("unroll") for (int k = 0; k < 2; ++k) dst[m][k] = *(const PG8_LAS bf16x8*)(lds + PG8_SA(b, h) + aoff + m * 2048 + k * 1024); } while (0)
; #define PG8_WAIT_V(n) asm volatile("s_waitcnt vmcnt(" #n ")" ::: "memory")
; #define PG8_WAIT_L(n) asm volatile("s_waitcnt lgkmcnt(" #n ")" ::: "memory")
; template <class Epi, class Sched, bool ALIGN_EPI = false, bool SP2 = false>
; __device__ __forceinline__ void gemm_phase(PG8_LAS unsigned char* lds, const Gemm g, const Sched& S, const Epi& E) {
;     ...
;         for (int t = 0; t < nt; t += 2) {
;             const bool last = (t == nt - 2);
;             const char* a1 = cA + (size_t)(t + 1) * kstep;
;             const char* a2 = last ? nA : cA + (size_t)(t + 2) * kstep; const char* b2 = last ? nB : cB + (size_t)(t + 2) * kstep;
;             const char* a3 = a2 + kstep; const char* b3 = b2 + kstep;
;             if (last && has_next) S.a_ready(nxt);
;             if (last) E.prefetch(lds + 139264, cur, wid, lane);
;             if constexpr (SP2) {
;             PG8_LDB(B0, 0, 0); PG8_LDB(B1, 0, 1); PG8_SCHED; PG8_LDA(At, 0, 0); PG8_STAGE(PG8_SA(1, 1), a1 + hstep, voffA);
;             PG8_WAIT_V(8); PG8_WAIT_L(0); PG8_BAR; PG8_MMA(0, 0, At, B0); PG8_MMA(0, 1, At, B1); PG8_BAR; PG8_SCHED;
;             PG8_LDA(At, 0, 1); PG8_STAGE(PG8_SB(0, 0), b2, voffB); PG8_STAGE(PG8_SB(0, 1), b2 + hstep, voffB); PG8_STAGE(PG8_SA(0, 0), a2, voffA);
;             PG8_WAIT_V(8); PG8_WAIT_L(0); PG8_BAR; PG8_MMA(1, 0, At, B0); PG8_MMA(1, 1, At, B1); PG8_BAR; PG8_SCHED;
;             PG8_LDB(B0, 1, 0); PG8_LDB(B1, 1, 1); PG8_SCHED; PG8_LDA(At, 1, 0); PG8_STAGE(PG8_SA(0, 1), a2 + hstep, voffA);
;             PG8_WAIT_V(8); PG8_WAIT_L(0); PG8_BAR; PG8_MMA(0, 0, At, B0); PG8_MMA(0, 1, At, B1); PG8_BAR; PG8_SCHED;
;             PG8_LDA(At, 1, 1); PG8_STAGE(PG8_SB(1, 0), b3, voffB); PG8_STAGE(PG8_SB(1, 1), b3 + hstep, voffB); PG8_STAGE(PG8_SA(1, 0), a3, voffA);
;             PG8_WAIT_V(8); PG8_WAIT_L(0); PG8_BAR; PG8_MMA(1, 0, At, B0); PG8_MMA(1, 1, At, B1); PG8_BAR; PG8_SCHED;
	s_add_i32 s14, s14, s55
	s_add_u32 s98, s50, s18
	s_addc_u32 s99, s51, s19
	s_mov_b32 m0, s14
	ds_read_b128 v[192:195], v168 offset:49152
	ds_read_b128 v[196:199], v168 offset:50176
	ds_read_b128 v[200:203], v168 offset:51200
	ds_read_b128 v[204:207], v168 offset:52224
	ds_read_b128 v[208:211], v168 offset:53248
	ds_read_b128 v[212:215], v168 offset:54272
	ds_read_b128 v[216:219], v168 offset:55296
	ds_read_b128 v[220:223], v168 offset:56320
	global_load_lds_dwordx4 v148, s[98:99]
	s_add_i32 m0, s14, 0x2000
	s_add_u32 s50, s50, 0x40080
	v_lshl_add_u64 v[130:131], v[226:227], 0, s[18:19]
	s_addc_u32 s51, s51, 0
	s_add_i32 s14, s15, s55
	global_load_lds_dwordx4 v[130:131], off
	s_mov_b32 m0, s14
	s_nop 0
	global_load_lds_dwordx4 v148, s[50:51]
	s_add_i32 m0, s14, 0x2000
	s_nop 0
	global_load_lds_dwordx4 v144, s[50:51]
	v_lshl_add_u64 v[130:131], v[228:229], 0, s[18:19]
	s_mov_b32 m0, s64
	s_nop 0
	global_load_lds_dwordx4 v[130:131], off
	v_lshl_add_u64 v[130:131], v[230:231], 0, s[18:19]
	s_mov_b32 m0, s65
	s_nop 0
	global_load_lds_dwordx4 v[130:131], off
	s_waitcnt vmcnt(8)
	s_waitcnt lgkmcnt(0)
	s_barrier
	s_setprio 1
	s_waitcnt lgkmcnt(0)
	v_mfma_f32_16x16x32_bf16 v[60:63], v[118:121], v[192:195], v[60:63]
	v_mfma_f32_16x16x32_bf16 v[56:59], v[126:129], v[192:195], v[56:59]
	v_mfma_f32_16x16x32_bf16 v[44:47], v[118:121], v[200:203], v[44:47]
	v_mfma_f32_16x16x32_bf16 v[40:43], v[126:129], v[200:203], v[40:43]
	v_mfma_f32_16x16x32_bf16 v[28:31], v[118:121], v[208:211], v[28:31]
	v_mfma_f32_16x16x32_bf16 v[24:27], v[126:129], v[208:211], v[24:27]
	v_mfma_f32_16x16x32_bf16 v[12:15], v[118:121], v[216:219], v[12:15]
	v_mfma_f32_16x16x32_bf16 v[8:11], v[126:129], v[216:219], v[8:11]
	v_mfma_f32_16x16x32_bf16 v[60:63], v[122:125], v[196:199], v[60:63]
	v_mfma_f32_16x16x32_bf16 v[56:59], v[170:173], v[196:199], v[56:59]
	v_mfma_f32_16x16x32_bf16 v[44:47], v[122:125], v[204:207], v[44:47]
	v_mfma_f32_16x16x32_bf16 v[40:43], v[170:173], v[204:207], v[40:43]
	v_mfma_f32_16x16x32_bf16 v[28:31], v[122:125], v[212:215], v[28:31]
	v_mfma_f32_16x16x32_bf16 v[24:27], v[170:173], v[212:215], v[24:27]
	v_mfma_f32_16x16x32_bf16 v[12:15], v[122:125], v[220:223], v[12:15]
	v_mfma_f32_16x16x32_bf16 v[8:11], v[170:173], v[220:223], v[8:11]
	s_setprio 0
	s_setprio 1
	v_mfma_f32_16x16x32_bf16 v[52:55], v[174:177], v[192:195], v[52:55]
	v_mfma_f32_16x16x32_bf16 v[48:51], v[184:187], v[192:195], v[48:51]
	v_mfma_f32_16x16x32_bf16 v[36:39], v[174:177], v[200:203], v[36:39]
	v_mfma_f32_16x16x32_bf16 v[32:35], v[184:187], v[200:203], v[32:35]
	v_mfma_f32_16x16x32_bf16 v[20:23], v[174:177], v[208:211], v[20:23]
	v_mfma_f32_16x16x32_bf16 v[16:19], v[184:187], v[208:211], v[16:19]
	v_mfma_f32_16x16x32_bf16 v[4:7], v[174:177], v[216:219], v[4:7]
	v_mfma_f32_16x16x32_bf16 v[0:3], v[184:187], v[216:219], v[0:3]
	v_mfma_f32_16x16x32_bf16 v[52:55], v[178:181], v[196:199], v[52:55]
	v_mfma_f32_16x16x32_bf16 v[48:51], v[188:191], v[196:199], v[48:51]
	v_mfma_f32_16x16x32_bf16 v[36:39], v[178:181], v[204:207], v[36:39]
	v_mfma_f32_16x16x32_bf16 v[32:35], v[188:191], v[204:207], v[32:35]
	v_mfma_f32_16x16x32_bf16 v[20:23], v[178:181], v[212:215], v[20:23]
	v_mfma_f32_16x16x32_bf16 v[16:19], v[188:191], v[212:215], v[16:19]
	v_mfma_f32_16x16x32_bf16 v[4:7], v[178:181], v[220:223], v[4:7]
	v_mfma_f32_16x16x32_bf16 v[0:3], v[188:191], v[220:223], v[0:3]
	s_setprio 0
	s_barrier
	s_add_i32 s75, s75, 2
	s_add_u32 s45, s45, 0x100
	s_addc_u32 s47, s47, 0
	s_add_u32 s48, s48, 0x100
	s_addc_u32 s49, s49, 0
	s_cmp_gt_u32 s75, 13
	s_cbranch_scc1 .LBB0_1361

; #define PG8_STAGE(bufoff, gbase, voff) do { _Pragma("unroll") for (int _i = 0; _i < 2; ++_i) \
;         __builtin_amdgcn_global_load_lds((const unsigned*)((const char*)(gbase) + (voff)[_i]), (PG8_LAS unsigned*)(lds + (bufoff) + ldsw + _i * 8192), 16, 0, 0); } while (0)
; #define PG8_LDA(dst, b, h) do { _Pragma("unroll") for (int m = 0; m < 4; ++m) _Pragma("unroll") for (int k = 0; k < 2; ++k) dst[m][k] = *(const PG8_LAS bf16x8*)(lds + PG8_SA(b, h) + aoff + m * 2048 + k * 1024); } while (0)
; #define PG8_LDB(dst, b, h) do { _Pragma("unroll") for (int n = 0; n < 2; ++n) _Pragma("unroll") for (int k = 0; k < 2; ++k) dst[n][k] = *(const PG8_LAS bf16x8*)(lds + PG8_SB(b, h) + boff + n * 2048 + k * 1024); } while (0)
; #define PG8_MMA(ai, bj, At, Bt) do { __builtin_amdgcn_s_setprio(1); _Pragma("unroll") for (int m = 0; m < 4; ++m) _Pragma("unroll") for (int n = 0; n < 2; ++n) _Pragma("unroll") for (int k = 0; k < 2; ++k) \
;         acc[ai][bj][m][n] = __builtin_amdgcn_mfma_f32_16x16x32_bf16(Bt[n][k], At[m][k], acc[ai][bj][m][n], 0, 0, 0); __builtin_amdgcn_s_setprio(0); } while (0)
; #define PG8_WAIT_V(n) asm volatile("s_waitcnt vmcnt(" #n ")" ::: "memory")
; #define PG8_BAR __builtin_amdgcn_s_barrier()
; template <class Epi, class Sched, bool ALIGN_EPI = false, bool SP2 = false>
; __device__ __forceinline__ void gemm_phase(PG8_LAS unsigned char* lds, const Gemm g, const Sched& S, const Epi& E) {
;     ...
;             const bool last = (t == nt - 2);
;             const char* a1 = cA + (size_t)(t + 1) * kstep;
;             const char* a2 = last ? nA : cA + (size_t)(t + 2) * kstep; const char* b2 = last ? nB : cB + (size_t)(t + 2) * kstep;
;             const char* a3 = a2 + kstep; const char* b3 = b2 + kstep;
;             if (last && has_next) S.a_ready(nxt);
;             if (last) E.prefetch(lds + 139264, cur, wid, lane);
;             if constexpr (SP2) {
;             PG8_LDB(B0, 0, 0); PG8_LDB(B1, 0, 1); PG8_SCHED; PG8_LDA(At, 0, 0); PG8_STAGE(PG8_SA(1, 1), a1 + hstep, voffA);
;             PG8_WAIT_V(8); PG8_WAIT_L(0); PG8_BAR; PG8_MMA(0, 0, At, B0); PG8_MMA(0, 1, At, B1); PG8_BAR; PG8_SCHED;
;             PG8_LDA(At, 0, 1); PG8_STAGE(PG8_SB(0, 0), b2, voffB); PG8_STAGE(PG8_SB(0, 1), b2 + hstep, voffB); PG8_STAGE(PG8_SA(0, 0), a2, voffA);
;             PG8_WAIT_V(8); PG8_WAIT_L(0); PG8_BAR; PG8_MMA(1, 0, At, B0); PG8_MMA(1, 1, At, B1); PG8_BAR; PG8_SCHED;
.LBB0_1432:
	ds_read_b128 v[128:131], v167
	ds_read_b128 v[132:135], v167 offset:1024
	ds_read_b128 v[136:139], v167 offset:2048
	ds_read_b128 v[140:143], v167 offset:3072
	ds_read_b128 v[160:163], v168
	ds_read_b128 v[170:173], v168 offset:1024
	ds_read_b128 v[174:177], v168 offset:2048
	ds_read_b128 v[178:181], v168 offset:3072
	s_add_u32 s20, s18, 0x100
	s_addc_u32 s21, s19, 0
	s_cmp_eq_u32 s52, 40
	s_cselect_b32 s27, s5, s21
	s_cselect_b32 s26, s4, s20
	s_cselect_b32 s23, s17, s51
	s_cselect_b32 s22, s16, s50
	v_lshl_add_u64 v[214:215], s[18:19], 0, v[154:155]
	s_add_i32 m0, s36, 0xc000
	ds_read_b128 v[182:185], v169
	ds_read_b128 v[186:189], v169 offset:1024
	ds_read_b128 v[190:193], v169 offset:2048
	ds_read_b128 v[194:197], v169 offset:3072
	ds_read_b128 v[198:201], v169 offset:4096
	ds_read_b128 v[202:205], v169 offset:5120
	ds_read_b128 v[206:209], v169 offset:6144
	ds_read_b128 v[210:213], v169 offset:7168
	global_load_lds_dwordx4 v[214:215], off
	v_lshl_add_u64 v[214:215], s[18:19], 0, v[152:153]
	s_add_i32 m0, s36, 0xe000
	s_nop 0
	global_load_lds_dwordx4 v[214:215], off
	s_waitcnt vmcnt(8)
	s_waitcnt lgkmcnt(0)
	s_barrier
	s_setprio 1
	s_waitcnt lgkmcnt(0)
	v_mfma_f32_16x16x32_bf16 v[124:127], v[128:131], v[182:185], v[124:127]
	v_mfma_f32_16x16x32_bf16 v[120:123], v[136:139], v[182:185], v[120:123]
	v_mfma_f32_16x16x32_bf16 v[116:119], v[128:131], v[190:193], v[116:119]
	v_mfma_f32_16x16x32_bf16 v[108:111], v[136:139], v[190:193], v[108:111]
	v_mfma_f32_16x16x32_bf16 v[100:103], v[128:131], v[198:201], v[100:103]
	v_mfma_f32_16x16x32_bf16 v[92:95], v[136:139], v[198:201], v[92:95]
	v_mfma_f32_16x16x32_bf16 v[84:87], v[128:131], v[206:209], v[84:87]
	v_mfma_f32_16x16x32_bf16 v[76:79], v[136:139], v[206:209], v[76:79]
	v_mfma_f32_16x16x32_bf16 v[124:127], v[132:135], v[186:189], v[124:127]
	v_mfma_f32_16x16x32_bf16 v[120:123], v[140:143], v[186:189], v[120:123]
	v_mfma_f32_16x16x32_bf16 v[116:119], v[132:135], v[194:197], v[116:119]
	v_mfma_f32_16x16x32_bf16 v[108:111], v[140:143], v[194:197], v[108:111]
	v_mfma_f32_16x16x32_bf16 v[100:103], v[132:135], v[202:205], v[100:103]
	v_mfma_f32_16x16x32_bf16 v[92:95], v[140:143], v[202:205], v[92:95]
	v_mfma_f32_16x16x32_bf16 v[84:87], v[132:135], v[210:213], v[84:87]
	v_mfma_f32_16x16x32_bf16 v[76:79], v[140:143], v[210:213], v[76:79]
	s_setprio 0
	s_setprio 1
	v_mfma_f32_16x16x32_bf16 v[112:115], v[160:163], v[182:185], v[112:115]
	v_mfma_f32_16x16x32_bf16 v[104:107], v[174:177], v[182:185], v[104:107]
	v_mfma_f32_16x16x32_bf16 v[96:99], v[160:163], v[190:193], v[96:99]
	v_mfma_f32_16x16x32_bf16 v[88:91], v[174:177], v[190:193], v[88:91]
	v_mfma_f32_16x16x32_bf16 v[80:83], v[160:163], v[198:201], v[80:83]
	v_mfma_f32_16x16x32_bf16 v[72:75], v[174:177], v[198:201], v[72:75]
	v_mfma_f32_16x16x32_bf16 v[68:71], v[160:163], v[206:209], v[68:71]
	v_mfma_f32_16x16x32_bf16 v[64:67], v[174:177], v[206:209], v[64:67]
	v_mfma_f32_16x16x32_bf16 v[112:115], v[170:173], v[186:189], v[112:115]
	v_mfma_f32_16x16x32_bf16 v[104:107], v[178:181], v[186:189], v[104:107]
	v_mfma_f32_16x16x32_bf16 v[96:99], v[170:173], v[194:197], v[96:99]
	v_mfma_f32_16x16x32_bf16 v[88:91], v[178:181], v[194:197], v[88:91]
	v_mfma_f32_16x16x32_bf16 v[80:83], v[170:173], v[202:205], v[80:83]
	v_mfma_f32_16x16x32_bf16 v[72:75], v[178:181], v[202:205], v[72:75]
	v_mfma_f32_16x16x32_bf16 v[68:71], v[170:173], v[210:213], v[68:71]
	v_mfma_f32_16x16x32_bf16 v[64:67], v[178:181], v[210:213], v[64:67]
	s_setprio 0
	s_barrier
	s_add_i32 s18, s44, s33
	s_mov_b32 m0, s18
	ds_read_b128 v[182:185], v169 offset:16384
	ds_read_b128 v[186:189], v169 offset:17408
	ds_read_b128 v[190:193], v169 offset:18432
	ds_read_b128 v[194:197], v169 offset:19456
	ds_read_b128 v[198:201], v169 offset:20480
	ds_read_b128 v[202:205], v169 offset:21504
	ds_read_b128 v[206:209], v169 offset:22528
	ds_read_b128 v[210:213], v169 offset:23552
	global_load_lds_dwordx4 v148, s[22:23]
	s_add_i32 m0, s18, 0x2000
	s_add_u32 s18, s22, 0xb0000
	v_lshl_add_u64 v[216:217], s[22:23], 0, v[144:145]
	s_addc_u32 s19, s23, 0
	s_add_i32 s53, s45, s33
	global_load_lds_dwordx4 v144, s[22:23]
	s_mov_b32 m0, s53
	s_nop 0
	global_load_lds_dwordx4 v148, s[18:19]
	s_add_i32 m0, s53, 0x2000
	s_nop 0
	global_load_lds_dwordx4 v144, s[18:19]
	s_mov_b32 m0, s36
	s_nop 0
	global_load_lds_dwordx4 v150, s[26:27]
	s_mov_b32 m0, s37
	s_nop 0
	global_load_lds_dwordx4 v146, s[26:27]
	s_waitcnt vmcnt(8)
	s_waitcnt lgkmcnt(0)
	s_barrier
	s_setprio 1
	s_waitcnt lgkmcnt(0)
	v_mfma_f32_16x16x32_bf16 v[60:63], v[128:131], v[182:185], v[60:63]
	v_mfma_f32_16x16x32_bf16 v[56:59], v[136:139], v[182:185], v[56:59]
	v_mfma_f32_16x16x32_bf16 v[48:51], v[128:131], v[190:193], v[48:51]
	v_mfma_f32_16x16x32_bf16 v[44:47], v[136:139], v[190:193], v[44:47]
	v_mfma_f32_16x16x32_bf16 v[36:39], v[128:131], v[198:201], v[36:39]
	v_mfma_f32_16x16x32_bf16 v[28:31], v[136:139], v[198:201], v[28:31]
	v_mfma_f32_16x16x32_bf16 v[20:23], v[128:131], v[206:209], v[20:23]
	v_mfma_f32_16x16x32_bf16 v[12:15], v[136:139], v[206:209], v[12:15]
	v_mfma_f32_16x16x32_bf16 v[60:63], v[132:135], v[186:189], v[60:63]
	v_mfma_f32_16x16x32_bf16 v[56:59], v[140:143], v[186:189], v[56:59]
	v_mfma_f32_16x16x32_bf16 v[48:51], v[132:135], v[194:197], v[48:51]
	v_mfma_f32_16x16x32_bf16 v[44:47], v[140:143], v[194:197], v[44:47]
	v_mfma_f32_16x16x32_bf16 v[36:39], v[132:135], v[202:205], v[36:39]
	v_mfma_f32_16x16x32_bf16 v[28:31], v[140:143], v[202:205], v[28:31]
	v_mfma_f32_16x16x32_bf16 v[20:23], v[132:135], v[210:213], v[20:23]
	v_mfma_f32_16x16x32_bf16 v[12:15], v[140:143], v[210:213], v[12:15]
	s_setprio 0
	s_setprio 1
	v_mfma_f32_16x16x32_bf16 v[52:55], v[160:163], v[182:185], v[52:55]
	v_mfma_f32_16x16x32_bf16 v[40:43], v[174:177], v[182:185], v[40:43]
	v_mfma_f32_16x16x32_bf16 v[32:35], v[160:163], v[190:193], v[32:35]
	v_mfma_f32_16x16x32_bf16 v[24:27], v[174:177], v[190:193], v[24:27]
	v_mfma_f32_16x16x32_bf16 v[16:19], v[160:163], v[198:201], v[16:19]
	v_mfma_f32_16x16x32_bf16 v[8:11], v[174:177], v[198:201], v[8:11]
	v_mfma_f32_16x16x32_bf16 v[4:7], v[160:163], v[206:209], v[4:7]
	v_mfma_f32_16x16x32_bf16 v[0:3], v[174:177], v[206:209], v[0:3]
	v_mfma_f32_16x16x32_bf16 v[52:55], v[170:173], v[186:189], v[52:55]
	v_mfma_f32_16x16x32_bf16 v[40:43], v[178:181], v[186:189], v[40:43]
	v_mfma_f32_16x16x32_bf16 v[32:35], v[170:173], v[194:197], v[32:35]
	v_mfma_f32_16x16x32_bf16 v[24:27], v[178:181], v[194:197], v[24:27]
	v_mfma_f32_16x16x32_bf16 v[16:19], v[170:173], v[202:205], v[16:19]
	v_mfma_f32_16x16x32_bf16 v[8:11], v[178:181], v[202:205], v[8:11]
	v_mfma_f32_16x16x32_bf16 v[4:7], v[170:173], v[210:213], v[4:7]
	v_mfma_f32_16x16x32_bf16 v[0:3], v[178:181], v[210:213], v[0:3]
	s_setprio 0
	s_barrier
; #define PG8_STAGE(bufoff, gbase, voff) do { _Pragma("unroll") for (int _i = 0; _i < 2; ++_i) \
;         __builtin_amdgcn_global_load_lds((const unsigned*)((const char*)(gbase) + (voff)[_i]), (PG8_LAS unsigned*)(lds + (bufoff) + ldsw + _i * 8192), 16, 0, 0); } while (0)
; #define PG8_LDA(dst, b, h) do { _Pragma("unroll") for (int m = 0; m < 4; ++m) _Pragma("unroll") for (int k = 0; k < 2; ++k) dst[m][k] = *(const PG8_LAS bf16x8*)(lds + PG8_SA(b, h) + aoff + m * 2048 + k * 1024); } while (0)
; #define PG8_LDB(dst, b, h) do { _Pragma("unroll") for (int n = 0; n < 2; ++n) _Pragma("unroll") for (int k = 0; k < 2; ++k) dst[n][k] = *(const PG8_LAS bf16x8*)(lds + PG8_SB(b, h) + boff + n * 2048 + k * 1024); } while (0)
; #define PG8_MMA(ai, bj, At, Bt) do { __builtin_amdgcn_s_setprio(1); _Pragma("unroll") for (int m = 0; m < 4; ++m) _Pragma("unroll") for (int n = 0; n < 2; ++n) _Pragma("unroll") for (int k = 0; k < 2; ++k) \
;         acc[ai][bj][m][n] = __builtin_amdgcn_mfma_f32_16x16x32_bf16(Bt[n][k], At[m][k], acc[ai][bj][m][n], 0, 0, 0); __builtin_amdgcn_s_setprio(0); } while (0)
; #define PG8_WAIT_V(n) asm volatile("s_waitcnt vmcnt(" #n ")" ::: "memory")
; #define PG8_WAIT_L(n) asm volatile("s_waitcnt lgkmcnt(" #n ")" ::: "memory")
; #define PG8_BAR __builtin_amdgcn_s_barrier()
; #define PG8_SCHED __builtin_amdgcn_sched_barrier(0)
; template <class Epi, class Sched, bool ALIGN_EPI = false, bool SP2 = false>
; __device__ __forceinline__ void gemm_phase(PG8_LAS unsigned char* lds, const Gemm g, const Sched& S, const Epi& E) {
;     ...
;             PG8_LDB(B0, 1, 0); PG8_LDB(B1, 1, 1); PG8_SCHED; PG8_LDA(At, 1, 0); PG8_STAGE(PG8_SA(0, 1), a2 + hstep, voffA);
;             PG8_WAIT_V(8); PG8_WAIT_L(0); PG8_BAR; PG8_MMA(0, 0, At, B0); PG8_MMA(0, 1, At, B1); PG8_BAR; PG8_SCHED;
;             PG8_LDA(At, 1, 1); PG8_STAGE(PG8_SB(1, 0), b3, voffB); PG8_STAGE(PG8_SB(1, 1), b3 + hstep, voffB); PG8_STAGE(PG8_SA(1, 0), a3, voffA);
;             PG8_WAIT_V(8); PG8_WAIT_L(0); PG8_BAR; PG8_MMA(1, 0, At, B0); PG8_MMA(1, 1, At, B1); PG8_BAR; PG8_SCHED;
;     ...
;         if constexpr (ALIGN_EPI) { if (wr == 0) PG8_BAR; }
	s_add_i32 s53, 0, 0x18000
	s_add_i32 s54, 0, 0x1c000
	v_add_u32_e32 v140, s53, v165
	v_add_u32_e32 v178, s54, v165
	ds_read_b128 v[128:131], v140
	ds_read_b128 v[132:135], v140 offset:1024
	ds_read_b128 v[136:139], v140 offset:2048
	ds_read_b128 v[140:143], v140 offset:3072
	ds_read_b128 v[160:163], v178
	ds_read_b128 v[170:173], v178 offset:1024
	ds_read_b128 v[174:177], v178 offset:2048
	ds_read_b128 v[178:181], v178 offset:3072
	s_add_u32 s18, s26, 0xb0000
	s_addc_u32 s19, s27, 0
	s_mov_b32 m0, s38
	ds_read_b128 v[182:185], v169 offset:32768
	ds_read_b128 v[186:189], v169 offset:33792
	ds_read_b128 v[190:193], v169 offset:34816
	ds_read_b128 v[194:197], v169 offset:35840
	ds_read_b128 v[198:201], v169 offset:36864
	ds_read_b128 v[202:205], v169 offset:37888
	ds_read_b128 v[206:209], v169 offset:38912
	ds_read_b128 v[210:213], v169 offset:39936
	global_load_lds_dwordx4 v150, s[18:19]
	s_mov_b32 m0, s39
	s_nop 0
	global_load_lds_dwordx4 v146, s[18:19]
	s_waitcnt vmcnt(8)
	s_waitcnt lgkmcnt(0)
	s_barrier
	s_setprio 1
	s_waitcnt lgkmcnt(0)
	v_mfma_f32_16x16x32_bf16 v[124:127], v[128:131], v[182:185], v[124:127]
	v_mfma_f32_16x16x32_bf16 v[120:123], v[136:139], v[182:185], v[120:123]
	v_mfma_f32_16x16x32_bf16 v[116:119], v[128:131], v[190:193], v[116:119]
	v_mfma_f32_16x16x32_bf16 v[108:111], v[136:139], v[190:193], v[108:111]
	v_mfma_f32_16x16x32_bf16 v[100:103], v[128:131], v[198:201], v[100:103]
	v_mfma_f32_16x16x32_bf16 v[92:95], v[136:139], v[198:201], v[92:95]
	v_mfma_f32_16x16x32_bf16 v[84:87], v[128:131], v[206:209], v[84:87]
	v_mfma_f32_16x16x32_bf16 v[76:79], v[136:139], v[206:209], v[76:79]
	v_mfma_f32_16x16x32_bf16 v[124:127], v[132:135], v[186:189], v[124:127]
	v_mfma_f32_16x16x32_bf16 v[120:123], v[140:143], v[186:189], v[120:123]
	v_mfma_f32_16x16x32_bf16 v[116:119], v[132:135], v[194:197], v[116:119]
	v_mfma_f32_16x16x32_bf16 v[108:111], v[140:143], v[194:197], v[108:111]
	v_mfma_f32_16x16x32_bf16 v[100:103], v[132:135], v[202:205], v[100:103]
	v_mfma_f32_16x16x32_bf16 v[92:95], v[140:143], v[202:205], v[92:95]
	v_mfma_f32_16x16x32_bf16 v[84:87], v[132:135], v[210:213], v[84:87]
	v_mfma_f32_16x16x32_bf16 v[76:79], v[140:143], v[210:213], v[76:79]
	s_setprio 0
	s_setprio 1
	v_mfma_f32_16x16x32_bf16 v[112:115], v[160:163], v[182:185], v[112:115]
	v_mfma_f32_16x16x32_bf16 v[104:107], v[174:177], v[182:185], v[104:107]
	v_mfma_f32_16x16x32_bf16 v[96:99], v[160:163], v[190:193], v[96:99]
	v_mfma_f32_16x16x32_bf16 v[88:91], v[174:177], v[190:193], v[88:91]
	v_mfma_f32_16x16x32_bf16 v[80:83], v[160:163], v[198:201], v[80:83]
	v_mfma_f32_16x16x32_bf16 v[72:75], v[174:177], v[198:201], v[72:75]
	v_mfma_f32_16x16x32_bf16 v[68:71], v[160:163], v[206:209], v[68:71]
	v_mfma_f32_16x16x32_bf16 v[64:67], v[174:177], v[206:209], v[64:67]
	v_mfma_f32_16x16x32_bf16 v[112:115], v[170:173], v[186:189], v[112:115]
	v_mfma_f32_16x16x32_bf16 v[104:107], v[178:181], v[186:189], v[104:107]
	v_mfma_f32_16x16x32_bf16 v[96:99], v[170:173], v[194:197], v[96:99]
	v_mfma_f32_16x16x32_bf16 v[88:91], v[178:181], v[194:197], v[88:91]
	v_mfma_f32_16x16x32_bf16 v[80:83], v[170:173], v[202:205], v[80:83]
	v_mfma_f32_16x16x32_bf16 v[72:75], v[178:181], v[202:205], v[72:75]
	v_mfma_f32_16x16x32_bf16 v[68:71], v[170:173], v[210:213], v[68:71]
	v_mfma_f32_16x16x32_bf16 v[64:67], v[178:181], v[210:213], v[64:67]
	s_setprio 0
	s_barrier
	s_add_i32 s18, s53, s33
	s_add_u32 s98, s22, s12
	s_addc_u32 s99, s23, s13
	s_add_u32 s100, s26, s12
	s_addc_u32 s101, s27, s13
	s_mov_b32 m0, s18
	ds_read_b128 v[182:185], v169 offset:49152
	ds_read_b128 v[186:189], v169 offset:50176
	ds_read_b128 v[190:193], v169 offset:51200
	ds_read_b128 v[194:197], v169 offset:52224
	ds_read_b128 v[198:201], v169 offset:53248
	ds_read_b128 v[202:205], v169 offset:54272
	ds_read_b128 v[206:209], v169 offset:55296
	ds_read_b128 v[210:213], v169 offset:56320
	global_load_lds_dwordx4 v148, s[98:99]
	s_add_i32 m0, s18, 0x2000
	s_add_u32 s18, s22, 0xb0080
	v_lshl_add_u64 v[214:215], v[216:217], 0, s[12:13]
	s_addc_u32 s19, s23, 0
	s_add_i32 s22, s54, s33
	global_load_lds_dwordx4 v[214:215], off
	s_mov_b32 m0, s22
	s_nop 0
	global_load_lds_dwordx4 v148, s[18:19]
	s_add_i32 m0, s22, 0x2000
	s_nop 0
	global_load_lds_dwordx4 v144, s[18:19]
	s_mov_b32 m0, s41
	s_nop 0
	global_load_lds_dwordx4 v150, s[100:101]
	s_mov_b32 m0, s42
	s_nop 0
	global_load_lds_dwordx4 v146, s[100:101]
	s_waitcnt vmcnt(8)
	s_waitcnt lgkmcnt(0)
	s_barrier
	s_setprio 1
	s_waitcnt lgkmcnt(0)
	v_mfma_f32_16x16x32_bf16 v[60:63], v[128:131], v[182:185], v[60:63]
	v_mfma_f32_16x16x32_bf16 v[56:59], v[136:139], v[182:185], v[56:59]
	v_mfma_f32_16x16x32_bf16 v[48:51], v[128:131], v[190:193], v[48:51]
	v_mfma_f32_16x16x32_bf16 v[44:47], v[136:139], v[190:193], v[44:47]
	v_mfma_f32_16x16x32_bf16 v[36:39], v[128:131], v[198:201], v[36:39]
	v_mfma_f32_16x16x32_bf16 v[28:31], v[136:139], v[198:201], v[28:31]
	v_mfma_f32_16x16x32_bf16 v[20:23], v[128:131], v[206:209], v[20:23]
	v_mfma_f32_16x16x32_bf16 v[12:15], v[136:139], v[206:209], v[12:15]
	v_mfma_f32_16x16x32_bf16 v[60:63], v[132:135], v[186:189], v[60:63]
	v_mfma_f32_16x16x32_bf16 v[56:59], v[140:143], v[186:189], v[56:59]
	v_mfma_f32_16x16x32_bf16 v[48:51], v[132:135], v[194:197], v[48:51]
	v_mfma_f32_16x16x32_bf16 v[44:47], v[140:143], v[194:197], v[44:47]
	v_mfma_f32_16x16x32_bf16 v[36:39], v[132:135], v[202:205], v[36:39]
	v_mfma_f32_16x16x32_bf16 v[28:31], v[140:143], v[202:205], v[28:31]
	v_mfma_f32_16x16x32_bf16 v[20:23], v[132:135], v[210:213], v[20:23]
	v_mfma_f32_16x16x32_bf16 v[12:15], v[140:143], v[210:213], v[12:15]
	s_setprio 0
	s_setprio 1
	v_mfma_f32_16x16x32_bf16 v[52:55], v[160:163], v[182:185], v[52:55]
	v_mfma_f32_16x16x32_bf16 v[40:43], v[174:177], v[182:185], v[40:43]
	v_mfma_f32_16x16x32_bf16 v[32:35], v[160:163], v[190:193], v[32:35]
	v_mfma_f32_16x16x32_bf16 v[24:27], v[174:177], v[190:193], v[24:27]
	v_mfma_f32_16x16x32_bf16 v[16:19], v[160:163], v[198:201], v[16:19]
	v_mfma_f32_16x16x32_bf16 v[8:11], v[174:177], v[198:201], v[8:11]
	v_mfma_f32_16x16x32_bf16 v[4:7], v[160:163], v[206:209], v[4:7]
	v_mfma_f32_16x16x32_bf16 v[0:3], v[174:177], v[206:209], v[0:3]
	v_mfma_f32_16x16x32_bf16 v[52:55], v[170:173], v[186:189], v[52:55]
	v_mfma_f32_16x16x32_bf16 v[40:43], v[178:181], v[186:189], v[40:43]
	v_mfma_f32_16x16x32_bf16 v[32:35], v[170:173], v[194:197], v[32:35]
	v_mfma_f32_16x16x32_bf16 v[24:27], v[178:181], v[194:197], v[24:27]
	v_mfma_f32_16x16x32_bf16 v[16:19], v[170:173], v[202:205], v[16:19]
	v_mfma_f32_16x16x32_bf16 v[8:11], v[178:181], v[202:205], v[8:11]
	v_mfma_f32_16x16x32_bf16 v[4:7], v[170:173], v[210:213], v[4:7]
	v_mfma_f32_16x16x32_bf16 v[0:3], v[178:181], v[210:213], v[0:3]
	s_setprio 0
	s_barrier
	s_add_i32 s52, s52, 2
	s_add_u32 s50, s50, 0x100
	s_addc_u32 s51, s51, 0
	s_cmp_gt_u32 s52, 41
	s_mov_b64 s[18:19], s[20:21]
	s_cbranch_scc0 .LBB0_1432
	s_and_b64 vcc, exec, s[14:15]
	s_cbranch_vccz .LBB0_1435
	s_barrier

; __global__ void __launch_bounds__(NWAVES * 64, 2) mega_fwd(Args args) {
	.amdhsa_kernel _Z8mega_fwd4Args
		.amdhsa_group_segment_fixed_size 0
		.amdhsa_private_segment_fixed_size 0
		.amdhsa_kernarg_size 464
		.amdhsa_user_sgpr_count 2
		.amdhsa_user_sgpr_dispatch_ptr 0
		.amdhsa_user_sgpr_queue_ptr 0
		.amdhsa_user_sgpr_kernarg_segment_ptr 1
		.amdhsa_user_sgpr_dispatch_id 0
		.amdhsa_user_sgpr_kernarg_preload_length 0
		.amdhsa_user_sgpr_kernarg_preload_offset 0
		.amdhsa_user_sgpr_private_segment_size 0
		.amdhsa_uses_dynamic_stack 0
		.amdhsa_enable_private_segment 0
		.amdhsa_system_sgpr_workgroup_id_x 1
		.amdhsa_system_sgpr_workgroup_id_y 0
		.amdhsa_system_sgpr_workgroup_id_z 0
		.amdhsa_system_sgpr_workgroup_info 0
		.amdhsa_system_vgpr_workitem_id 2
		.amdhsa_next_free_vgpr 253
		.amdhsa_next_free_sgpr 102
		.amdhsa_accum_offset 256
		.amdhsa_reserve_vcc 1
		.amdhsa_float_round_mode_32 0
		.amdhsa_float_round_mode_16_64 0
		.amdhsa_float_denorm_mode_32 3
		.amdhsa_float_denorm_mode_16_64 3
		.amdhsa_dx10_clamp 1
		.amdhsa_ieee_mode 1
		.amdhsa_fp16_overflow 0
		.amdhsa_tg_split 0
		.amdhsa_exception_fp_ieee_invalid_op 0
		.amdhsa_exception_fp_denorm_src 0
		.amdhsa_exception_fp_ieee_div_zero 0
		.amdhsa_exception_fp_ieee_overflow 0
		.amdhsa_exception_fp_ieee_underflow 0
		.amdhsa_exception_fp_ieee_inexact 0
		.amdhsa_exception_int_div_zero 0
	.end_amdhsa_kernel

; __global__ void __launch_bounds__(NWAVES * 64, 2) mega_fwd(Args args) {
.Lfunc_end0:
	.size	_Z8mega_fwd4Args, .Lfunc_end0-_Z8mega_fwd4Args
	.set _Z8mega_fwd4Args.num_vgpr, 253
	.set _Z8mega_fwd4Args.num_agpr, 0
	.set _Z8mega_fwd4Args.numbered_sgpr, 102
	.set _Z8mega_fwd4Args.num_named_barrier, 0
	.set _Z8mega_fwd4Args.private_seg_size, 0
	.set _Z8mega_fwd4Args.uses_vcc, 1
	.set _Z8mega_fwd4Args.uses_flat_scratch, 0
	.set _Z8mega_fwd4Args.has_dyn_sized_stack, 0
	.set _Z8mega_fwd4Args.has_recursion, 0
	.set _Z8mega_fwd4Args.has_indirect_call, 0

; __global__ void __launch_bounds__(NWAVES * 64, 2) mega_fwd(Args args) {
amdhsa.kernels:
  - .agpr_count:     0
    .args:
      - .offset:         0
        .size:           208
        .value_kind:     by_value
      - .offset:         208
        .size:           4
        .value_kind:     hidden_block_count_x
      - .offset:         212
        .size:           4
        .value_kind:     hidden_block_count_y
      - .offset:         216
        .size:           4
        .value_kind:     hidden_block_count_z
      - .offset:         220
        .size:           2
        .value_kind:     hidden_group_size_x
      - .offset:         222
        .size:           2
        .value_kind:     hidden_group_size_y
      - .offset:         224
        .size:           2
        .value_kind:     hidden_group_size_z
      - .offset:         226
        .size:           2
        .value_kind:     hidden_remainder_x
      - .offset:         228
        .size:           2
        .value_kind:     hidden_remainder_y
      - .offset:         230
        .size:           2
        .value_kind:     hidden_remainder_z
      - .offset:         248
        .size:           8
        .value_kind:     hidden_global_offset_x
      - .offset:         256
        .size:           8
        .value_kind:     hidden_global_offset_y
      - .offset:         264
        .size:           8
        .value_kind:     hidden_global_offset_z
      - .offset:         272
        .size:           2
        .value_kind:     hidden_grid_dims
      - .offset:         296
        .size:           8
        .value_kind:     hidden_multigrid_sync_arg
      - .offset:         328
        .size:           4
        .value_kind:     hidden_dynamic_lds_size
    .group_segment_fixed_size: 0
    .kernarg_segment_align: 8
    .kernarg_segment_size: 464
    .language:       OpenCL C
    .language_version:
      - 2
      - 0
    .max_flat_workgroup_size: 512
    .name:           _Z8mega_fwd4Args
    .private_segment_fixed_size: 0
    .sgpr_count:     108
    .sgpr_spill_count: 5
    .symbol:         _Z8mega_fwd4Args.kd
    .uniform_work_group_size: 1
    .uses_dynamic_stack: false
    .vgpr_count:     253
    .vgpr_spill_count: 0
    .wavefront_size: 64
